# hand-written norm/fixup phases store write-through (sc1) and the grid barriers that follow them skip the L2 writeback
# speedup vs baseline: 1.0125x; 1.0014x over previous
; DI void norm_phase(const Args& A, int wave_s, int l, int which, int rows) {
;     const Ctx C = make_ctx(A, wave_s);
;     const float* gn = (which == 1 ? C.n1g : C.n2g) + l * 1024;
;     const bool from_in = (l == 0 && which == 1);
;     f32x4 g[4];
; #pragma unroll
;     for (int j = 0; j < 4; ++j) g[j] = *(const f32x4*)(gn + 4 * (C.lane + 64 * j));
;     for (int m0 = C.gw * 2; m0 < rows; m0 += C.NGW * 2) {
;         f32x4 xv[2][4];
;         const float* modp[2];
; #pragma unroll
;         for (int rr = 0; rr < 2; ++rr) {
;             const int m = m0 + rr; const float* xr; int v;
;             if (m < NLAT) { xr = (from_in ? C.x : C.out) + (size_t)m * 1024; v = m >> 13; }
;             else { xr = (from_in ? C.ctx : C.XC) + (size_t)(m - NLAT) * 1024; v = 4; }
;             modp[rr] = C.SM + SM_MOD + (l * 5 + v) * 6144 + (which == 1 ? 0 : 3072);
; #pragma unroll
;             for (int j = 0; j < 4; ++j) xv[rr][j] = ((const f32x4*)xr)[C.lane + 64 * j];
;         }
; #pragma unroll
;         for (int rr = 0; rr < 2; ++rr) {
;             const int m = m0 + rr;
;             f32x4 sh[4], sc[4];
; #pragma unroll
;             for (int j = 0; j < 4; ++j) { const int col = 4 * (C.lane + 64 * j); sh[j] = *(const f32x4*)(modp[rr] + col); sc[j] = *(const f32x4*)(modp[rr] + 1024 + col); }
.LBB0_55:
	s_lshl_b32 s4, s56, 10
	s_mov_b32 s5, s97
	v_writelane_b32 v255, s4, 32
	s_mul_i32 s45, s56, 5
	v_mbcnt_lo_u32_b32 v48, -1, 0
	v_mbcnt_hi_u32_b32 v48, -1, v48
	s_nop 0
	v_writelane_b32 v255, s5, 33
	v_mbcnt_lo_u32_b32 v0, -1, 0
	v_mbcnt_hi_u32_b32 v0, -1, v0
	v_readlane_b32 s6, v255, 32
	v_lshlrev_b32_e32 v1, 4, v0
	v_lshlrev_b32_e32 v2, 3, v0
	v_xor_b32_e32 v4, 1, v0
	v_xor_b32_e32 v5, 2, v0
	v_xor_b32_e32 v6, 4, v0
	v_xor_b32_e32 v7, 8, v0
	v_xor_b32_e32 v8, 16, v0
	v_xor_b32_e32 v9, 32, v0
	v_lshlrev_b32_e32 v4, 2, v4
	v_lshlrev_b32_e32 v5, 2, v5
	v_lshlrev_b32_e32 v6, 2, v6
	v_lshlrev_b32_e32 v7, 2, v7
	v_lshlrev_b32_e32 v8, 2, v8
	v_lshlrev_b32_e32 v9, 2, v9
	v_mov_b32_e32 v60, 0x358637bd
	s_lshr_b32 s6, s6, 10
	s_lshr_b32 s4, s94, 6
	s_lshl_b32 s5, s65, 3
	s_add_u32 s4, s4, s5
	s_lshr_b32 s5, s4, 9
	s_mul_i32 s7, s6, 5
	s_add_u32 s5, s7, s5
	s_mul_i32 s5, s5, 0x6000
	s_add_u32 s24, s88, 0x100000
	s_addc_u32 s25, s89, 0
	s_add_u32 s24, s24, s5
	s_addc_u32 s25, s25, 0
	s_add_u32 s26, s24, 0x1000
	s_addc_u32 s27, s25, 0
	v_readlane_b32 s28, v252, 46
	v_readlane_b32 s29, v252, 47
	s_lshl_b32 s7, s6, 12
	s_nop 1
	s_add_u32 s28, s28, s7
	s_addc_u32 s29, s29, 0
	v_readlane_b32 s8, v252, 31
	v_readlane_b32 s9, v252, 32
	s_add_u32 s30, s88, 0x3400000
	s_addc_u32 s31, s89, 0
	v_readlane_b32 s10, v252, 34
	v_readlane_b32 s11, v252, 35
	v_readlane_b32 s2, v252, 38
	v_readlane_b32 s32, v252, 39
	s_nop 1
	s_cmp_eq_u32 s6, 0
	s_cselect_b32 s8, s10, s8
	s_cselect_b32 s9, s11, s9
	s_cselect_b32 s30, s2, s30
	s_cselect_b32 s31, s32, s31
	s_mov_b32 s2, 1
	s_cmp_lt_u32 s4, 0x400
	s_cselect_b32 s2, s2, 0
	s_and_b32 s7, s4, 0x3ff
	s_lshl_b32 s5, s7, 12
	s_add_u32 s30, s30, s5
	s_addc_u32 s31, s31, 0
	s_lshl_b32 s5, s4, 16
	s_add_u32 s8, s8, s5
	s_addc_u32 s9, s9, 0
	s_add_u32 s10, s88, 0x3800000
	s_addc_u32 s11, s89, 0
	s_lshl_b32 s5, s4, 15
	s_add_u32 s10, s10, s5
	s_addc_u32 s11, s11, 0
	s_mov_b32 s32, 0x3a800000
	global_load_dwordx4 v[24:27], v1, s[28:29]
	global_load_dwordx4 v[28:31], v1, s[28:29] offset:1024
	global_load_dwordx4 v[32:35], v1, s[28:29] offset:2048
	global_load_dwordx4 v[36:39], v1, s[28:29] offset:3072
	global_load_dwordx4 v[40:43], v1, s[26:27]
	global_load_dwordx4 v[64:67], v1, s[26:27] offset:1024
	global_load_dwordx4 v[68:71], v1, s[26:27] offset:2048
	global_load_dwordx4 v[72:75], v1, s[26:27] offset:3072
	global_load_dwordx4 v[80:83], v1, s[24:25]
	global_load_dwordx4 v[84:87], v1, s[24:25] offset:1024
	global_load_dwordx4 v[88:91], v1, s[24:25] offset:2048
	global_load_dwordx4 v[92:95], v1, s[24:25] offset:3072
	global_load_dwordx4 v[96:99], v1, s[8:9]
	global_load_dwordx4 v[100:103], v1, s[8:9] offset:1024
	global_load_dwordx4 v[104:107], v1, s[8:9] offset:2048
	global_load_dwordx4 v[108:111], v1, s[8:9] offset:3072
	s_add_u32 s8, s8, 0x1000
	s_addc_u32 s9, s9, 0
	global_load_dwordx4 v[112:115], v1, s[8:9]
	global_load_dwordx4 v[116:119], v1, s[8:9] offset:1024
	global_load_dwordx4 v[120:123], v1, s[8:9] offset:2048
	global_load_dwordx4 v[124:127], v1, s[8:9] offset:3072
	s_add_u32 s8, s8, 0x1000
	s_addc_u32 s9, s9, 0
	global_load_dwordx4 v[128:131], v1, s[8:9]
	global_load_dwordx4 v[132:135], v1, s[8:9] offset:1024
	global_load_dwordx4 v[136:139], v1, s[8:9] offset:2048
	global_load_dwordx4 v[140:143], v1, s[8:9] offset:3072
	s_add_u32 s8, s8, 0x1000
	s_addc_u32 s9, s9, 0
	global_load_dwordx4 v[144:147], v1, s[8:9]
	global_load_dwordx4 v[148:151], v1, s[8:9] offset:1024
	global_load_dwordx4 v[152:155], v1, s[8:9] offset:2048
	global_load_dwordx4 v[156:159], v1, s[8:9] offset:3072
	s_add_u32 s8, s8, 0x1000
	s_addc_u32 s9, s9, 0
	global_load_dwordx4 v[164:167], v1, s[8:9]
	global_load_dwordx4 v[168:171], v1, s[8:9] offset:1024
	global_load_dwordx4 v[172:175], v1, s[8:9] offset:2048
	global_load_dwordx4 v[176:179], v1, s[8:9] offset:3072
	s_add_u32 s8, s8, 0x1000
	s_addc_u32 s9, s9, 0
	global_load_dwordx4 v[180:183], v1, s[8:9]
	global_load_dwordx4 v[184:187], v1, s[8:9] offset:1024
	global_load_dwordx4 v[188:191], v1, s[8:9] offset:2048
	global_load_dwordx4 v[192:195], v1, s[8:9] offset:3072
	s_add_u32 s8, s8, 0x1000
	s_addc_u32 s9, s9, 0
	global_load_dwordx4 v[196:199], v1, s[8:9]
	global_load_dwordx4 v[200:203], v1, s[8:9] offset:1024
	global_load_dwordx4 v[204:207], v1, s[8:9] offset:2048
	global_load_dwordx4 v[208:211], v1, s[8:9] offset:3072
	s_add_u32 s8, s8, 0x1000
	s_addc_u32 s9, s9, 0
	global_load_dwordx4 v[212:215], v1, s[8:9]
	global_load_dwordx4 v[216:219], v1, s[8:9] offset:1024
	global_load_dwordx4 v[220:223], v1, s[8:9] offset:2048
	global_load_dwordx4 v[224:227], v1, s[8:9] offset:3072
	s_add_u32 s8, s8, 0x1000
	s_addc_u32 s9, s9, 0
	s_waitcnt vmcnt(32)
	v_pk_add_f32 v[40:41], v[40:41], 1.0 op_sel_hi:[1,0]
	v_pk_add_f32 v[42:43], v[42:43], 1.0 op_sel_hi:[1,0]
	v_pk_add_f32 v[64:65], v[64:65], 1.0 op_sel_hi:[1,0]
	v_pk_add_f32 v[66:67], v[66:67], 1.0 op_sel_hi:[1,0]
	v_pk_add_f32 v[68:69], v[68:69], 1.0 op_sel_hi:[1,0]
	v_pk_add_f32 v[70:71], v[70:71], 1.0 op_sel_hi:[1,0]
	v_pk_add_f32 v[72:73], v[72:73], 1.0 op_sel_hi:[1,0]
	v_pk_add_f32 v[74:75], v[74:75], 1.0 op_sel_hi:[1,0]
	s_waitcnt vmcnt(16)
; DI unsigned pk2(float lo, float hi) { return f2bf(lo) | (f2bf(hi) << 16); }
; DI void norm_phase(const Args& A, int wave_s, int l, int which, int rows) {
;     ...
;             float ss = 0.f;
; #pragma unroll
;             for (int j = 0; j < 4; ++j) ss += (xv[rr][j].x * xv[rr][j].x + xv[rr][j].y * xv[rr][j].y) + (xv[rr][j].z * xv[rr][j].z + xv[rr][j].w * xv[rr][j].w);
;             ss = wave_sum(C.lane, ss);
;             const float rs = rsqrtf(ss * (1.f / 1024.f) + EPS);
; #pragma unroll
;             for (int j = 0; j < 4; ++j) { const int col = 4 * (C.lane + 64 * j);
;                 const f32x4 y = xv[rr][j] * rs * g[j] * (sc[j] + 1.f) + sh[j];
;                 v2u o; o.x = pk2(y.x, y.y); o.y = pk2(y.z, y.w);
;                 *(v2u*)(C.H + (size_t)m * 1024 + col) = o; }
	v_mul_f32_e32 v10, v96, v96
	v_fmac_f32_e32 v10, v97, v97
	v_fmac_f32_e32 v10, v98, v98
	v_fmac_f32_e32 v10, v99, v99
	v_fmac_f32_e32 v10, v100, v100
	v_fmac_f32_e32 v10, v101, v101
	v_fmac_f32_e32 v10, v102, v102
	v_fmac_f32_e32 v10, v103, v103
	v_fmac_f32_e32 v10, v104, v104
	v_fmac_f32_e32 v10, v105, v105
	v_fmac_f32_e32 v10, v106, v106
	v_fmac_f32_e32 v10, v107, v107
	v_fmac_f32_e32 v10, v108, v108
	v_fmac_f32_e32 v10, v109, v109
	v_fmac_f32_e32 v10, v110, v110
	v_fmac_f32_e32 v10, v111, v111
	v_mul_f32_e32 v11, v112, v112
	v_fmac_f32_e32 v11, v113, v113
	v_fmac_f32_e32 v11, v114, v114
	v_fmac_f32_e32 v11, v115, v115
	v_fmac_f32_e32 v11, v116, v116
	v_fmac_f32_e32 v11, v117, v117
	v_fmac_f32_e32 v11, v118, v118
	v_fmac_f32_e32 v11, v119, v119
	v_fmac_f32_e32 v11, v120, v120
	v_fmac_f32_e32 v11, v121, v121
	v_fmac_f32_e32 v11, v122, v122
	v_fmac_f32_e32 v11, v123, v123
	v_fmac_f32_e32 v11, v124, v124
	v_fmac_f32_e32 v11, v125, v125
	v_fmac_f32_e32 v11, v126, v126
	v_fmac_f32_e32 v11, v127, v127
	v_mul_f32_e32 v12, v128, v128
	v_fmac_f32_e32 v12, v129, v129
	v_fmac_f32_e32 v12, v130, v130
	v_fmac_f32_e32 v12, v131, v131
	v_fmac_f32_e32 v12, v132, v132
	v_fmac_f32_e32 v12, v133, v133
	v_fmac_f32_e32 v12, v134, v134
	v_fmac_f32_e32 v12, v135, v135
	v_fmac_f32_e32 v12, v136, v136
	v_fmac_f32_e32 v12, v137, v137
	v_fmac_f32_e32 v12, v138, v138
	v_fmac_f32_e32 v12, v139, v139
	v_fmac_f32_e32 v12, v140, v140
	v_fmac_f32_e32 v12, v141, v141
	v_fmac_f32_e32 v12, v142, v142
	v_fmac_f32_e32 v12, v143, v143
	v_mul_f32_e32 v13, v144, v144
	v_fmac_f32_e32 v13, v145, v145
	v_fmac_f32_e32 v13, v146, v146
	v_fmac_f32_e32 v13, v147, v147
	v_fmac_f32_e32 v13, v148, v148
	v_fmac_f32_e32 v13, v149, v149
	v_fmac_f32_e32 v13, v150, v150
	v_fmac_f32_e32 v13, v151, v151
	v_fmac_f32_e32 v13, v152, v152
	v_fmac_f32_e32 v13, v153, v153
	v_fmac_f32_e32 v13, v154, v154
	v_fmac_f32_e32 v13, v155, v155
	v_fmac_f32_e32 v13, v156, v156
	v_fmac_f32_e32 v13, v157, v157
	v_fmac_f32_e32 v13, v158, v158
	v_fmac_f32_e32 v13, v159, v159
	ds_bpermute_b32 v14, v4, v10
	ds_bpermute_b32 v15, v4, v11
	ds_bpermute_b32 v16, v4, v12
	ds_bpermute_b32 v17, v4, v13
	s_waitcnt lgkmcnt(0)
	v_add_f32_e32 v10, v10, v14
	v_add_f32_e32 v11, v11, v15
	v_add_f32_e32 v12, v12, v16
	v_add_f32_e32 v13, v13, v17
	ds_bpermute_b32 v14, v5, v10
	ds_bpermute_b32 v15, v5, v11
	ds_bpermute_b32 v16, v5, v12
	ds_bpermute_b32 v17, v5, v13
	s_waitcnt lgkmcnt(0)
	v_add_f32_e32 v10, v10, v14
	v_add_f32_e32 v11, v11, v15
	v_add_f32_e32 v12, v12, v16
	v_add_f32_e32 v13, v13, v17
	ds_bpermute_b32 v14, v6, v10
	ds_bpermute_b32 v15, v6, v11
	ds_bpermute_b32 v16, v6, v12
	ds_bpermute_b32 v17, v6, v13
	s_waitcnt lgkmcnt(0)
	v_add_f32_e32 v10, v10, v14
	v_add_f32_e32 v11, v11, v15
	v_add_f32_e32 v12, v12, v16
	v_add_f32_e32 v13, v13, v17
	ds_bpermute_b32 v14, v7, v10
	ds_bpermute_b32 v15, v7, v11
	ds_bpermute_b32 v16, v7, v12
	ds_bpermute_b32 v17, v7, v13
	s_waitcnt lgkmcnt(0)
	v_add_f32_e32 v10, v10, v14
	v_add_f32_e32 v11, v11, v15
	v_add_f32_e32 v12, v12, v16
	v_add_f32_e32 v13, v13, v17
	ds_bpermute_b32 v14, v8, v10
	ds_bpermute_b32 v15, v8, v11
	ds_bpermute_b32 v16, v8, v12
	ds_bpermute_b32 v17, v8, v13
	s_waitcnt lgkmcnt(0)
	v_add_f32_e32 v10, v10, v14
	v_add_f32_e32 v11, v11, v15
	v_add_f32_e32 v12, v12, v16
	v_add_f32_e32 v13, v13, v17
	ds_bpermute_b32 v14, v9, v10
	ds_bpermute_b32 v15, v9, v11
	ds_bpermute_b32 v16, v9, v12
	ds_bpermute_b32 v17, v9, v13
	s_waitcnt lgkmcnt(0)
	v_add_f32_e32 v10, v10, v14
	v_add_f32_e32 v11, v11, v15
	v_add_f32_e32 v12, v12, v16
	v_add_f32_e32 v13, v13, v17
	v_fma_f32 v10, v10, s32, v60
	v_fma_f32 v11, v11, s32, v60
	v_fma_f32 v12, v12, s32, v60
	v_fma_f32 v13, v13, s32, v60
	v_rsq_f32_e32 v18, v10
	v_rsq_f32_e32 v20, v11
	v_rsq_f32_e32 v22, v12
	v_rsq_f32_e32 v62, v13
	s_nop 0
	v_pk_mul_f32 v[96:97], v[96:97], v[18:19] op_sel_hi:[1,0]
	v_pk_mul_f32 v[98:99], v[98:99], v[18:19] op_sel_hi:[1,0]
	v_pk_mul_f32 v[100:101], v[100:101], v[18:19] op_sel_hi:[1,0]
	v_pk_mul_f32 v[102:103], v[102:103], v[18:19] op_sel_hi:[1,0]
	v_pk_mul_f32 v[104:105], v[104:105], v[18:19] op_sel_hi:[1,0]
	v_pk_mul_f32 v[106:107], v[106:107], v[18:19] op_sel_hi:[1,0]
	v_pk_mul_f32 v[108:109], v[108:109], v[18:19] op_sel_hi:[1,0]
	v_pk_mul_f32 v[110:111], v[110:111], v[18:19] op_sel_hi:[1,0]
	v_pk_mul_f32 v[96:97], v[24:25], v[96:97]
	v_pk_mul_f32 v[98:99], v[26:27], v[98:99]
	v_pk_mul_f32 v[100:101], v[28:29], v[100:101]
	v_pk_mul_f32 v[102:103], v[30:31], v[102:103]
	v_pk_mul_f32 v[104:105], v[32:33], v[104:105]
	v_pk_mul_f32 v[106:107], v[34:35], v[106:107]
	v_pk_mul_f32 v[108:109], v[36:37], v[108:109]
	v_pk_mul_f32 v[110:111], v[38:39], v[110:111]
	v_pk_fma_f32 v[96:97], v[40:41], v[96:97], v[80:81]
	v_pk_fma_f32 v[98:99], v[42:43], v[98:99], v[82:83]
	v_pk_fma_f32 v[100:101], v[64:65], v[100:101], v[84:85]
	v_pk_fma_f32 v[102:103], v[66:67], v[102:103], v[86:87]
	v_pk_fma_f32 v[104:105], v[68:69], v[104:105], v[88:89]
	v_pk_fma_f32 v[106:107], v[70:71], v[106:107], v[90:91]
	v_pk_fma_f32 v[108:109], v[72:73], v[108:109], v[92:93]
	v_pk_fma_f32 v[110:111], v[74:75], v[110:111], v[94:95]
	v_cvt_pk_bf16_f32 v96, v96, v97
	v_cvt_pk_bf16_f32 v97, v98, v99
	v_cvt_pk_bf16_f32 v100, v100, v101
	v_cvt_pk_bf16_f32 v101, v102, v103
	v_cvt_pk_bf16_f32 v104, v104, v105
	v_cvt_pk_bf16_f32 v105, v106, v107
	v_cvt_pk_bf16_f32 v108, v108, v109
	v_cvt_pk_bf16_f32 v109, v110, v111
	global_store_dwordx2 v2, v[96:97], s[10:11] sc1
	global_store_dwordx2 v2, v[100:101], s[10:11] offset:512 sc1
	global_store_dwordx2 v2, v[104:105], s[10:11] offset:1024 sc1
	global_store_dwordx2 v2, v[108:109], s[10:11] offset:1536 sc1
; DI unsigned pk2(float lo, float hi) { return f2bf(lo) | (f2bf(hi) << 16); }
; DI void norm_phase(const Args& A, int wave_s, int l, int which, int rows) {
;     ...
;     for (int m0 = C.gw * 2; m0 < rows; m0 += C.NGW * 2) {
;         f32x4 xv[2][4];
;         const float* modp[2];
; #pragma unroll
;         for (int rr = 0; rr < 2; ++rr) {
;             const int m = m0 + rr; const float* xr; int v;
;             if (m < NLAT) { xr = (from_in ? C.x : C.out) + (size_t)m * 1024; v = m >> 13; }
;             else { xr = (from_in ? C.ctx : C.XC) + (size_t)(m - NLAT) * 1024; v = 4; }
;             modp[rr] = C.SM + SM_MOD + (l * 5 + v) * 6144 + (which == 1 ? 0 : 3072);
; #pragma unroll
;             for (int j = 0; j < 4; ++j) xv[rr][j] = ((const f32x4*)xr)[C.lane + 64 * j];
;     ...
;             for (int j = 0; j < 4; ++j) { const int col = 4 * (C.lane + 64 * j);
;                 const f32x4 y = xv[rr][j] * rs * g[j] * (sc[j] + 1.f) + sh[j];
;                 v2u o; o.x = pk2(y.x, y.y); o.y = pk2(y.z, y.w);
;                 *(v2u*)(C.H + (size_t)m * 1024 + col) = o; }
	s_add_u32 s10, s10, 0x800
	s_addc_u32 s11, s11, 0
	v_pk_mul_f32 v[112:113], v[112:113], v[20:21] op_sel_hi:[1,0]
	v_pk_mul_f32 v[114:115], v[114:115], v[20:21] op_sel_hi:[1,0]
	v_pk_mul_f32 v[116:117], v[116:117], v[20:21] op_sel_hi:[1,0]
	v_pk_mul_f32 v[118:119], v[118:119], v[20:21] op_sel_hi:[1,0]
	v_pk_mul_f32 v[120:121], v[120:121], v[20:21] op_sel_hi:[1,0]
	v_pk_mul_f32 v[122:123], v[122:123], v[20:21] op_sel_hi:[1,0]
	v_pk_mul_f32 v[124:125], v[124:125], v[20:21] op_sel_hi:[1,0]
	v_pk_mul_f32 v[126:127], v[126:127], v[20:21] op_sel_hi:[1,0]
	v_pk_mul_f32 v[112:113], v[24:25], v[112:113]
	v_pk_mul_f32 v[114:115], v[26:27], v[114:115]
	v_pk_mul_f32 v[116:117], v[28:29], v[116:117]
	v_pk_mul_f32 v[118:119], v[30:31], v[118:119]
	v_pk_mul_f32 v[120:121], v[32:33], v[120:121]
	v_pk_mul_f32 v[122:123], v[34:35], v[122:123]
	v_pk_mul_f32 v[124:125], v[36:37], v[124:125]
	v_pk_mul_f32 v[126:127], v[38:39], v[126:127]
	v_pk_fma_f32 v[112:113], v[40:41], v[112:113], v[80:81]
	v_pk_fma_f32 v[114:115], v[42:43], v[114:115], v[82:83]
	v_pk_fma_f32 v[116:117], v[64:65], v[116:117], v[84:85]
	v_pk_fma_f32 v[118:119], v[66:67], v[118:119], v[86:87]
	v_pk_fma_f32 v[120:121], v[68:69], v[120:121], v[88:89]
	v_pk_fma_f32 v[122:123], v[70:71], v[122:123], v[90:91]
	v_pk_fma_f32 v[124:125], v[72:73], v[124:125], v[92:93]
	v_pk_fma_f32 v[126:127], v[74:75], v[126:127], v[94:95]
	v_cvt_pk_bf16_f32 v112, v112, v113
	v_cvt_pk_bf16_f32 v113, v114, v115
	v_cvt_pk_bf16_f32 v116, v116, v117
	v_cvt_pk_bf16_f32 v117, v118, v119
	v_cvt_pk_bf16_f32 v120, v120, v121
	v_cvt_pk_bf16_f32 v121, v122, v123
	v_cvt_pk_bf16_f32 v124, v124, v125
	v_cvt_pk_bf16_f32 v125, v126, v127
	global_store_dwordx2 v2, v[112:113], s[10:11] sc1
	global_store_dwordx2 v2, v[116:117], s[10:11] offset:512 sc1
	global_store_dwordx2 v2, v[120:121], s[10:11] offset:1024 sc1
	global_store_dwordx2 v2, v[124:125], s[10:11] offset:1536 sc1
	s_add_u32 s10, s10, 0x800
	s_addc_u32 s11, s11, 0
	v_pk_mul_f32 v[128:129], v[128:129], v[22:23] op_sel_hi:[1,0]
	v_pk_mul_f32 v[130:131], v[130:131], v[22:23] op_sel_hi:[1,0]
	v_pk_mul_f32 v[132:133], v[132:133], v[22:23] op_sel_hi:[1,0]
	v_pk_mul_f32 v[134:135], v[134:135], v[22:23] op_sel_hi:[1,0]
	v_pk_mul_f32 v[136:137], v[136:137], v[22:23] op_sel_hi:[1,0]
	v_pk_mul_f32 v[138:139], v[138:139], v[22:23] op_sel_hi:[1,0]
	v_pk_mul_f32 v[140:141], v[140:141], v[22:23] op_sel_hi:[1,0]
	v_pk_mul_f32 v[142:143], v[142:143], v[22:23] op_sel_hi:[1,0]
	v_pk_mul_f32 v[128:129], v[24:25], v[128:129]
	v_pk_mul_f32 v[130:131], v[26:27], v[130:131]
	v_pk_mul_f32 v[132:133], v[28:29], v[132:133]
	v_pk_mul_f32 v[134:135], v[30:31], v[134:135]
	v_pk_mul_f32 v[136:137], v[32:33], v[136:137]
	v_pk_mul_f32 v[138:139], v[34:35], v[138:139]
	v_pk_mul_f32 v[140:141], v[36:37], v[140:141]
	v_pk_mul_f32 v[142:143], v[38:39], v[142:143]
	v_pk_fma_f32 v[128:129], v[40:41], v[128:129], v[80:81]
	v_pk_fma_f32 v[130:131], v[42:43], v[130:131], v[82:83]
	v_pk_fma_f32 v[132:133], v[64:65], v[132:133], v[84:85]
	v_pk_fma_f32 v[134:135], v[66:67], v[134:135], v[86:87]
	v_pk_fma_f32 v[136:137], v[68:69], v[136:137], v[88:89]
	v_pk_fma_f32 v[138:139], v[70:71], v[138:139], v[90:91]
	v_pk_fma_f32 v[140:141], v[72:73], v[140:141], v[92:93]
	v_pk_fma_f32 v[142:143], v[74:75], v[142:143], v[94:95]
	v_cvt_pk_bf16_f32 v128, v128, v129
	v_cvt_pk_bf16_f32 v129, v130, v131
	v_cvt_pk_bf16_f32 v132, v132, v133
	v_cvt_pk_bf16_f32 v133, v134, v135
	v_cvt_pk_bf16_f32 v136, v136, v137
	v_cvt_pk_bf16_f32 v137, v138, v139
	v_cvt_pk_bf16_f32 v140, v140, v141
	v_cvt_pk_bf16_f32 v141, v142, v143
	global_store_dwordx2 v2, v[128:129], s[10:11] sc1
	global_store_dwordx2 v2, v[132:133], s[10:11] offset:512 sc1
	global_store_dwordx2 v2, v[136:137], s[10:11] offset:1024 sc1
	global_store_dwordx2 v2, v[140:141], s[10:11] offset:1536 sc1
	s_add_u32 s10, s10, 0x800
	s_addc_u32 s11, s11, 0
	v_pk_mul_f32 v[144:145], v[144:145], v[62:63] op_sel_hi:[1,0]
	v_pk_mul_f32 v[146:147], v[146:147], v[62:63] op_sel_hi:[1,0]
	v_pk_mul_f32 v[148:149], v[148:149], v[62:63] op_sel_hi:[1,0]
	v_pk_mul_f32 v[150:151], v[150:151], v[62:63] op_sel_hi:[1,0]
	v_pk_mul_f32 v[152:153], v[152:153], v[62:63] op_sel_hi:[1,0]
	v_pk_mul_f32 v[154:155], v[154:155], v[62:63] op_sel_hi:[1,0]
	v_pk_mul_f32 v[156:157], v[156:157], v[62:63] op_sel_hi:[1,0]
	v_pk_mul_f32 v[158:159], v[158:159], v[62:63] op_sel_hi:[1,0]
	v_pk_mul_f32 v[144:145], v[24:25], v[144:145]
	v_pk_mul_f32 v[146:147], v[26:27], v[146:147]
	v_pk_mul_f32 v[148:149], v[28:29], v[148:149]
	v_pk_mul_f32 v[150:151], v[30:31], v[150:151]
	v_pk_mul_f32 v[152:153], v[32:33], v[152:153]
	v_pk_mul_f32 v[154:155], v[34:35], v[154:155]
	v_pk_mul_f32 v[156:157], v[36:37], v[156:157]
	v_pk_mul_f32 v[158:159], v[38:39], v[158:159]
	v_pk_fma_f32 v[144:145], v[40:41], v[144:145], v[80:81]
	v_pk_fma_f32 v[146:147], v[42:43], v[146:147], v[82:83]
	v_pk_fma_f32 v[148:149], v[64:65], v[148:149], v[84:85]
	v_pk_fma_f32 v[150:151], v[66:67], v[150:151], v[86:87]
	v_pk_fma_f32 v[152:153], v[68:69], v[152:153], v[88:89]
	v_pk_fma_f32 v[154:155], v[70:71], v[154:155], v[90:91]
	v_pk_fma_f32 v[156:157], v[72:73], v[156:157], v[92:93]
	v_pk_fma_f32 v[158:159], v[74:75], v[158:159], v[94:95]
	v_cvt_pk_bf16_f32 v144, v144, v145
	v_cvt_pk_bf16_f32 v145, v146, v147
	v_cvt_pk_bf16_f32 v148, v148, v149
	v_cvt_pk_bf16_f32 v149, v150, v151
	v_cvt_pk_bf16_f32 v152, v152, v153
	v_cvt_pk_bf16_f32 v153, v154, v155
	v_cvt_pk_bf16_f32 v156, v156, v157
	v_cvt_pk_bf16_f32 v157, v158, v159
	global_store_dwordx2 v2, v[144:145], s[10:11] sc1
	global_store_dwordx2 v2, v[148:149], s[10:11] offset:512 sc1
	global_store_dwordx2 v2, v[152:153], s[10:11] offset:1024 sc1
	global_store_dwordx2 v2, v[156:157], s[10:11] offset:1536 sc1
	s_add_u32 s10, s10, 0x800
	s_addc_u32 s11, s11, 0
	global_load_dwordx4 v[96:99], v1, s[8:9]
	global_load_dwordx4 v[100:103], v1, s[8:9] offset:1024
	global_load_dwordx4 v[104:107], v1, s[8:9] offset:2048
	global_load_dwordx4 v[108:111], v1, s[8:9] offset:3072
	s_add_u32 s8, s8, 0x1000
	s_addc_u32 s9, s9, 0
	global_load_dwordx4 v[112:115], v1, s[8:9]
	global_load_dwordx4 v[116:119], v1, s[8:9] offset:1024
	global_load_dwordx4 v[120:123], v1, s[8:9] offset:2048
	global_load_dwordx4 v[124:127], v1, s[8:9] offset:3072
	s_add_u32 s8, s8, 0x1000
	s_addc_u32 s9, s9, 0
	global_load_dwordx4 v[128:131], v1, s[8:9]
	global_load_dwordx4 v[132:135], v1, s[8:9] offset:1024
	global_load_dwordx4 v[136:139], v1, s[8:9] offset:2048
	global_load_dwordx4 v[140:143], v1, s[8:9] offset:3072
	s_add_u32 s8, s8, 0x1000
	s_addc_u32 s9, s9, 0
	global_load_dwordx4 v[144:147], v1, s[8:9]
	global_load_dwordx4 v[148:151], v1, s[8:9] offset:1024
	global_load_dwordx4 v[152:155], v1, s[8:9] offset:2048
	global_load_dwordx4 v[156:159], v1, s[8:9] offset:3072
	s_add_u32 s8, s8, 0x1000
	s_addc_u32 s9, s9, 0
	s_waitcnt vmcnt(32)
; DI unsigned pk2(float lo, float hi) { return f2bf(lo) | (f2bf(hi) << 16); }
; DI void norm_phase(const Args& A, int wave_s, int l, int which, int rows) {
;     ...
;             float ss = 0.f;
; #pragma unroll
;             for (int j = 0; j < 4; ++j) ss += (xv[rr][j].x * xv[rr][j].x + xv[rr][j].y * xv[rr][j].y) + (xv[rr][j].z * xv[rr][j].z + xv[rr][j].w * xv[rr][j].w);
;             ss = wave_sum(C.lane, ss);
;             const float rs = rsqrtf(ss * (1.f / 1024.f) + EPS);
; #pragma unroll
;             for (int j = 0; j < 4; ++j) { const int col = 4 * (C.lane + 64 * j);
;                 const f32x4 y = xv[rr][j] * rs * g[j] * (sc[j] + 1.f) + sh[j];
;                 v2u o; o.x = pk2(y.x, y.y); o.y = pk2(y.z, y.w);
;                 *(v2u*)(C.H + (size_t)m * 1024 + col) = o; }
	v_mul_f32_e32 v10, v164, v164
	v_fmac_f32_e32 v10, v165, v165
	v_fmac_f32_e32 v10, v166, v166
	v_fmac_f32_e32 v10, v167, v167
	v_fmac_f32_e32 v10, v168, v168
	v_fmac_f32_e32 v10, v169, v169
	v_fmac_f32_e32 v10, v170, v170
	v_fmac_f32_e32 v10, v171, v171
	v_fmac_f32_e32 v10, v172, v172
	v_fmac_f32_e32 v10, v173, v173
	v_fmac_f32_e32 v10, v174, v174
	v_fmac_f32_e32 v10, v175, v175
	v_fmac_f32_e32 v10, v176, v176
	v_fmac_f32_e32 v10, v177, v177
	v_fmac_f32_e32 v10, v178, v178
	v_fmac_f32_e32 v10, v179, v179
	v_mul_f32_e32 v11, v180, v180
	v_fmac_f32_e32 v11, v181, v181
	v_fmac_f32_e32 v11, v182, v182
	v_fmac_f32_e32 v11, v183, v183
	v_fmac_f32_e32 v11, v184, v184
	v_fmac_f32_e32 v11, v185, v185
	v_fmac_f32_e32 v11, v186, v186
	v_fmac_f32_e32 v11, v187, v187
	v_fmac_f32_e32 v11, v188, v188
	v_fmac_f32_e32 v11, v189, v189
	v_fmac_f32_e32 v11, v190, v190
	v_fmac_f32_e32 v11, v191, v191
	v_fmac_f32_e32 v11, v192, v192
	v_fmac_f32_e32 v11, v193, v193
	v_fmac_f32_e32 v11, v194, v194
	v_fmac_f32_e32 v11, v195, v195
	v_mul_f32_e32 v12, v196, v196
	v_fmac_f32_e32 v12, v197, v197
	v_fmac_f32_e32 v12, v198, v198
	v_fmac_f32_e32 v12, v199, v199
	v_fmac_f32_e32 v12, v200, v200
	v_fmac_f32_e32 v12, v201, v201
	v_fmac_f32_e32 v12, v202, v202
	v_fmac_f32_e32 v12, v203, v203
	v_fmac_f32_e32 v12, v204, v204
	v_fmac_f32_e32 v12, v205, v205
	v_fmac_f32_e32 v12, v206, v206
	v_fmac_f32_e32 v12, v207, v207
	v_fmac_f32_e32 v12, v208, v208
	v_fmac_f32_e32 v12, v209, v209
	v_fmac_f32_e32 v12, v210, v210
	v_fmac_f32_e32 v12, v211, v211
	v_mul_f32_e32 v13, v212, v212
	v_fmac_f32_e32 v13, v213, v213
	v_fmac_f32_e32 v13, v214, v214
	v_fmac_f32_e32 v13, v215, v215
	v_fmac_f32_e32 v13, v216, v216
	v_fmac_f32_e32 v13, v217, v217
	v_fmac_f32_e32 v13, v218, v218
	v_fmac_f32_e32 v13, v219, v219
	v_fmac_f32_e32 v13, v220, v220
	v_fmac_f32_e32 v13, v221, v221
	v_fmac_f32_e32 v13, v222, v222
	v_fmac_f32_e32 v13, v223, v223
	v_fmac_f32_e32 v13, v224, v224
	v_fmac_f32_e32 v13, v225, v225
	v_fmac_f32_e32 v13, v226, v226
	v_fmac_f32_e32 v13, v227, v227
	ds_bpermute_b32 v14, v4, v10
	ds_bpermute_b32 v15, v4, v11
	ds_bpermute_b32 v16, v4, v12
	ds_bpermute_b32 v17, v4, v13
	s_waitcnt lgkmcnt(0)
	v_add_f32_e32 v10, v10, v14
	v_add_f32_e32 v11, v11, v15
	v_add_f32_e32 v12, v12, v16
	v_add_f32_e32 v13, v13, v17
	ds_bpermute_b32 v14, v5, v10
	ds_bpermute_b32 v15, v5, v11
	ds_bpermute_b32 v16, v5, v12
	ds_bpermute_b32 v17, v5, v13
	s_waitcnt lgkmcnt(0)
	v_add_f32_e32 v10, v10, v14
	v_add_f32_e32 v11, v11, v15
	v_add_f32_e32 v12, v12, v16
	v_add_f32_e32 v13, v13, v17
	ds_bpermute_b32 v14, v6, v10
	ds_bpermute_b32 v15, v6, v11
	ds_bpermute_b32 v16, v6, v12
	ds_bpermute_b32 v17, v6, v13
	s_waitcnt lgkmcnt(0)
	v_add_f32_e32 v10, v10, v14
	v_add_f32_e32 v11, v11, v15
	v_add_f32_e32 v12, v12, v16
	v_add_f32_e32 v13, v13, v17
	ds_bpermute_b32 v14, v7, v10
	ds_bpermute_b32 v15, v7, v11
	ds_bpermute_b32 v16, v7, v12
	ds_bpermute_b32 v17, v7, v13
	s_waitcnt lgkmcnt(0)
	v_add_f32_e32 v10, v10, v14
	v_add_f32_e32 v11, v11, v15
	v_add_f32_e32 v12, v12, v16
	v_add_f32_e32 v13, v13, v17
	ds_bpermute_b32 v14, v8, v10
	ds_bpermute_b32 v15, v8, v11
	ds_bpermute_b32 v16, v8, v12
	ds_bpermute_b32 v17, v8, v13
	s_waitcnt lgkmcnt(0)
	v_add_f32_e32 v10, v10, v14
	v_add_f32_e32 v11, v11, v15
	v_add_f32_e32 v12, v12, v16
	v_add_f32_e32 v13, v13, v17
	ds_bpermute_b32 v14, v9, v10
	ds_bpermute_b32 v15, v9, v11
	ds_bpermute_b32 v16, v9, v12
	ds_bpermute_b32 v17, v9, v13
	s_waitcnt lgkmcnt(0)
	v_add_f32_e32 v10, v10, v14
	v_add_f32_e32 v11, v11, v15
	v_add_f32_e32 v12, v12, v16
	v_add_f32_e32 v13, v13, v17
	v_fma_f32 v10, v10, s32, v60
	v_fma_f32 v11, v11, s32, v60
	v_fma_f32 v12, v12, s32, v60
	v_fma_f32 v13, v13, s32, v60
	v_rsq_f32_e32 v18, v10
	v_rsq_f32_e32 v20, v11
	v_rsq_f32_e32 v22, v12
	v_rsq_f32_e32 v62, v13
	s_nop 0
	v_pk_mul_f32 v[164:165], v[164:165], v[18:19] op_sel_hi:[1,0]
	v_pk_mul_f32 v[166:167], v[166:167], v[18:19] op_sel_hi:[1,0]
	v_pk_mul_f32 v[168:169], v[168:169], v[18:19] op_sel_hi:[1,0]
	v_pk_mul_f32 v[170:171], v[170:171], v[18:19] op_sel_hi:[1,0]
	v_pk_mul_f32 v[172:173], v[172:173], v[18:19] op_sel_hi:[1,0]
	v_pk_mul_f32 v[174:175], v[174:175], v[18:19] op_sel_hi:[1,0]
	v_pk_mul_f32 v[176:177], v[176:177], v[18:19] op_sel_hi:[1,0]
	v_pk_mul_f32 v[178:179], v[178:179], v[18:19] op_sel_hi:[1,0]
	v_pk_mul_f32 v[164:165], v[24:25], v[164:165]
	v_pk_mul_f32 v[166:167], v[26:27], v[166:167]
	v_pk_mul_f32 v[168:169], v[28:29], v[168:169]
	v_pk_mul_f32 v[170:171], v[30:31], v[170:171]
	v_pk_mul_f32 v[172:173], v[32:33], v[172:173]
	v_pk_mul_f32 v[174:175], v[34:35], v[174:175]
	v_pk_mul_f32 v[176:177], v[36:37], v[176:177]
	v_pk_mul_f32 v[178:179], v[38:39], v[178:179]
	v_pk_fma_f32 v[164:165], v[40:41], v[164:165], v[80:81]
	v_pk_fma_f32 v[166:167], v[42:43], v[166:167], v[82:83]
	v_pk_fma_f32 v[168:169], v[64:65], v[168:169], v[84:85]
	v_pk_fma_f32 v[170:171], v[66:67], v[170:171], v[86:87]
	v_pk_fma_f32 v[172:173], v[68:69], v[172:173], v[88:89]
	v_pk_fma_f32 v[174:175], v[70:71], v[174:175], v[90:91]
	v_pk_fma_f32 v[176:177], v[72:73], v[176:177], v[92:93]
	v_pk_fma_f32 v[178:179], v[74:75], v[178:179], v[94:95]
	v_cvt_pk_bf16_f32 v164, v164, v165
	v_cvt_pk_bf16_f32 v165, v166, v167
	v_cvt_pk_bf16_f32 v168, v168, v169
	v_cvt_pk_bf16_f32 v169, v170, v171
	v_cvt_pk_bf16_f32 v172, v172, v173
	v_cvt_pk_bf16_f32 v173, v174, v175
	v_cvt_pk_bf16_f32 v176, v176, v177
	v_cvt_pk_bf16_f32 v177, v178, v179
	global_store_dwordx2 v2, v[164:165], s[10:11] sc1
	global_store_dwordx2 v2, v[168:169], s[10:11] offset:512 sc1
	global_store_dwordx2 v2, v[172:173], s[10:11] offset:1024 sc1
; DI unsigned pk2(float lo, float hi) { return f2bf(lo) | (f2bf(hi) << 16); }
; DI void norm_phase(const Args& A, int wave_s, int l, int which, int rows) {
;     ...
;             for (int j = 0; j < 4; ++j) { const int col = 4 * (C.lane + 64 * j);
;                 const f32x4 y = xv[rr][j] * rs * g[j] * (sc[j] + 1.f) + sh[j];
;                 v2u o; o.x = pk2(y.x, y.y); o.y = pk2(y.z, y.w);
;                 *(v2u*)(C.H + (size_t)m * 1024 + col) = o; }
	global_store_dwordx2 v2, v[176:177], s[10:11] offset:1536 sc1
	s_add_u32 s10, s10, 0x800
	s_addc_u32 s11, s11, 0
	v_pk_mul_f32 v[180:181], v[180:181], v[20:21] op_sel_hi:[1,0]
	v_pk_mul_f32 v[182:183], v[182:183], v[20:21] op_sel_hi:[1,0]
	v_pk_mul_f32 v[184:185], v[184:185], v[20:21] op_sel_hi:[1,0]
	v_pk_mul_f32 v[186:187], v[186:187], v[20:21] op_sel_hi:[1,0]
	v_pk_mul_f32 v[188:189], v[188:189], v[20:21] op_sel_hi:[1,0]
	v_pk_mul_f32 v[190:191], v[190:191], v[20:21] op_sel_hi:[1,0]
	v_pk_mul_f32 v[192:193], v[192:193], v[20:21] op_sel_hi:[1,0]
	v_pk_mul_f32 v[194:195], v[194:195], v[20:21] op_sel_hi:[1,0]
	v_pk_mul_f32 v[180:181], v[24:25], v[180:181]
	v_pk_mul_f32 v[182:183], v[26:27], v[182:183]
	v_pk_mul_f32 v[184:185], v[28:29], v[184:185]
	v_pk_mul_f32 v[186:187], v[30:31], v[186:187]
	v_pk_mul_f32 v[188:189], v[32:33], v[188:189]
	v_pk_mul_f32 v[190:191], v[34:35], v[190:191]
	v_pk_mul_f32 v[192:193], v[36:37], v[192:193]
	v_pk_mul_f32 v[194:195], v[38:39], v[194:195]
	v_pk_fma_f32 v[180:181], v[40:41], v[180:181], v[80:81]
	v_pk_fma_f32 v[182:183], v[42:43], v[182:183], v[82:83]
	v_pk_fma_f32 v[184:185], v[64:65], v[184:185], v[84:85]
	v_pk_fma_f32 v[186:187], v[66:67], v[186:187], v[86:87]
	v_pk_fma_f32 v[188:189], v[68:69], v[188:189], v[88:89]
	v_pk_fma_f32 v[190:191], v[70:71], v[190:191], v[90:91]
	v_pk_fma_f32 v[192:193], v[72:73], v[192:193], v[92:93]
	v_pk_fma_f32 v[194:195], v[74:75], v[194:195], v[94:95]
	v_cvt_pk_bf16_f32 v180, v180, v181
	v_cvt_pk_bf16_f32 v181, v182, v183
	v_cvt_pk_bf16_f32 v184, v184, v185
	v_cvt_pk_bf16_f32 v185, v186, v187
	v_cvt_pk_bf16_f32 v188, v188, v189
	v_cvt_pk_bf16_f32 v189, v190, v191
	v_cvt_pk_bf16_f32 v192, v192, v193
	v_cvt_pk_bf16_f32 v193, v194, v195
	global_store_dwordx2 v2, v[180:181], s[10:11] sc1
	global_store_dwordx2 v2, v[184:185], s[10:11] offset:512 sc1
	global_store_dwordx2 v2, v[188:189], s[10:11] offset:1024 sc1
	global_store_dwordx2 v2, v[192:193], s[10:11] offset:1536 sc1
	s_add_u32 s10, s10, 0x800
	s_addc_u32 s11, s11, 0
	v_pk_mul_f32 v[196:197], v[196:197], v[22:23] op_sel_hi:[1,0]
	v_pk_mul_f32 v[198:199], v[198:199], v[22:23] op_sel_hi:[1,0]
	v_pk_mul_f32 v[200:201], v[200:201], v[22:23] op_sel_hi:[1,0]
	v_pk_mul_f32 v[202:203], v[202:203], v[22:23] op_sel_hi:[1,0]
	v_pk_mul_f32 v[204:205], v[204:205], v[22:23] op_sel_hi:[1,0]
	v_pk_mul_f32 v[206:207], v[206:207], v[22:23] op_sel_hi:[1,0]
	v_pk_mul_f32 v[208:209], v[208:209], v[22:23] op_sel_hi:[1,0]
	v_pk_mul_f32 v[210:211], v[210:211], v[22:23] op_sel_hi:[1,0]
	v_pk_mul_f32 v[196:197], v[24:25], v[196:197]
	v_pk_mul_f32 v[198:199], v[26:27], v[198:199]
	v_pk_mul_f32 v[200:201], v[28:29], v[200:201]
	v_pk_mul_f32 v[202:203], v[30:31], v[202:203]
	v_pk_mul_f32 v[204:205], v[32:33], v[204:205]
	v_pk_mul_f32 v[206:207], v[34:35], v[206:207]
	v_pk_mul_f32 v[208:209], v[36:37], v[208:209]
	v_pk_mul_f32 v[210:211], v[38:39], v[210:211]
	v_pk_fma_f32 v[196:197], v[40:41], v[196:197], v[80:81]
	v_pk_fma_f32 v[198:199], v[42:43], v[198:199], v[82:83]
	v_pk_fma_f32 v[200:201], v[64:65], v[200:201], v[84:85]
	v_pk_fma_f32 v[202:203], v[66:67], v[202:203], v[86:87]
	v_pk_fma_f32 v[204:205], v[68:69], v[204:205], v[88:89]
	v_pk_fma_f32 v[206:207], v[70:71], v[206:207], v[90:91]
	v_pk_fma_f32 v[208:209], v[72:73], v[208:209], v[92:93]
	v_pk_fma_f32 v[210:211], v[74:75], v[210:211], v[94:95]
	v_cvt_pk_bf16_f32 v196, v196, v197
	v_cvt_pk_bf16_f32 v197, v198, v199
	v_cvt_pk_bf16_f32 v200, v200, v201
	v_cvt_pk_bf16_f32 v201, v202, v203
	v_cvt_pk_bf16_f32 v204, v204, v205
	v_cvt_pk_bf16_f32 v205, v206, v207
	v_cvt_pk_bf16_f32 v208, v208, v209
	v_cvt_pk_bf16_f32 v209, v210, v211
	global_store_dwordx2 v2, v[196:197], s[10:11] sc1
	global_store_dwordx2 v2, v[200:201], s[10:11] offset:512 sc1
	global_store_dwordx2 v2, v[204:205], s[10:11] offset:1024 sc1
	global_store_dwordx2 v2, v[208:209], s[10:11] offset:1536 sc1
	s_add_u32 s10, s10, 0x800
	s_addc_u32 s11, s11, 0
	v_pk_mul_f32 v[212:213], v[212:213], v[62:63] op_sel_hi:[1,0]
	v_pk_mul_f32 v[214:215], v[214:215], v[62:63] op_sel_hi:[1,0]
	v_pk_mul_f32 v[216:217], v[216:217], v[62:63] op_sel_hi:[1,0]
	v_pk_mul_f32 v[218:219], v[218:219], v[62:63] op_sel_hi:[1,0]
	v_pk_mul_f32 v[220:221], v[220:221], v[62:63] op_sel_hi:[1,0]
	v_pk_mul_f32 v[222:223], v[222:223], v[62:63] op_sel_hi:[1,0]
	v_pk_mul_f32 v[224:225], v[224:225], v[62:63] op_sel_hi:[1,0]
	v_pk_mul_f32 v[226:227], v[226:227], v[62:63] op_sel_hi:[1,0]
	v_pk_mul_f32 v[212:213], v[24:25], v[212:213]
	v_pk_mul_f32 v[214:215], v[26:27], v[214:215]
	v_pk_mul_f32 v[216:217], v[28:29], v[216:217]
	v_pk_mul_f32 v[218:219], v[30:31], v[218:219]
	v_pk_mul_f32 v[220:221], v[32:33], v[220:221]
	v_pk_mul_f32 v[222:223], v[34:35], v[222:223]
	v_pk_mul_f32 v[224:225], v[36:37], v[224:225]
	v_pk_mul_f32 v[226:227], v[38:39], v[226:227]
	v_pk_fma_f32 v[212:213], v[40:41], v[212:213], v[80:81]
	v_pk_fma_f32 v[214:215], v[42:43], v[214:215], v[82:83]
	v_pk_fma_f32 v[216:217], v[64:65], v[216:217], v[84:85]
	v_pk_fma_f32 v[218:219], v[66:67], v[218:219], v[86:87]
	v_pk_fma_f32 v[220:221], v[68:69], v[220:221], v[88:89]
	v_pk_fma_f32 v[222:223], v[70:71], v[222:223], v[90:91]
	v_pk_fma_f32 v[224:225], v[72:73], v[224:225], v[92:93]
	v_pk_fma_f32 v[226:227], v[74:75], v[226:227], v[94:95]
	v_cvt_pk_bf16_f32 v212, v212, v213
	v_cvt_pk_bf16_f32 v213, v214, v215
	v_cvt_pk_bf16_f32 v216, v216, v217
	v_cvt_pk_bf16_f32 v217, v218, v219
	v_cvt_pk_bf16_f32 v220, v220, v221
	v_cvt_pk_bf16_f32 v221, v222, v223
	v_cvt_pk_bf16_f32 v224, v224, v225
	v_cvt_pk_bf16_f32 v225, v226, v227
	global_store_dwordx2 v2, v[212:213], s[10:11] sc1
	global_store_dwordx2 v2, v[216:217], s[10:11] offset:512 sc1
	global_store_dwordx2 v2, v[220:221], s[10:11] offset:1024 sc1
	global_store_dwordx2 v2, v[224:225], s[10:11] offset:1536 sc1
	s_add_u32 s10, s10, 0x800
	s_addc_u32 s11, s11, 0
	global_load_dwordx4 v[164:167], v1, s[8:9]
	global_load_dwordx4 v[168:171], v1, s[8:9] offset:1024
	global_load_dwordx4 v[172:175], v1, s[8:9] offset:2048
	global_load_dwordx4 v[176:179], v1, s[8:9] offset:3072
	s_add_u32 s8, s8, 0x1000
	s_addc_u32 s9, s9, 0
	global_load_dwordx4 v[180:183], v1, s[8:9]
	global_load_dwordx4 v[184:187], v1, s[8:9] offset:1024
	global_load_dwordx4 v[188:191], v1, s[8:9] offset:2048
	global_load_dwordx4 v[192:195], v1, s[8:9] offset:3072
	s_add_u32 s8, s8, 0x1000
	s_addc_u32 s9, s9, 0
	global_load_dwordx4 v[196:199], v1, s[8:9]
	global_load_dwordx4 v[200:203], v1, s[8:9] offset:1024
	global_load_dwordx4 v[204:207], v1, s[8:9] offset:2048
	global_load_dwordx4 v[208:211], v1, s[8:9] offset:3072
	s_add_u32 s8, s8, 0x1000
	s_addc_u32 s9, s9, 0
	global_load_dwordx4 v[212:215], v1, s[8:9]
	global_load_dwordx4 v[216:219], v1, s[8:9] offset:1024
	global_load_dwordx4 v[220:223], v1, s[8:9] offset:2048
	global_load_dwordx4 v[224:227], v1, s[8:9] offset:3072
	s_add_u32 s8, s8, 0x1000
	s_addc_u32 s9, s9, 0
	s_waitcnt vmcnt(32)
; DI unsigned pk2(float lo, float hi) { return f2bf(lo) | (f2bf(hi) << 16); }
; DI void norm_phase(const Args& A, int wave_s, int l, int which, int rows) {
;     ...
;             float ss = 0.f;
; #pragma unroll
;             for (int j = 0; j < 4; ++j) ss += (xv[rr][j].x * xv[rr][j].x + xv[rr][j].y * xv[rr][j].y) + (xv[rr][j].z * xv[rr][j].z + xv[rr][j].w * xv[rr][j].w);
;             ss = wave_sum(C.lane, ss);
;             const float rs = rsqrtf(ss * (1.f / 1024.f) + EPS);
; #pragma unroll
;             for (int j = 0; j < 4; ++j) { const int col = 4 * (C.lane + 64 * j);
;                 const f32x4 y = xv[rr][j] * rs * g[j] * (sc[j] + 1.f) + sh[j];
;                 v2u o; o.x = pk2(y.x, y.y); o.y = pk2(y.z, y.w);
;                 *(v2u*)(C.H + (size_t)m * 1024 + col) = o; }
	v_mul_f32_e32 v10, v96, v96
	v_fmac_f32_e32 v10, v97, v97
	v_fmac_f32_e32 v10, v98, v98
	v_fmac_f32_e32 v10, v99, v99
	v_fmac_f32_e32 v10, v100, v100
	v_fmac_f32_e32 v10, v101, v101
	v_fmac_f32_e32 v10, v102, v102
	v_fmac_f32_e32 v10, v103, v103
	v_fmac_f32_e32 v10, v104, v104
	v_fmac_f32_e32 v10, v105, v105
	v_fmac_f32_e32 v10, v106, v106
	v_fmac_f32_e32 v10, v107, v107
	v_fmac_f32_e32 v10, v108, v108
	v_fmac_f32_e32 v10, v109, v109
	v_fmac_f32_e32 v10, v110, v110
	v_fmac_f32_e32 v10, v111, v111
	v_mul_f32_e32 v11, v112, v112
	v_fmac_f32_e32 v11, v113, v113
	v_fmac_f32_e32 v11, v114, v114
	v_fmac_f32_e32 v11, v115, v115
	v_fmac_f32_e32 v11, v116, v116
	v_fmac_f32_e32 v11, v117, v117
	v_fmac_f32_e32 v11, v118, v118
	v_fmac_f32_e32 v11, v119, v119
	v_fmac_f32_e32 v11, v120, v120
	v_fmac_f32_e32 v11, v121, v121
	v_fmac_f32_e32 v11, v122, v122
	v_fmac_f32_e32 v11, v123, v123
	v_fmac_f32_e32 v11, v124, v124
	v_fmac_f32_e32 v11, v125, v125
	v_fmac_f32_e32 v11, v126, v126
	v_fmac_f32_e32 v11, v127, v127
	v_mul_f32_e32 v12, v128, v128
	v_fmac_f32_e32 v12, v129, v129
	v_fmac_f32_e32 v12, v130, v130
	v_fmac_f32_e32 v12, v131, v131
	v_fmac_f32_e32 v12, v132, v132
	v_fmac_f32_e32 v12, v133, v133
	v_fmac_f32_e32 v12, v134, v134
	v_fmac_f32_e32 v12, v135, v135
	v_fmac_f32_e32 v12, v136, v136
	v_fmac_f32_e32 v12, v137, v137
	v_fmac_f32_e32 v12, v138, v138
	v_fmac_f32_e32 v12, v139, v139
	v_fmac_f32_e32 v12, v140, v140
	v_fmac_f32_e32 v12, v141, v141
	v_fmac_f32_e32 v12, v142, v142
	v_fmac_f32_e32 v12, v143, v143
	v_mul_f32_e32 v13, v144, v144
	v_fmac_f32_e32 v13, v145, v145
	v_fmac_f32_e32 v13, v146, v146
	v_fmac_f32_e32 v13, v147, v147
	v_fmac_f32_e32 v13, v148, v148
	v_fmac_f32_e32 v13, v149, v149
	v_fmac_f32_e32 v13, v150, v150
	v_fmac_f32_e32 v13, v151, v151
	v_fmac_f32_e32 v13, v152, v152
	v_fmac_f32_e32 v13, v153, v153
	v_fmac_f32_e32 v13, v154, v154
	v_fmac_f32_e32 v13, v155, v155
	v_fmac_f32_e32 v13, v156, v156
	v_fmac_f32_e32 v13, v157, v157
	v_fmac_f32_e32 v13, v158, v158
	v_fmac_f32_e32 v13, v159, v159
	ds_bpermute_b32 v14, v4, v10
	ds_bpermute_b32 v15, v4, v11
	ds_bpermute_b32 v16, v4, v12
	ds_bpermute_b32 v17, v4, v13
	s_waitcnt lgkmcnt(0)
	v_add_f32_e32 v10, v10, v14
	v_add_f32_e32 v11, v11, v15
	v_add_f32_e32 v12, v12, v16
	v_add_f32_e32 v13, v13, v17
	ds_bpermute_b32 v14, v5, v10
	ds_bpermute_b32 v15, v5, v11
	ds_bpermute_b32 v16, v5, v12
	ds_bpermute_b32 v17, v5, v13
	s_waitcnt lgkmcnt(0)
	v_add_f32_e32 v10, v10, v14
	v_add_f32_e32 v11, v11, v15
	v_add_f32_e32 v12, v12, v16
	v_add_f32_e32 v13, v13, v17
	ds_bpermute_b32 v14, v6, v10
	ds_bpermute_b32 v15, v6, v11
	ds_bpermute_b32 v16, v6, v12
	ds_bpermute_b32 v17, v6, v13
	s_waitcnt lgkmcnt(0)
	v_add_f32_e32 v10, v10, v14
	v_add_f32_e32 v11, v11, v15
	v_add_f32_e32 v12, v12, v16
	v_add_f32_e32 v13, v13, v17
	ds_bpermute_b32 v14, v7, v10
	ds_bpermute_b32 v15, v7, v11
	ds_bpermute_b32 v16, v7, v12
	ds_bpermute_b32 v17, v7, v13
	s_waitcnt lgkmcnt(0)
	v_add_f32_e32 v10, v10, v14
	v_add_f32_e32 v11, v11, v15
	v_add_f32_e32 v12, v12, v16
	v_add_f32_e32 v13, v13, v17
	ds_bpermute_b32 v14, v8, v10
	ds_bpermute_b32 v15, v8, v11
	ds_bpermute_b32 v16, v8, v12
	ds_bpermute_b32 v17, v8, v13
	s_waitcnt lgkmcnt(0)
	v_add_f32_e32 v10, v10, v14
	v_add_f32_e32 v11, v11, v15
	v_add_f32_e32 v12, v12, v16
	v_add_f32_e32 v13, v13, v17
	ds_bpermute_b32 v14, v9, v10
	ds_bpermute_b32 v15, v9, v11
	ds_bpermute_b32 v16, v9, v12
	ds_bpermute_b32 v17, v9, v13
	s_waitcnt lgkmcnt(0)
	v_add_f32_e32 v10, v10, v14
	v_add_f32_e32 v11, v11, v15
	v_add_f32_e32 v12, v12, v16
	v_add_f32_e32 v13, v13, v17
	v_fma_f32 v10, v10, s32, v60
	v_fma_f32 v11, v11, s32, v60
	v_fma_f32 v12, v12, s32, v60
	v_fma_f32 v13, v13, s32, v60
	v_rsq_f32_e32 v18, v10
	v_rsq_f32_e32 v20, v11
	v_rsq_f32_e32 v22, v12
	v_rsq_f32_e32 v62, v13
	s_nop 0
	v_pk_mul_f32 v[96:97], v[96:97], v[18:19] op_sel_hi:[1,0]
	v_pk_mul_f32 v[98:99], v[98:99], v[18:19] op_sel_hi:[1,0]
	v_pk_mul_f32 v[100:101], v[100:101], v[18:19] op_sel_hi:[1,0]
	v_pk_mul_f32 v[102:103], v[102:103], v[18:19] op_sel_hi:[1,0]
	v_pk_mul_f32 v[104:105], v[104:105], v[18:19] op_sel_hi:[1,0]
	v_pk_mul_f32 v[106:107], v[106:107], v[18:19] op_sel_hi:[1,0]
	v_pk_mul_f32 v[108:109], v[108:109], v[18:19] op_sel_hi:[1,0]
	v_pk_mul_f32 v[110:111], v[110:111], v[18:19] op_sel_hi:[1,0]
	v_pk_mul_f32 v[96:97], v[24:25], v[96:97]
	v_pk_mul_f32 v[98:99], v[26:27], v[98:99]
	v_pk_mul_f32 v[100:101], v[28:29], v[100:101]
	v_pk_mul_f32 v[102:103], v[30:31], v[102:103]
	v_pk_mul_f32 v[104:105], v[32:33], v[104:105]
	v_pk_mul_f32 v[106:107], v[34:35], v[106:107]
	v_pk_mul_f32 v[108:109], v[36:37], v[108:109]
	v_pk_mul_f32 v[110:111], v[38:39], v[110:111]
	v_pk_fma_f32 v[96:97], v[40:41], v[96:97], v[80:81]
	v_pk_fma_f32 v[98:99], v[42:43], v[98:99], v[82:83]
	v_pk_fma_f32 v[100:101], v[64:65], v[100:101], v[84:85]
	v_pk_fma_f32 v[102:103], v[66:67], v[102:103], v[86:87]
	v_pk_fma_f32 v[104:105], v[68:69], v[104:105], v[88:89]
	v_pk_fma_f32 v[106:107], v[70:71], v[106:107], v[90:91]
	v_pk_fma_f32 v[108:109], v[72:73], v[108:109], v[92:93]
	v_pk_fma_f32 v[110:111], v[74:75], v[110:111], v[94:95]
	v_cvt_pk_bf16_f32 v96, v96, v97
	v_cvt_pk_bf16_f32 v97, v98, v99
	v_cvt_pk_bf16_f32 v100, v100, v101
	v_cvt_pk_bf16_f32 v101, v102, v103
	v_cvt_pk_bf16_f32 v104, v104, v105
	v_cvt_pk_bf16_f32 v105, v106, v107
	v_cvt_pk_bf16_f32 v108, v108, v109
	v_cvt_pk_bf16_f32 v109, v110, v111
	global_store_dwordx2 v2, v[96:97], s[10:11] sc1
	global_store_dwordx2 v2, v[100:101], s[10:11] offset:512 sc1
	global_store_dwordx2 v2, v[104:105], s[10:11] offset:1024 sc1
	global_store_dwordx2 v2, v[108:109], s[10:11] offset:1536 sc1
; DI unsigned pk2(float lo, float hi) { return f2bf(lo) | (f2bf(hi) << 16); }
; DI void norm_phase(const Args& A, int wave_s, int l, int which, int rows) {
;     ...
;             const int m = m0 + rr; const float* xr; int v;
;             if (m < NLAT) { xr = (from_in ? C.x : C.out) + (size_t)m * 1024; v = m >> 13; }
;             else { xr = (from_in ? C.ctx : C.XC) + (size_t)(m - NLAT) * 1024; v = 4; }
;             modp[rr] = C.SM + SM_MOD + (l * 5 + v) * 6144 + (which == 1 ? 0 : 3072);
; #pragma unroll
;             for (int j = 0; j < 4; ++j) xv[rr][j] = ((const f32x4*)xr)[C.lane + 64 * j];
;         }
; #pragma unroll
;         for (int rr = 0; rr < 2; ++rr) {
;             const int m = m0 + rr;
;             f32x4 sh[4], sc[4];
; #pragma unroll
;             for (int j = 0; j < 4; ++j) { const int col = 4 * (C.lane + 64 * j); sh[j] = *(const f32x4*)(modp[rr] + col); sc[j] = *(const f32x4*)(modp[rr] + 1024 + col); }
;     ...
;             for (int j = 0; j < 4; ++j) { const int col = 4 * (C.lane + 64 * j);
;                 const f32x4 y = xv[rr][j] * rs * g[j] * (sc[j] + 1.f) + sh[j];
;                 v2u o; o.x = pk2(y.x, y.y); o.y = pk2(y.z, y.w);
;                 *(v2u*)(C.H + (size_t)m * 1024 + col) = o; }
	s_add_u32 s10, s10, 0x800
	s_addc_u32 s11, s11, 0
	v_pk_mul_f32 v[112:113], v[112:113], v[20:21] op_sel_hi:[1,0]
	v_pk_mul_f32 v[114:115], v[114:115], v[20:21] op_sel_hi:[1,0]
	v_pk_mul_f32 v[116:117], v[116:117], v[20:21] op_sel_hi:[1,0]
	v_pk_mul_f32 v[118:119], v[118:119], v[20:21] op_sel_hi:[1,0]
	v_pk_mul_f32 v[120:121], v[120:121], v[20:21] op_sel_hi:[1,0]
	v_pk_mul_f32 v[122:123], v[122:123], v[20:21] op_sel_hi:[1,0]
	v_pk_mul_f32 v[124:125], v[124:125], v[20:21] op_sel_hi:[1,0]
	v_pk_mul_f32 v[126:127], v[126:127], v[20:21] op_sel_hi:[1,0]
	v_pk_mul_f32 v[112:113], v[24:25], v[112:113]
	v_pk_mul_f32 v[114:115], v[26:27], v[114:115]
	v_pk_mul_f32 v[116:117], v[28:29], v[116:117]
	v_pk_mul_f32 v[118:119], v[30:31], v[118:119]
	v_pk_mul_f32 v[120:121], v[32:33], v[120:121]
	v_pk_mul_f32 v[122:123], v[34:35], v[122:123]
	v_pk_mul_f32 v[124:125], v[36:37], v[124:125]
	v_pk_mul_f32 v[126:127], v[38:39], v[126:127]
	v_pk_fma_f32 v[112:113], v[40:41], v[112:113], v[80:81]
	v_pk_fma_f32 v[114:115], v[42:43], v[114:115], v[82:83]
	v_pk_fma_f32 v[116:117], v[64:65], v[116:117], v[84:85]
	v_pk_fma_f32 v[118:119], v[66:67], v[118:119], v[86:87]
	v_pk_fma_f32 v[120:121], v[68:69], v[120:121], v[88:89]
	v_pk_fma_f32 v[122:123], v[70:71], v[122:123], v[90:91]
	v_pk_fma_f32 v[124:125], v[72:73], v[124:125], v[92:93]
	v_pk_fma_f32 v[126:127], v[74:75], v[126:127], v[94:95]
	v_cvt_pk_bf16_f32 v112, v112, v113
	v_cvt_pk_bf16_f32 v113, v114, v115
	v_cvt_pk_bf16_f32 v116, v116, v117
	v_cvt_pk_bf16_f32 v117, v118, v119
	v_cvt_pk_bf16_f32 v120, v120, v121
	v_cvt_pk_bf16_f32 v121, v122, v123
	v_cvt_pk_bf16_f32 v124, v124, v125
	v_cvt_pk_bf16_f32 v125, v126, v127
	global_store_dwordx2 v2, v[112:113], s[10:11] sc1
	global_store_dwordx2 v2, v[116:117], s[10:11] offset:512 sc1
	global_store_dwordx2 v2, v[120:121], s[10:11] offset:1024 sc1
	global_store_dwordx2 v2, v[124:125], s[10:11] offset:1536 sc1
	s_add_u32 s10, s10, 0x800
	s_addc_u32 s11, s11, 0
	v_pk_mul_f32 v[128:129], v[128:129], v[22:23] op_sel_hi:[1,0]
	v_pk_mul_f32 v[130:131], v[130:131], v[22:23] op_sel_hi:[1,0]
	v_pk_mul_f32 v[132:133], v[132:133], v[22:23] op_sel_hi:[1,0]
	v_pk_mul_f32 v[134:135], v[134:135], v[22:23] op_sel_hi:[1,0]
	v_pk_mul_f32 v[136:137], v[136:137], v[22:23] op_sel_hi:[1,0]
	v_pk_mul_f32 v[138:139], v[138:139], v[22:23] op_sel_hi:[1,0]
	v_pk_mul_f32 v[140:141], v[140:141], v[22:23] op_sel_hi:[1,0]
	v_pk_mul_f32 v[142:143], v[142:143], v[22:23] op_sel_hi:[1,0]
	v_pk_mul_f32 v[128:129], v[24:25], v[128:129]
	v_pk_mul_f32 v[130:131], v[26:27], v[130:131]
	v_pk_mul_f32 v[132:133], v[28:29], v[132:133]
	v_pk_mul_f32 v[134:135], v[30:31], v[134:135]
	v_pk_mul_f32 v[136:137], v[32:33], v[136:137]
	v_pk_mul_f32 v[138:139], v[34:35], v[138:139]
	v_pk_mul_f32 v[140:141], v[36:37], v[140:141]
	v_pk_mul_f32 v[142:143], v[38:39], v[142:143]
	v_pk_fma_f32 v[128:129], v[40:41], v[128:129], v[80:81]
	v_pk_fma_f32 v[130:131], v[42:43], v[130:131], v[82:83]
	v_pk_fma_f32 v[132:133], v[64:65], v[132:133], v[84:85]
	v_pk_fma_f32 v[134:135], v[66:67], v[134:135], v[86:87]
	v_pk_fma_f32 v[136:137], v[68:69], v[136:137], v[88:89]
	v_pk_fma_f32 v[138:139], v[70:71], v[138:139], v[90:91]
	v_pk_fma_f32 v[140:141], v[72:73], v[140:141], v[92:93]
	v_pk_fma_f32 v[142:143], v[74:75], v[142:143], v[94:95]
	v_cvt_pk_bf16_f32 v128, v128, v129
	v_cvt_pk_bf16_f32 v129, v130, v131
	v_cvt_pk_bf16_f32 v132, v132, v133
	v_cvt_pk_bf16_f32 v133, v134, v135
	v_cvt_pk_bf16_f32 v136, v136, v137
	v_cvt_pk_bf16_f32 v137, v138, v139
	v_cvt_pk_bf16_f32 v140, v140, v141
	v_cvt_pk_bf16_f32 v141, v142, v143
	global_store_dwordx2 v2, v[128:129], s[10:11] sc1
	global_store_dwordx2 v2, v[132:133], s[10:11] offset:512 sc1
	global_store_dwordx2 v2, v[136:137], s[10:11] offset:1024 sc1
	global_store_dwordx2 v2, v[140:141], s[10:11] offset:1536 sc1
	s_add_u32 s10, s10, 0x800
	s_addc_u32 s11, s11, 0
	v_pk_mul_f32 v[144:145], v[144:145], v[62:63] op_sel_hi:[1,0]
	v_pk_mul_f32 v[146:147], v[146:147], v[62:63] op_sel_hi:[1,0]
	v_pk_mul_f32 v[148:149], v[148:149], v[62:63] op_sel_hi:[1,0]
	v_pk_mul_f32 v[150:151], v[150:151], v[62:63] op_sel_hi:[1,0]
	v_pk_mul_f32 v[152:153], v[152:153], v[62:63] op_sel_hi:[1,0]
	v_pk_mul_f32 v[154:155], v[154:155], v[62:63] op_sel_hi:[1,0]
	v_pk_mul_f32 v[156:157], v[156:157], v[62:63] op_sel_hi:[1,0]
	v_pk_mul_f32 v[158:159], v[158:159], v[62:63] op_sel_hi:[1,0]
	v_pk_mul_f32 v[144:145], v[24:25], v[144:145]
	v_pk_mul_f32 v[146:147], v[26:27], v[146:147]
	v_pk_mul_f32 v[148:149], v[28:29], v[148:149]
	v_pk_mul_f32 v[150:151], v[30:31], v[150:151]
	v_pk_mul_f32 v[152:153], v[32:33], v[152:153]
	v_pk_mul_f32 v[154:155], v[34:35], v[154:155]
	v_pk_mul_f32 v[156:157], v[36:37], v[156:157]
	v_pk_mul_f32 v[158:159], v[38:39], v[158:159]
	v_pk_fma_f32 v[144:145], v[40:41], v[144:145], v[80:81]
	v_pk_fma_f32 v[146:147], v[42:43], v[146:147], v[82:83]
	v_pk_fma_f32 v[148:149], v[64:65], v[148:149], v[84:85]
	v_pk_fma_f32 v[150:151], v[66:67], v[150:151], v[86:87]
	v_pk_fma_f32 v[152:153], v[68:69], v[152:153], v[88:89]
	v_pk_fma_f32 v[154:155], v[70:71], v[154:155], v[90:91]
	v_pk_fma_f32 v[156:157], v[72:73], v[156:157], v[92:93]
	v_pk_fma_f32 v[158:159], v[74:75], v[158:159], v[94:95]
	v_cvt_pk_bf16_f32 v144, v144, v145
	v_cvt_pk_bf16_f32 v145, v146, v147
	v_cvt_pk_bf16_f32 v148, v148, v149
	v_cvt_pk_bf16_f32 v149, v150, v151
	v_cvt_pk_bf16_f32 v152, v152, v153
	v_cvt_pk_bf16_f32 v153, v154, v155
	v_cvt_pk_bf16_f32 v156, v156, v157
	v_cvt_pk_bf16_f32 v157, v158, v159
	global_store_dwordx2 v2, v[144:145], s[10:11] sc1
	global_store_dwordx2 v2, v[148:149], s[10:11] offset:512 sc1
	global_store_dwordx2 v2, v[152:153], s[10:11] offset:1024 sc1
	global_store_dwordx2 v2, v[156:157], s[10:11] offset:1536 sc1
	s_add_u32 s10, s10, 0x800
	s_addc_u32 s11, s11, 0
	s_mul_i32 s5, s6, 5
	s_add_u32 s5, s5, 4
	s_mul_i32 s5, s5, 0x6000
	s_add_u32 s24, s88, 0x100000
	s_addc_u32 s25, s89, 0
	s_add_u32 s24, s24, s5
	s_addc_u32 s25, s25, 0
	s_add_u32 s26, s24, 0x1000
	s_addc_u32 s27, s25, 0
	global_load_dwordx4 v[96:99], v1, s[30:31]
	global_load_dwordx4 v[100:103], v1, s[30:31] offset:1024
	global_load_dwordx4 v[104:107], v1, s[30:31] offset:2048
	global_load_dwordx4 v[108:111], v1, s[30:31] offset:3072
	global_load_dwordx4 v[112:115], v1, s[26:27]
	global_load_dwordx4 v[116:119], v1, s[26:27] offset:1024
	global_load_dwordx4 v[120:123], v1, s[26:27] offset:2048
	global_load_dwordx4 v[124:127], v1, s[26:27] offset:3072
	global_load_dwordx4 v[128:131], v1, s[24:25]
	global_load_dwordx4 v[132:135], v1, s[24:25] offset:1024
	global_load_dwordx4 v[136:139], v1, s[24:25] offset:2048
	global_load_dwordx4 v[140:143], v1, s[24:25] offset:3072
	s_waitcnt vmcnt(28)
; DI unsigned pk2(float lo, float hi) { return f2bf(lo) | (f2bf(hi) << 16); }
; DI void norm_phase(const Args& A, int wave_s, int l, int which, int rows) {
;     ...
; #pragma unroll
;         for (int rr = 0; rr < 2; ++rr) {
;             const int m = m0 + rr;
;             f32x4 sh[4], sc[4];
; #pragma unroll
;             for (int j = 0; j < 4; ++j) { const int col = 4 * (C.lane + 64 * j); sh[j] = *(const f32x4*)(modp[rr] + col); sc[j] = *(const f32x4*)(modp[rr] + 1024 + col); }
;             float ss = 0.f;
; #pragma unroll
;             for (int j = 0; j < 4; ++j) ss += (xv[rr][j].x * xv[rr][j].x + xv[rr][j].y * xv[rr][j].y) + (xv[rr][j].z * xv[rr][j].z + xv[rr][j].w * xv[rr][j].w);
;             ss = wave_sum(C.lane, ss);
;             const float rs = rsqrtf(ss * (1.f / 1024.f) + EPS);
; #pragma unroll
;             for (int j = 0; j < 4; ++j) { const int col = 4 * (C.lane + 64 * j);
;                 const f32x4 y = xv[rr][j] * rs * g[j] * (sc[j] + 1.f) + sh[j];
;                 v2u o; o.x = pk2(y.x, y.y); o.y = pk2(y.z, y.w);
;                 *(v2u*)(C.H + (size_t)m * 1024 + col) = o; }
;         }
	v_mul_f32_e32 v10, v164, v164
	v_fmac_f32_e32 v10, v165, v165
	v_fmac_f32_e32 v10, v166, v166
	v_fmac_f32_e32 v10, v167, v167
	v_fmac_f32_e32 v10, v168, v168
	v_fmac_f32_e32 v10, v169, v169
	v_fmac_f32_e32 v10, v170, v170
	v_fmac_f32_e32 v10, v171, v171
	v_fmac_f32_e32 v10, v172, v172
	v_fmac_f32_e32 v10, v173, v173
	v_fmac_f32_e32 v10, v174, v174
	v_fmac_f32_e32 v10, v175, v175
	v_fmac_f32_e32 v10, v176, v176
	v_fmac_f32_e32 v10, v177, v177
	v_fmac_f32_e32 v10, v178, v178
	v_fmac_f32_e32 v10, v179, v179
	v_mul_f32_e32 v11, v180, v180
	v_fmac_f32_e32 v11, v181, v181
	v_fmac_f32_e32 v11, v182, v182
	v_fmac_f32_e32 v11, v183, v183
	v_fmac_f32_e32 v11, v184, v184
	v_fmac_f32_e32 v11, v185, v185
	v_fmac_f32_e32 v11, v186, v186
	v_fmac_f32_e32 v11, v187, v187
	v_fmac_f32_e32 v11, v188, v188
	v_fmac_f32_e32 v11, v189, v189
	v_fmac_f32_e32 v11, v190, v190
	v_fmac_f32_e32 v11, v191, v191
	v_fmac_f32_e32 v11, v192, v192
	v_fmac_f32_e32 v11, v193, v193
	v_fmac_f32_e32 v11, v194, v194
	v_fmac_f32_e32 v11, v195, v195
	v_mul_f32_e32 v12, v196, v196
	v_fmac_f32_e32 v12, v197, v197
	v_fmac_f32_e32 v12, v198, v198
	v_fmac_f32_e32 v12, v199, v199
	v_fmac_f32_e32 v12, v200, v200
	v_fmac_f32_e32 v12, v201, v201
	v_fmac_f32_e32 v12, v202, v202
	v_fmac_f32_e32 v12, v203, v203
	v_fmac_f32_e32 v12, v204, v204
	v_fmac_f32_e32 v12, v205, v205
	v_fmac_f32_e32 v12, v206, v206
	v_fmac_f32_e32 v12, v207, v207
	v_fmac_f32_e32 v12, v208, v208
	v_fmac_f32_e32 v12, v209, v209
	v_fmac_f32_e32 v12, v210, v210
	v_fmac_f32_e32 v12, v211, v211
	v_mul_f32_e32 v13, v212, v212
	v_fmac_f32_e32 v13, v213, v213
	v_fmac_f32_e32 v13, v214, v214
	v_fmac_f32_e32 v13, v215, v215
	v_fmac_f32_e32 v13, v216, v216
	v_fmac_f32_e32 v13, v217, v217
	v_fmac_f32_e32 v13, v218, v218
	v_fmac_f32_e32 v13, v219, v219
	v_fmac_f32_e32 v13, v220, v220
	v_fmac_f32_e32 v13, v221, v221
	v_fmac_f32_e32 v13, v222, v222
	v_fmac_f32_e32 v13, v223, v223
	v_fmac_f32_e32 v13, v224, v224
	v_fmac_f32_e32 v13, v225, v225
	v_fmac_f32_e32 v13, v226, v226
	v_fmac_f32_e32 v13, v227, v227
	ds_bpermute_b32 v14, v4, v10
	ds_bpermute_b32 v15, v4, v11
	ds_bpermute_b32 v16, v4, v12
	ds_bpermute_b32 v17, v4, v13
	s_waitcnt lgkmcnt(0)
	v_add_f32_e32 v10, v10, v14
	v_add_f32_e32 v11, v11, v15
	v_add_f32_e32 v12, v12, v16
	v_add_f32_e32 v13, v13, v17
	ds_bpermute_b32 v14, v5, v10
	ds_bpermute_b32 v15, v5, v11
	ds_bpermute_b32 v16, v5, v12
	ds_bpermute_b32 v17, v5, v13
	s_waitcnt lgkmcnt(0)
	v_add_f32_e32 v10, v10, v14
	v_add_f32_e32 v11, v11, v15
	v_add_f32_e32 v12, v12, v16
	v_add_f32_e32 v13, v13, v17
	ds_bpermute_b32 v14, v6, v10
	ds_bpermute_b32 v15, v6, v11
	ds_bpermute_b32 v16, v6, v12
	ds_bpermute_b32 v17, v6, v13
	s_waitcnt lgkmcnt(0)
	v_add_f32_e32 v10, v10, v14
	v_add_f32_e32 v11, v11, v15
	v_add_f32_e32 v12, v12, v16
	v_add_f32_e32 v13, v13, v17
	ds_bpermute_b32 v14, v7, v10
	ds_bpermute_b32 v15, v7, v11
	ds_bpermute_b32 v16, v7, v12
	ds_bpermute_b32 v17, v7, v13
	s_waitcnt lgkmcnt(0)
	v_add_f32_e32 v10, v10, v14
	v_add_f32_e32 v11, v11, v15
	v_add_f32_e32 v12, v12, v16
	v_add_f32_e32 v13, v13, v17
	ds_bpermute_b32 v14, v8, v10
	ds_bpermute_b32 v15, v8, v11
	ds_bpermute_b32 v16, v8, v12
	ds_bpermute_b32 v17, v8, v13
	s_waitcnt lgkmcnt(0)
	v_add_f32_e32 v10, v10, v14
	v_add_f32_e32 v11, v11, v15
	v_add_f32_e32 v12, v12, v16
	v_add_f32_e32 v13, v13, v17
	ds_bpermute_b32 v14, v9, v10
	ds_bpermute_b32 v15, v9, v11
	ds_bpermute_b32 v16, v9, v12
	ds_bpermute_b32 v17, v9, v13
	s_waitcnt lgkmcnt(0)
	v_add_f32_e32 v10, v10, v14
	v_add_f32_e32 v11, v11, v15
	v_add_f32_e32 v12, v12, v16
	v_add_f32_e32 v13, v13, v17
	v_fma_f32 v10, v10, s32, v60
	v_fma_f32 v11, v11, s32, v60
	v_fma_f32 v12, v12, s32, v60
	v_fma_f32 v13, v13, s32, v60
	v_rsq_f32_e32 v18, v10
	v_rsq_f32_e32 v20, v11
	v_rsq_f32_e32 v22, v12
	v_rsq_f32_e32 v62, v13
	s_nop 0
	v_pk_mul_f32 v[164:165], v[164:165], v[18:19] op_sel_hi:[1,0]
	v_pk_mul_f32 v[166:167], v[166:167], v[18:19] op_sel_hi:[1,0]
	v_pk_mul_f32 v[168:169], v[168:169], v[18:19] op_sel_hi:[1,0]
	v_pk_mul_f32 v[170:171], v[170:171], v[18:19] op_sel_hi:[1,0]
	v_pk_mul_f32 v[172:173], v[172:173], v[18:19] op_sel_hi:[1,0]
	v_pk_mul_f32 v[174:175], v[174:175], v[18:19] op_sel_hi:[1,0]
	v_pk_mul_f32 v[176:177], v[176:177], v[18:19] op_sel_hi:[1,0]
	v_pk_mul_f32 v[178:179], v[178:179], v[18:19] op_sel_hi:[1,0]
	v_pk_mul_f32 v[164:165], v[24:25], v[164:165]
	v_pk_mul_f32 v[166:167], v[26:27], v[166:167]
	v_pk_mul_f32 v[168:169], v[28:29], v[168:169]
	v_pk_mul_f32 v[170:171], v[30:31], v[170:171]
	v_pk_mul_f32 v[172:173], v[32:33], v[172:173]
	v_pk_mul_f32 v[174:175], v[34:35], v[174:175]
	v_pk_mul_f32 v[176:177], v[36:37], v[176:177]
	v_pk_mul_f32 v[178:179], v[38:39], v[178:179]
	v_pk_fma_f32 v[164:165], v[40:41], v[164:165], v[80:81]
	v_pk_fma_f32 v[166:167], v[42:43], v[166:167], v[82:83]
	v_pk_fma_f32 v[168:169], v[64:65], v[168:169], v[84:85]
	v_pk_fma_f32 v[170:171], v[66:67], v[170:171], v[86:87]
	v_pk_fma_f32 v[172:173], v[68:69], v[172:173], v[88:89]
	v_pk_fma_f32 v[174:175], v[70:71], v[174:175], v[90:91]
	v_pk_fma_f32 v[176:177], v[72:73], v[176:177], v[92:93]
	v_pk_fma_f32 v[178:179], v[74:75], v[178:179], v[94:95]
	v_cvt_pk_bf16_f32 v164, v164, v165
	v_cvt_pk_bf16_f32 v165, v166, v167
	v_cvt_pk_bf16_f32 v168, v168, v169
	v_cvt_pk_bf16_f32 v169, v170, v171
	v_cvt_pk_bf16_f32 v172, v172, v173
	v_cvt_pk_bf16_f32 v173, v174, v175
	v_cvt_pk_bf16_f32 v176, v176, v177
	v_cvt_pk_bf16_f32 v177, v178, v179
	global_store_dwordx2 v2, v[164:165], s[10:11] sc1
	global_store_dwordx2 v2, v[168:169], s[10:11] offset:512 sc1
	global_store_dwordx2 v2, v[172:173], s[10:11] offset:1024 sc1
; DI unsigned pk2(float lo, float hi) { return f2bf(lo) | (f2bf(hi) << 16); }
; DI void norm_phase(const Args& A, int wave_s, int l, int which, int rows) {
;     ...
; #pragma unroll
;             for (int j = 0; j < 4; ++j) { const int col = 4 * (C.lane + 64 * j);
;                 const f32x4 y = xv[rr][j] * rs * g[j] * (sc[j] + 1.f) + sh[j];
;                 v2u o; o.x = pk2(y.x, y.y); o.y = pk2(y.z, y.w);
;                 *(v2u*)(C.H + (size_t)m * 1024 + col) = o; }
	global_store_dwordx2 v2, v[176:177], s[10:11] offset:1536 sc1
	s_add_u32 s10, s10, 0x800
	s_addc_u32 s11, s11, 0
	v_pk_mul_f32 v[180:181], v[180:181], v[20:21] op_sel_hi:[1,0]
	v_pk_mul_f32 v[182:183], v[182:183], v[20:21] op_sel_hi:[1,0]
	v_pk_mul_f32 v[184:185], v[184:185], v[20:21] op_sel_hi:[1,0]
	v_pk_mul_f32 v[186:187], v[186:187], v[20:21] op_sel_hi:[1,0]
	v_pk_mul_f32 v[188:189], v[188:189], v[20:21] op_sel_hi:[1,0]
	v_pk_mul_f32 v[190:191], v[190:191], v[20:21] op_sel_hi:[1,0]
	v_pk_mul_f32 v[192:193], v[192:193], v[20:21] op_sel_hi:[1,0]
	v_pk_mul_f32 v[194:195], v[194:195], v[20:21] op_sel_hi:[1,0]
	v_pk_mul_f32 v[180:181], v[24:25], v[180:181]
	v_pk_mul_f32 v[182:183], v[26:27], v[182:183]
	v_pk_mul_f32 v[184:185], v[28:29], v[184:185]
	v_pk_mul_f32 v[186:187], v[30:31], v[186:187]
	v_pk_mul_f32 v[188:189], v[32:33], v[188:189]
	v_pk_mul_f32 v[190:191], v[34:35], v[190:191]
	v_pk_mul_f32 v[192:193], v[36:37], v[192:193]
	v_pk_mul_f32 v[194:195], v[38:39], v[194:195]
	v_pk_fma_f32 v[180:181], v[40:41], v[180:181], v[80:81]
	v_pk_fma_f32 v[182:183], v[42:43], v[182:183], v[82:83]
	v_pk_fma_f32 v[184:185], v[64:65], v[184:185], v[84:85]
	v_pk_fma_f32 v[186:187], v[66:67], v[186:187], v[86:87]
	v_pk_fma_f32 v[188:189], v[68:69], v[188:189], v[88:89]
	v_pk_fma_f32 v[190:191], v[70:71], v[190:191], v[90:91]
	v_pk_fma_f32 v[192:193], v[72:73], v[192:193], v[92:93]
	v_pk_fma_f32 v[194:195], v[74:75], v[194:195], v[94:95]
	v_cvt_pk_bf16_f32 v180, v180, v181
	v_cvt_pk_bf16_f32 v181, v182, v183
	v_cvt_pk_bf16_f32 v184, v184, v185
	v_cvt_pk_bf16_f32 v185, v186, v187
	v_cvt_pk_bf16_f32 v188, v188, v189
	v_cvt_pk_bf16_f32 v189, v190, v191
	v_cvt_pk_bf16_f32 v192, v192, v193
	v_cvt_pk_bf16_f32 v193, v194, v195
	global_store_dwordx2 v2, v[180:181], s[10:11] sc1
	global_store_dwordx2 v2, v[184:185], s[10:11] offset:512 sc1
	global_store_dwordx2 v2, v[188:189], s[10:11] offset:1024 sc1
	global_store_dwordx2 v2, v[192:193], s[10:11] offset:1536 sc1
	s_add_u32 s10, s10, 0x800
	s_addc_u32 s11, s11, 0
	v_pk_mul_f32 v[196:197], v[196:197], v[22:23] op_sel_hi:[1,0]
	v_pk_mul_f32 v[198:199], v[198:199], v[22:23] op_sel_hi:[1,0]
	v_pk_mul_f32 v[200:201], v[200:201], v[22:23] op_sel_hi:[1,0]
	v_pk_mul_f32 v[202:203], v[202:203], v[22:23] op_sel_hi:[1,0]
	v_pk_mul_f32 v[204:205], v[204:205], v[22:23] op_sel_hi:[1,0]
	v_pk_mul_f32 v[206:207], v[206:207], v[22:23] op_sel_hi:[1,0]
	v_pk_mul_f32 v[208:209], v[208:209], v[22:23] op_sel_hi:[1,0]
	v_pk_mul_f32 v[210:211], v[210:211], v[22:23] op_sel_hi:[1,0]
	v_pk_mul_f32 v[196:197], v[24:25], v[196:197]
	v_pk_mul_f32 v[198:199], v[26:27], v[198:199]
	v_pk_mul_f32 v[200:201], v[28:29], v[200:201]
	v_pk_mul_f32 v[202:203], v[30:31], v[202:203]
	v_pk_mul_f32 v[204:205], v[32:33], v[204:205]
	v_pk_mul_f32 v[206:207], v[34:35], v[206:207]
	v_pk_mul_f32 v[208:209], v[36:37], v[208:209]
	v_pk_mul_f32 v[210:211], v[38:39], v[210:211]
	v_pk_fma_f32 v[196:197], v[40:41], v[196:197], v[80:81]
	v_pk_fma_f32 v[198:199], v[42:43], v[198:199], v[82:83]
	v_pk_fma_f32 v[200:201], v[64:65], v[200:201], v[84:85]
	v_pk_fma_f32 v[202:203], v[66:67], v[202:203], v[86:87]
	v_pk_fma_f32 v[204:205], v[68:69], v[204:205], v[88:89]
	v_pk_fma_f32 v[206:207], v[70:71], v[206:207], v[90:91]
	v_pk_fma_f32 v[208:209], v[72:73], v[208:209], v[92:93]
	v_pk_fma_f32 v[210:211], v[74:75], v[210:211], v[94:95]
	v_cvt_pk_bf16_f32 v196, v196, v197
	v_cvt_pk_bf16_f32 v197, v198, v199
	v_cvt_pk_bf16_f32 v200, v200, v201
	v_cvt_pk_bf16_f32 v201, v202, v203
	v_cvt_pk_bf16_f32 v204, v204, v205
	v_cvt_pk_bf16_f32 v205, v206, v207
	v_cvt_pk_bf16_f32 v208, v208, v209
	v_cvt_pk_bf16_f32 v209, v210, v211
	global_store_dwordx2 v2, v[196:197], s[10:11] sc1
	global_store_dwordx2 v2, v[200:201], s[10:11] offset:512 sc1
	global_store_dwordx2 v2, v[204:205], s[10:11] offset:1024 sc1
	global_store_dwordx2 v2, v[208:209], s[10:11] offset:1536 sc1
	s_add_u32 s10, s10, 0x800
	s_addc_u32 s11, s11, 0
	v_pk_mul_f32 v[212:213], v[212:213], v[62:63] op_sel_hi:[1,0]
	v_pk_mul_f32 v[214:215], v[214:215], v[62:63] op_sel_hi:[1,0]
	v_pk_mul_f32 v[216:217], v[216:217], v[62:63] op_sel_hi:[1,0]
	v_pk_mul_f32 v[218:219], v[218:219], v[62:63] op_sel_hi:[1,0]
	v_pk_mul_f32 v[220:221], v[220:221], v[62:63] op_sel_hi:[1,0]
	v_pk_mul_f32 v[222:223], v[222:223], v[62:63] op_sel_hi:[1,0]
	v_pk_mul_f32 v[224:225], v[224:225], v[62:63] op_sel_hi:[1,0]
	v_pk_mul_f32 v[226:227], v[226:227], v[62:63] op_sel_hi:[1,0]
	v_pk_mul_f32 v[212:213], v[24:25], v[212:213]
	v_pk_mul_f32 v[214:215], v[26:27], v[214:215]
	v_pk_mul_f32 v[216:217], v[28:29], v[216:217]
	v_pk_mul_f32 v[218:219], v[30:31], v[218:219]
	v_pk_mul_f32 v[220:221], v[32:33], v[220:221]
	v_pk_mul_f32 v[222:223], v[34:35], v[222:223]
	v_pk_mul_f32 v[224:225], v[36:37], v[224:225]
	v_pk_mul_f32 v[226:227], v[38:39], v[226:227]
	v_pk_fma_f32 v[212:213], v[40:41], v[212:213], v[80:81]
	v_pk_fma_f32 v[214:215], v[42:43], v[214:215], v[82:83]
	v_pk_fma_f32 v[216:217], v[64:65], v[216:217], v[84:85]
	v_pk_fma_f32 v[218:219], v[66:67], v[218:219], v[86:87]
	v_pk_fma_f32 v[220:221], v[68:69], v[220:221], v[88:89]
	v_pk_fma_f32 v[222:223], v[70:71], v[222:223], v[90:91]
	v_pk_fma_f32 v[224:225], v[72:73], v[224:225], v[92:93]
	v_pk_fma_f32 v[226:227], v[74:75], v[226:227], v[94:95]
	v_cvt_pk_bf16_f32 v212, v212, v213
	v_cvt_pk_bf16_f32 v213, v214, v215
	v_cvt_pk_bf16_f32 v216, v216, v217
	v_cvt_pk_bf16_f32 v217, v218, v219
	v_cvt_pk_bf16_f32 v220, v220, v221
	v_cvt_pk_bf16_f32 v221, v222, v223
	v_cvt_pk_bf16_f32 v224, v224, v225
	v_cvt_pk_bf16_f32 v225, v226, v227
	global_store_dwordx2 v2, v[212:213], s[10:11] sc1
	global_store_dwordx2 v2, v[216:217], s[10:11] offset:512 sc1
	global_store_dwordx2 v2, v[220:221], s[10:11] offset:1024 sc1
	global_store_dwordx2 v2, v[224:225], s[10:11] offset:1536 sc1
	s_add_u32 s10, s10, 0x800
	s_addc_u32 s11, s11, 0
	s_add_u32 s10, s88, 0x3800000
	s_addc_u32 s11, s89, 0
	s_add_u32 s10, s10, 0x4000000
	s_addc_u32 s11, s11, 0
	s_lshl_b32 s5, s7, 11
	s_add_u32 s10, s10, s5
	s_addc_u32 s11, s11, 0
	s_waitcnt vmcnt(16)
	v_pk_add_f32 v[112:113], v[112:113], 1.0 op_sel_hi:[1,0]
	v_pk_add_f32 v[114:115], v[114:115], 1.0 op_sel_hi:[1,0]
	v_pk_add_f32 v[116:117], v[116:117], 1.0 op_sel_hi:[1,0]
	v_pk_add_f32 v[118:119], v[118:119], 1.0 op_sel_hi:[1,0]
	v_pk_add_f32 v[120:121], v[120:121], 1.0 op_sel_hi:[1,0]
	v_pk_add_f32 v[122:123], v[122:123], 1.0 op_sel_hi:[1,0]
	v_pk_add_f32 v[124:125], v[124:125], 1.0 op_sel_hi:[1,0]
	v_pk_add_f32 v[126:127], v[126:127], 1.0 op_sel_hi:[1,0]
	s_cmp_eq_u32 s2, 0
	s_cbranch_scc1 .Lnorm_n1_done
; DI unsigned pk2(float lo, float hi) { return f2bf(lo) | (f2bf(hi) << 16); }
; DI void norm_phase(const Args& A, int wave_s, int l, int which, int rows) {
;     ...
;             float ss = 0.f;
; #pragma unroll
;             for (int j = 0; j < 4; ++j) ss += (xv[rr][j].x * xv[rr][j].x + xv[rr][j].y * xv[rr][j].y) + (xv[rr][j].z * xv[rr][j].z + xv[rr][j].w * xv[rr][j].w);
;             ss = wave_sum(C.lane, ss);
;             const float rs = rsqrtf(ss * (1.f / 1024.f) + EPS);
; #pragma unroll
;             for (int j = 0; j < 4; ++j) { const int col = 4 * (C.lane + 64 * j);
;                 const f32x4 y = xv[rr][j] * rs * g[j] * (sc[j] + 1.f) + sh[j];
;                 v2u o; o.x = pk2(y.x, y.y); o.y = pk2(y.z, y.w);
;                 *(v2u*)(C.H + (size_t)m * 1024 + col) = o; }
	v_mul_f32_e32 v10, v96, v96
	v_fmac_f32_e32 v10, v97, v97
	v_fmac_f32_e32 v10, v98, v98
	v_fmac_f32_e32 v10, v99, v99
	v_fmac_f32_e32 v10, v100, v100
	v_fmac_f32_e32 v10, v101, v101
	v_fmac_f32_e32 v10, v102, v102
	v_fmac_f32_e32 v10, v103, v103
	v_fmac_f32_e32 v10, v104, v104
	v_fmac_f32_e32 v10, v105, v105
	v_fmac_f32_e32 v10, v106, v106
	v_fmac_f32_e32 v10, v107, v107
	v_fmac_f32_e32 v10, v108, v108
	v_fmac_f32_e32 v10, v109, v109
	v_fmac_f32_e32 v10, v110, v110
	v_fmac_f32_e32 v10, v111, v111
	ds_bpermute_b32 v14, v4, v10
	s_waitcnt lgkmcnt(0)
	v_add_f32_e32 v10, v10, v14
	ds_bpermute_b32 v14, v5, v10
	s_waitcnt lgkmcnt(0)
	v_add_f32_e32 v10, v10, v14
	ds_bpermute_b32 v14, v6, v10
	s_waitcnt lgkmcnt(0)
	v_add_f32_e32 v10, v10, v14
	ds_bpermute_b32 v14, v7, v10
	s_waitcnt lgkmcnt(0)
	v_add_f32_e32 v10, v10, v14
	ds_bpermute_b32 v14, v8, v10
	s_waitcnt lgkmcnt(0)
	v_add_f32_e32 v10, v10, v14
	ds_bpermute_b32 v14, v9, v10
	s_waitcnt lgkmcnt(0)
	v_add_f32_e32 v10, v10, v14
	v_fma_f32 v10, v10, s32, v60
	v_rsq_f32_e32 v18, v10
	s_nop 0
	v_pk_mul_f32 v[96:97], v[96:97], v[18:19] op_sel_hi:[1,0]
	v_pk_mul_f32 v[98:99], v[98:99], v[18:19] op_sel_hi:[1,0]
	v_pk_mul_f32 v[100:101], v[100:101], v[18:19] op_sel_hi:[1,0]
	v_pk_mul_f32 v[102:103], v[102:103], v[18:19] op_sel_hi:[1,0]
	v_pk_mul_f32 v[104:105], v[104:105], v[18:19] op_sel_hi:[1,0]
	v_pk_mul_f32 v[106:107], v[106:107], v[18:19] op_sel_hi:[1,0]
	v_pk_mul_f32 v[108:109], v[108:109], v[18:19] op_sel_hi:[1,0]
	v_pk_mul_f32 v[110:111], v[110:111], v[18:19] op_sel_hi:[1,0]
	v_pk_mul_f32 v[96:97], v[24:25], v[96:97]
	v_pk_mul_f32 v[98:99], v[26:27], v[98:99]
	v_pk_mul_f32 v[100:101], v[28:29], v[100:101]
	v_pk_mul_f32 v[102:103], v[30:31], v[102:103]
	v_pk_mul_f32 v[104:105], v[32:33], v[104:105]
	v_pk_mul_f32 v[106:107], v[34:35], v[106:107]
	v_pk_mul_f32 v[108:109], v[36:37], v[108:109]
	v_pk_mul_f32 v[110:111], v[38:39], v[110:111]
	v_pk_fma_f32 v[96:97], v[112:113], v[96:97], v[128:129]
	v_pk_fma_f32 v[98:99], v[114:115], v[98:99], v[130:131]
	v_pk_fma_f32 v[100:101], v[116:117], v[100:101], v[132:133]
	v_pk_fma_f32 v[102:103], v[118:119], v[102:103], v[134:135]
	v_pk_fma_f32 v[104:105], v[120:121], v[104:105], v[136:137]
	v_pk_fma_f32 v[106:107], v[122:123], v[106:107], v[138:139]
	v_pk_fma_f32 v[108:109], v[124:125], v[108:109], v[140:141]
	v_pk_fma_f32 v[110:111], v[126:127], v[110:111], v[142:143]
	v_cvt_pk_bf16_f32 v96, v96, v97
	v_cvt_pk_bf16_f32 v97, v98, v99
	v_cvt_pk_bf16_f32 v100, v100, v101
	v_cvt_pk_bf16_f32 v101, v102, v103
	v_cvt_pk_bf16_f32 v104, v104, v105
	v_cvt_pk_bf16_f32 v105, v106, v107
	v_cvt_pk_bf16_f32 v108, v108, v109
	v_cvt_pk_bf16_f32 v109, v110, v111
	global_store_dwordx2 v2, v[96:97], s[10:11] sc1
	global_store_dwordx2 v2, v[100:101], s[10:11] offset:512 sc1
	global_store_dwordx2 v2, v[104:105], s[10:11] offset:1024 sc1
	global_store_dwordx2 v2, v[108:109], s[10:11] offset:1536 sc1

; __device__ __forceinline__ unsigned xb_ld(unsigned* p)              { return __hip_atomic_load(p, __ATOMIC_RELAXED, __HIP_MEMORY_SCOPE_AGENT); }
; __device__ __forceinline__ unsigned xb_add(unsigned* p, unsigned v) { return __hip_atomic_fetch_add(p, v, __ATOMIC_RELAXED, __HIP_MEMORY_SCOPE_AGENT); }
; #define XB_SPIN(cond, bar) do { unsigned _sp = 0; while (cond) { __builtin_amdgcn_s_sleep(1); \
;     if ((++_sp & 255u) == 0u) { if (xb_ld(&(bar)[XB_TMO])) break; if (_sp > XB_SPIN_CAP) { atomicAdd(&(bar)[XB_TMO], 1u); break; } } } } while (0)
; __device__ __forceinline__ void xcd_barrier(const XcdBarrier& b, int xtid) {
;     ...
;     if (xtid == 0) {
;         unsigned* bar = b.bar; unsigned bx_ = b.x; asm volatile("" : "+s"(bx_));
;         __builtin_amdgcn_s_waitcnt(0);
;         unsigned nloc = b.st[0], nx = b.st[1];
;         if (nloc == 0u) { xcd_barrier_complete(bar, bx_, nloc, nx); b.st[0] = nloc; b.st[1] = nx; }
;         const unsigned old = xb_add(&bar[XB_XSUB(bx_)], 1u);
;         const unsigned gen = old / nloc;
;         if (old + 1u == (gen + 1u) * nloc) {
;             __builtin_amdgcn_fence(__ATOMIC_RELEASE, "agent");
;             asm volatile("s_waitcnt vmcnt(0)" ::: "memory");
;             const unsigned og = xb_add(&bar[XB_TOP], 1u);
;             const unsigned tg = og / nx;
;             if (og + 1u == (tg + 1u) * nx) xb_add(&bar[XB_TOPGEN], 1u);
;             else XB_SPIN(xb_ld(&bar[XB_TOPGEN]) == tg, bar);
;             __builtin_amdgcn_fence(__ATOMIC_ACQUIRE, "agent");
;             xb_add(&bar[XB_XGEN(bx_)], 1u);
;             asm volatile("s_waitcnt vmcnt(0)" ::: "memory");
.LBB0_93:
	s_andn2_saveexec_b64 s[6:7], s[6:7]
	s_cbranch_execz .LBB0_113
	s_mov_b64 s[6:7], exec
	s_nop 0
	s_waitcnt lgkmcnt(0)
	s_waitcnt vmcnt(0)
	v_mbcnt_lo_u32_b32 v1, s6, 0
	v_mbcnt_hi_u32_b32 v1, s7, v1
	v_cmp_eq_u32_e32 vcc, 0, v1
	s_and_saveexec_b64 s[8:9], vcc
	s_cbranch_execz .LBB0_96
	s_bcnt1_i32_b64 s6, s[6:7]
	v_mov_b32_e32 v2, s6
	v_readlane_b32 s6, v253, 8
	v_readlane_b32 s7, v253, 9
	s_nop 4
	global_atomic_add v2, v161, v2, s[6:7] sc0

; DI void norm_phase(const Args& A, int wave_s, int l, int which, int rows) {
;     const Ctx C = make_ctx(A, wave_s);
;     const float* gn = (which == 1 ? C.n1g : C.n2g) + l * 1024;
;     const bool from_in = (l == 0 && which == 1);
;     f32x4 g[4];
; #pragma unroll
;     for (int j = 0; j < 4; ++j) g[j] = *(const f32x4*)(gn + 4 * (C.lane + 64 * j));
;     for (int m0 = C.gw * 2; m0 < rows; m0 += C.NGW * 2) {
;         f32x4 xv[2][4];
;         const float* modp[2];
; #pragma unroll
;         for (int rr = 0; rr < 2; ++rr) {
;             const int m = m0 + rr; const float* xr; int v;
;             if (m < NLAT) { xr = (from_in ? C.x : C.out) + (size_t)m * 1024; v = m >> 13; }
;             else { xr = (from_in ? C.ctx : C.XC) + (size_t)(m - NLAT) * 1024; v = 4; }
;             modp[rr] = C.SM + SM_MOD + (l * 5 + v) * 6144 + (which == 1 ? 0 : 3072);
; #pragma unroll
;             for (int j = 0; j < 4; ++j) xv[rr][j] = ((const f32x4*)xr)[C.lane + 64 * j];
;         }
; #pragma unroll
;         for (int rr = 0; rr < 2; ++rr) {
;             const int m = m0 + rr;
;             f32x4 sh[4], sc[4];
; #pragma unroll
;             for (int j = 0; j < 4; ++j) { const int col = 4 * (C.lane + 64 * j); sh[j] = *(const f32x4*)(modp[rr] + col); sc[j] = *(const f32x4*)(modp[rr] + 1024 + col); }
.LBB0_528:
	s_or_b64 exec, exec, s[4:5]
	v_readlane_b32 s4, v254, 41
	s_cmp_ge_i32 s4, s42
	s_waitcnt lgkmcnt(0)
	s_barrier
	v_readlane_b32 s5, v254, 42
	v_mbcnt_lo_u32_b32 v48, -1, 0
	v_mbcnt_hi_u32_b32 v48, -1, v48
	v_mbcnt_lo_u32_b32 v0, -1, 0
	v_mbcnt_hi_u32_b32 v0, -1, v0
	v_readlane_b32 s6, v255, 32
	v_lshlrev_b32_e32 v1, 4, v0
	v_lshlrev_b32_e32 v2, 3, v0
	v_xor_b32_e32 v4, 1, v0
	v_xor_b32_e32 v5, 2, v0
	v_xor_b32_e32 v6, 4, v0
	v_xor_b32_e32 v7, 8, v0
	v_xor_b32_e32 v8, 16, v0
	v_xor_b32_e32 v9, 32, v0
	v_lshlrev_b32_e32 v4, 2, v4
	v_lshlrev_b32_e32 v5, 2, v5
	v_lshlrev_b32_e32 v6, 2, v6
	v_lshlrev_b32_e32 v7, 2, v7
	v_lshlrev_b32_e32 v8, 2, v8
	v_lshlrev_b32_e32 v9, 2, v9
	v_mov_b32_e32 v60, 0x358637bd
	s_lshr_b32 s6, s6, 10
	s_lshr_b32 s4, s94, 6
	s_lshl_b32 s5, s65, 3
	s_add_u32 s4, s4, s5
	s_lshr_b32 s5, s4, 9
	s_mul_i32 s7, s6, 5
	s_add_u32 s5, s7, s5
	s_mul_i32 s5, s5, 0x6000
	s_add_u32 s24, s88, 0x103000
	s_addc_u32 s25, s89, 0
	s_add_u32 s24, s24, s5
	s_addc_u32 s25, s25, 0
	s_add_u32 s26, s24, 0x1000
	s_addc_u32 s27, s25, 0
	v_readlane_b32 s28, v252, 48
	v_readlane_b32 s29, v252, 49
	s_lshl_b32 s7, s6, 12
	s_nop 1
	s_add_u32 s28, s28, s7
	s_addc_u32 s29, s29, 0
	v_readlane_b32 s8, v252, 31
	v_readlane_b32 s9, v252, 32
	s_add_u32 s30, s88, 0x3400000
	s_addc_u32 s31, s89, 0
	s_nop 1
	s_cmp_gt_u32 s42, 0x8000
	s_cselect_b32 s2, 1, 0
	s_cmp_lt_u32 s4, 0x400
	s_cselect_b32 s2, s2, 0
	s_and_b32 s7, s4, 0x3ff
	s_lshl_b32 s5, s7, 12
	s_add_u32 s30, s30, s5
	s_addc_u32 s31, s31, 0
	s_lshl_b32 s5, s4, 16
	s_add_u32 s8, s8, s5
	s_addc_u32 s9, s9, 0
	s_add_u32 s10, s88, 0x3800000
	s_addc_u32 s11, s89, 0
	s_lshl_b32 s5, s4, 15
	s_add_u32 s10, s10, s5
	s_addc_u32 s11, s11, 0
	s_mov_b32 s32, 0x3a800000
	global_load_dwordx4 v[24:27], v1, s[28:29]
	global_load_dwordx4 v[28:31], v1, s[28:29] offset:1024
	global_load_dwordx4 v[32:35], v1, s[28:29] offset:2048
	global_load_dwordx4 v[36:39], v1, s[28:29] offset:3072
	global_load_dwordx4 v[40:43], v1, s[26:27]
	global_load_dwordx4 v[64:67], v1, s[26:27] offset:1024
	global_load_dwordx4 v[68:71], v1, s[26:27] offset:2048
	global_load_dwordx4 v[72:75], v1, s[26:27] offset:3072
	global_load_dwordx4 v[80:83], v1, s[24:25]
	global_load_dwordx4 v[84:87], v1, s[24:25] offset:1024
	global_load_dwordx4 v[88:91], v1, s[24:25] offset:2048
	global_load_dwordx4 v[92:95], v1, s[24:25] offset:3072
	global_load_dwordx4 v[96:99], v1, s[8:9]
	global_load_dwordx4 v[100:103], v1, s[8:9] offset:1024
	global_load_dwordx4 v[104:107], v1, s[8:9] offset:2048
	global_load_dwordx4 v[108:111], v1, s[8:9] offset:3072
	s_add_u32 s8, s8, 0x1000
	s_addc_u32 s9, s9, 0
	global_load_dwordx4 v[112:115], v1, s[8:9]
	global_load_dwordx4 v[116:119], v1, s[8:9] offset:1024
	global_load_dwordx4 v[120:123], v1, s[8:9] offset:2048
	global_load_dwordx4 v[124:127], v1, s[8:9] offset:3072
	s_add_u32 s8, s8, 0x1000
	s_addc_u32 s9, s9, 0
	global_load_dwordx4 v[128:131], v1, s[8:9]
	global_load_dwordx4 v[132:135], v1, s[8:9] offset:1024
	global_load_dwordx4 v[136:139], v1, s[8:9] offset:2048
	global_load_dwordx4 v[140:143], v1, s[8:9] offset:3072
	s_add_u32 s8, s8, 0x1000
	s_addc_u32 s9, s9, 0
	global_load_dwordx4 v[144:147], v1, s[8:9]
	global_load_dwordx4 v[148:151], v1, s[8:9] offset:1024
	global_load_dwordx4 v[152:155], v1, s[8:9] offset:2048
	global_load_dwordx4 v[156:159], v1, s[8:9] offset:3072
	s_add_u32 s8, s8, 0x1000
	s_addc_u32 s9, s9, 0
	global_load_dwordx4 v[164:167], v1, s[8:9]
	global_load_dwordx4 v[168:171], v1, s[8:9] offset:1024
	global_load_dwordx4 v[172:175], v1, s[8:9] offset:2048
	global_load_dwordx4 v[176:179], v1, s[8:9] offset:3072
	s_add_u32 s8, s8, 0x1000
	s_addc_u32 s9, s9, 0
	global_load_dwordx4 v[180:183], v1, s[8:9]
	global_load_dwordx4 v[184:187], v1, s[8:9] offset:1024
	global_load_dwordx4 v[188:191], v1, s[8:9] offset:2048
	global_load_dwordx4 v[192:195], v1, s[8:9] offset:3072
	s_add_u32 s8, s8, 0x1000
	s_addc_u32 s9, s9, 0
	global_load_dwordx4 v[196:199], v1, s[8:9]
	global_load_dwordx4 v[200:203], v1, s[8:9] offset:1024
	global_load_dwordx4 v[204:207], v1, s[8:9] offset:2048
	global_load_dwordx4 v[208:211], v1, s[8:9] offset:3072
	s_add_u32 s8, s8, 0x1000
	s_addc_u32 s9, s9, 0
	global_load_dwordx4 v[212:215], v1, s[8:9]
	global_load_dwordx4 v[216:219], v1, s[8:9] offset:1024
	global_load_dwordx4 v[220:223], v1, s[8:9] offset:2048
	global_load_dwordx4 v[224:227], v1, s[8:9] offset:3072
	s_add_u32 s8, s8, 0x1000
	s_addc_u32 s9, s9, 0
	s_waitcnt vmcnt(32)
	v_pk_add_f32 v[40:41], v[40:41], 1.0 op_sel_hi:[1,0]
	v_pk_add_f32 v[42:43], v[42:43], 1.0 op_sel_hi:[1,0]
	v_pk_add_f32 v[64:65], v[64:65], 1.0 op_sel_hi:[1,0]
	v_pk_add_f32 v[66:67], v[66:67], 1.0 op_sel_hi:[1,0]
	v_pk_add_f32 v[68:69], v[68:69], 1.0 op_sel_hi:[1,0]
	v_pk_add_f32 v[70:71], v[70:71], 1.0 op_sel_hi:[1,0]
	v_pk_add_f32 v[72:73], v[72:73], 1.0 op_sel_hi:[1,0]
	v_pk_add_f32 v[74:75], v[74:75], 1.0 op_sel_hi:[1,0]
	s_waitcnt vmcnt(16)
; DI unsigned pk2(float lo, float hi) { return f2bf(lo) | (f2bf(hi) << 16); }
; DI void norm_phase(const Args& A, int wave_s, int l, int which, int rows) {
;     ...
;             float ss = 0.f;
; #pragma unroll
;             for (int j = 0; j < 4; ++j) ss += (xv[rr][j].x * xv[rr][j].x + xv[rr][j].y * xv[rr][j].y) + (xv[rr][j].z * xv[rr][j].z + xv[rr][j].w * xv[rr][j].w);
;             ss = wave_sum(C.lane, ss);
;             const float rs = rsqrtf(ss * (1.f / 1024.f) + EPS);
; #pragma unroll
;             for (int j = 0; j < 4; ++j) { const int col = 4 * (C.lane + 64 * j);
;                 const f32x4 y = xv[rr][j] * rs * g[j] * (sc[j] + 1.f) + sh[j];
;                 v2u o; o.x = pk2(y.x, y.y); o.y = pk2(y.z, y.w);
;                 *(v2u*)(C.H + (size_t)m * 1024 + col) = o; }
	v_mul_f32_e32 v10, v96, v96
	v_fmac_f32_e32 v10, v97, v97
	v_fmac_f32_e32 v10, v98, v98
	v_fmac_f32_e32 v10, v99, v99
	v_fmac_f32_e32 v10, v100, v100
	v_fmac_f32_e32 v10, v101, v101
	v_fmac_f32_e32 v10, v102, v102
	v_fmac_f32_e32 v10, v103, v103
	v_fmac_f32_e32 v10, v104, v104
	v_fmac_f32_e32 v10, v105, v105
	v_fmac_f32_e32 v10, v106, v106
	v_fmac_f32_e32 v10, v107, v107
	v_fmac_f32_e32 v10, v108, v108
	v_fmac_f32_e32 v10, v109, v109
	v_fmac_f32_e32 v10, v110, v110
	v_fmac_f32_e32 v10, v111, v111
	v_mul_f32_e32 v11, v112, v112
	v_fmac_f32_e32 v11, v113, v113
	v_fmac_f32_e32 v11, v114, v114
	v_fmac_f32_e32 v11, v115, v115
	v_fmac_f32_e32 v11, v116, v116
	v_fmac_f32_e32 v11, v117, v117
	v_fmac_f32_e32 v11, v118, v118
	v_fmac_f32_e32 v11, v119, v119
	v_fmac_f32_e32 v11, v120, v120
	v_fmac_f32_e32 v11, v121, v121
	v_fmac_f32_e32 v11, v122, v122
	v_fmac_f32_e32 v11, v123, v123
	v_fmac_f32_e32 v11, v124, v124
	v_fmac_f32_e32 v11, v125, v125
	v_fmac_f32_e32 v11, v126, v126
	v_fmac_f32_e32 v11, v127, v127
	v_mul_f32_e32 v12, v128, v128
	v_fmac_f32_e32 v12, v129, v129
	v_fmac_f32_e32 v12, v130, v130
	v_fmac_f32_e32 v12, v131, v131
	v_fmac_f32_e32 v12, v132, v132
	v_fmac_f32_e32 v12, v133, v133
	v_fmac_f32_e32 v12, v134, v134
	v_fmac_f32_e32 v12, v135, v135
	v_fmac_f32_e32 v12, v136, v136
	v_fmac_f32_e32 v12, v137, v137
	v_fmac_f32_e32 v12, v138, v138
	v_fmac_f32_e32 v12, v139, v139
	v_fmac_f32_e32 v12, v140, v140
	v_fmac_f32_e32 v12, v141, v141
	v_fmac_f32_e32 v12, v142, v142
	v_fmac_f32_e32 v12, v143, v143
	v_mul_f32_e32 v13, v144, v144
	v_fmac_f32_e32 v13, v145, v145
	v_fmac_f32_e32 v13, v146, v146
	v_fmac_f32_e32 v13, v147, v147
	v_fmac_f32_e32 v13, v148, v148
	v_fmac_f32_e32 v13, v149, v149
	v_fmac_f32_e32 v13, v150, v150
	v_fmac_f32_e32 v13, v151, v151
	v_fmac_f32_e32 v13, v152, v152
	v_fmac_f32_e32 v13, v153, v153
	v_fmac_f32_e32 v13, v154, v154
	v_fmac_f32_e32 v13, v155, v155
	v_fmac_f32_e32 v13, v156, v156
	v_fmac_f32_e32 v13, v157, v157
	v_fmac_f32_e32 v13, v158, v158
	v_fmac_f32_e32 v13, v159, v159
	ds_bpermute_b32 v14, v4, v10
	ds_bpermute_b32 v15, v4, v11
	ds_bpermute_b32 v16, v4, v12
	ds_bpermute_b32 v17, v4, v13
	s_waitcnt lgkmcnt(0)
	v_add_f32_e32 v10, v10, v14
	v_add_f32_e32 v11, v11, v15
	v_add_f32_e32 v12, v12, v16
	v_add_f32_e32 v13, v13, v17
	ds_bpermute_b32 v14, v5, v10
	ds_bpermute_b32 v15, v5, v11
	ds_bpermute_b32 v16, v5, v12
	ds_bpermute_b32 v17, v5, v13
	s_waitcnt lgkmcnt(0)
	v_add_f32_e32 v10, v10, v14
	v_add_f32_e32 v11, v11, v15
	v_add_f32_e32 v12, v12, v16
	v_add_f32_e32 v13, v13, v17
	ds_bpermute_b32 v14, v6, v10
	ds_bpermute_b32 v15, v6, v11
	ds_bpermute_b32 v16, v6, v12
	ds_bpermute_b32 v17, v6, v13
	s_waitcnt lgkmcnt(0)
	v_add_f32_e32 v10, v10, v14
	v_add_f32_e32 v11, v11, v15
	v_add_f32_e32 v12, v12, v16
	v_add_f32_e32 v13, v13, v17
	ds_bpermute_b32 v14, v7, v10
	ds_bpermute_b32 v15, v7, v11
	ds_bpermute_b32 v16, v7, v12
	ds_bpermute_b32 v17, v7, v13
	s_waitcnt lgkmcnt(0)
	v_add_f32_e32 v10, v10, v14
	v_add_f32_e32 v11, v11, v15
	v_add_f32_e32 v12, v12, v16
	v_add_f32_e32 v13, v13, v17
	ds_bpermute_b32 v14, v8, v10
	ds_bpermute_b32 v15, v8, v11
	ds_bpermute_b32 v16, v8, v12
	ds_bpermute_b32 v17, v8, v13
	s_waitcnt lgkmcnt(0)
	v_add_f32_e32 v10, v10, v14
	v_add_f32_e32 v11, v11, v15
	v_add_f32_e32 v12, v12, v16
	v_add_f32_e32 v13, v13, v17
	ds_bpermute_b32 v14, v9, v10
	ds_bpermute_b32 v15, v9, v11
	ds_bpermute_b32 v16, v9, v12
	ds_bpermute_b32 v17, v9, v13
	s_waitcnt lgkmcnt(0)
	v_add_f32_e32 v10, v10, v14
	v_add_f32_e32 v11, v11, v15
	v_add_f32_e32 v12, v12, v16
	v_add_f32_e32 v13, v13, v17
	v_fma_f32 v10, v10, s32, v60
	v_fma_f32 v11, v11, s32, v60
	v_fma_f32 v12, v12, s32, v60
	v_fma_f32 v13, v13, s32, v60
	v_rsq_f32_e32 v18, v10
	v_rsq_f32_e32 v20, v11
	v_rsq_f32_e32 v22, v12
	v_rsq_f32_e32 v62, v13
	s_nop 0
	v_pk_mul_f32 v[96:97], v[96:97], v[18:19] op_sel_hi:[1,0]
	v_pk_mul_f32 v[98:99], v[98:99], v[18:19] op_sel_hi:[1,0]
	v_pk_mul_f32 v[100:101], v[100:101], v[18:19] op_sel_hi:[1,0]
	v_pk_mul_f32 v[102:103], v[102:103], v[18:19] op_sel_hi:[1,0]
	v_pk_mul_f32 v[104:105], v[104:105], v[18:19] op_sel_hi:[1,0]
	v_pk_mul_f32 v[106:107], v[106:107], v[18:19] op_sel_hi:[1,0]
	v_pk_mul_f32 v[108:109], v[108:109], v[18:19] op_sel_hi:[1,0]
	v_pk_mul_f32 v[110:111], v[110:111], v[18:19] op_sel_hi:[1,0]
	v_pk_mul_f32 v[96:97], v[24:25], v[96:97]
	v_pk_mul_f32 v[98:99], v[26:27], v[98:99]
	v_pk_mul_f32 v[100:101], v[28:29], v[100:101]
	v_pk_mul_f32 v[102:103], v[30:31], v[102:103]
	v_pk_mul_f32 v[104:105], v[32:33], v[104:105]
	v_pk_mul_f32 v[106:107], v[34:35], v[106:107]
	v_pk_mul_f32 v[108:109], v[36:37], v[108:109]
	v_pk_mul_f32 v[110:111], v[38:39], v[110:111]
	v_pk_fma_f32 v[96:97], v[40:41], v[96:97], v[80:81]
	v_pk_fma_f32 v[98:99], v[42:43], v[98:99], v[82:83]
	v_pk_fma_f32 v[100:101], v[64:65], v[100:101], v[84:85]
	v_pk_fma_f32 v[102:103], v[66:67], v[102:103], v[86:87]
	v_pk_fma_f32 v[104:105], v[68:69], v[104:105], v[88:89]
	v_pk_fma_f32 v[106:107], v[70:71], v[106:107], v[90:91]
	v_pk_fma_f32 v[108:109], v[72:73], v[108:109], v[92:93]
	v_pk_fma_f32 v[110:111], v[74:75], v[110:111], v[94:95]
	v_cvt_pk_bf16_f32 v96, v96, v97
	v_cvt_pk_bf16_f32 v97, v98, v99
	v_cvt_pk_bf16_f32 v100, v100, v101
	v_cvt_pk_bf16_f32 v101, v102, v103
	v_cvt_pk_bf16_f32 v104, v104, v105
	v_cvt_pk_bf16_f32 v105, v106, v107
	v_cvt_pk_bf16_f32 v108, v108, v109
	v_cvt_pk_bf16_f32 v109, v110, v111
	global_store_dwordx2 v2, v[96:97], s[10:11] sc1
	global_store_dwordx2 v2, v[100:101], s[10:11] offset:512 sc1
	global_store_dwordx2 v2, v[104:105], s[10:11] offset:1024 sc1
	global_store_dwordx2 v2, v[108:109], s[10:11] offset:1536 sc1
; DI unsigned pk2(float lo, float hi) { return f2bf(lo) | (f2bf(hi) << 16); }
; DI void norm_phase(const Args& A, int wave_s, int l, int which, int rows) {
;     ...
;             for (int j = 0; j < 4; ++j) xv[rr][j] = ((const f32x4*)xr)[C.lane + 64 * j];
;     ...
; #pragma unroll
;             for (int j = 0; j < 4; ++j) { const int col = 4 * (C.lane + 64 * j);
;                 const f32x4 y = xv[rr][j] * rs * g[j] * (sc[j] + 1.f) + sh[j];
;                 v2u o; o.x = pk2(y.x, y.y); o.y = pk2(y.z, y.w);
;                 *(v2u*)(C.H + (size_t)m * 1024 + col) = o; }
	s_add_u32 s10, s10, 0x800
	s_addc_u32 s11, s11, 0
	v_pk_mul_f32 v[112:113], v[112:113], v[20:21] op_sel_hi:[1,0]
	v_pk_mul_f32 v[114:115], v[114:115], v[20:21] op_sel_hi:[1,0]
	v_pk_mul_f32 v[116:117], v[116:117], v[20:21] op_sel_hi:[1,0]
	v_pk_mul_f32 v[118:119], v[118:119], v[20:21] op_sel_hi:[1,0]
	v_pk_mul_f32 v[120:121], v[120:121], v[20:21] op_sel_hi:[1,0]
	v_pk_mul_f32 v[122:123], v[122:123], v[20:21] op_sel_hi:[1,0]
	v_pk_mul_f32 v[124:125], v[124:125], v[20:21] op_sel_hi:[1,0]
	v_pk_mul_f32 v[126:127], v[126:127], v[20:21] op_sel_hi:[1,0]
	v_pk_mul_f32 v[112:113], v[24:25], v[112:113]
	v_pk_mul_f32 v[114:115], v[26:27], v[114:115]
	v_pk_mul_f32 v[116:117], v[28:29], v[116:117]
	v_pk_mul_f32 v[118:119], v[30:31], v[118:119]
	v_pk_mul_f32 v[120:121], v[32:33], v[120:121]
	v_pk_mul_f32 v[122:123], v[34:35], v[122:123]
	v_pk_mul_f32 v[124:125], v[36:37], v[124:125]
	v_pk_mul_f32 v[126:127], v[38:39], v[126:127]
	v_pk_fma_f32 v[112:113], v[40:41], v[112:113], v[80:81]
	v_pk_fma_f32 v[114:115], v[42:43], v[114:115], v[82:83]
	v_pk_fma_f32 v[116:117], v[64:65], v[116:117], v[84:85]
	v_pk_fma_f32 v[118:119], v[66:67], v[118:119], v[86:87]
	v_pk_fma_f32 v[120:121], v[68:69], v[120:121], v[88:89]
	v_pk_fma_f32 v[122:123], v[70:71], v[122:123], v[90:91]
	v_pk_fma_f32 v[124:125], v[72:73], v[124:125], v[92:93]
	v_pk_fma_f32 v[126:127], v[74:75], v[126:127], v[94:95]
	v_cvt_pk_bf16_f32 v112, v112, v113
	v_cvt_pk_bf16_f32 v113, v114, v115
	v_cvt_pk_bf16_f32 v116, v116, v117
	v_cvt_pk_bf16_f32 v117, v118, v119
	v_cvt_pk_bf16_f32 v120, v120, v121
	v_cvt_pk_bf16_f32 v121, v122, v123
	v_cvt_pk_bf16_f32 v124, v124, v125
	v_cvt_pk_bf16_f32 v125, v126, v127
	global_store_dwordx2 v2, v[112:113], s[10:11] sc1
	global_store_dwordx2 v2, v[116:117], s[10:11] offset:512 sc1
	global_store_dwordx2 v2, v[120:121], s[10:11] offset:1024 sc1
	global_store_dwordx2 v2, v[124:125], s[10:11] offset:1536 sc1
	s_add_u32 s10, s10, 0x800
	s_addc_u32 s11, s11, 0
	v_pk_mul_f32 v[128:129], v[128:129], v[22:23] op_sel_hi:[1,0]
	v_pk_mul_f32 v[130:131], v[130:131], v[22:23] op_sel_hi:[1,0]
	v_pk_mul_f32 v[132:133], v[132:133], v[22:23] op_sel_hi:[1,0]
	v_pk_mul_f32 v[134:135], v[134:135], v[22:23] op_sel_hi:[1,0]
	v_pk_mul_f32 v[136:137], v[136:137], v[22:23] op_sel_hi:[1,0]
	v_pk_mul_f32 v[138:139], v[138:139], v[22:23] op_sel_hi:[1,0]
	v_pk_mul_f32 v[140:141], v[140:141], v[22:23] op_sel_hi:[1,0]
	v_pk_mul_f32 v[142:143], v[142:143], v[22:23] op_sel_hi:[1,0]
	v_pk_mul_f32 v[128:129], v[24:25], v[128:129]
	v_pk_mul_f32 v[130:131], v[26:27], v[130:131]
	v_pk_mul_f32 v[132:133], v[28:29], v[132:133]
	v_pk_mul_f32 v[134:135], v[30:31], v[134:135]
	v_pk_mul_f32 v[136:137], v[32:33], v[136:137]
	v_pk_mul_f32 v[138:139], v[34:35], v[138:139]
	v_pk_mul_f32 v[140:141], v[36:37], v[140:141]
	v_pk_mul_f32 v[142:143], v[38:39], v[142:143]
	v_pk_fma_f32 v[128:129], v[40:41], v[128:129], v[80:81]
	v_pk_fma_f32 v[130:131], v[42:43], v[130:131], v[82:83]
	v_pk_fma_f32 v[132:133], v[64:65], v[132:133], v[84:85]
	v_pk_fma_f32 v[134:135], v[66:67], v[134:135], v[86:87]
	v_pk_fma_f32 v[136:137], v[68:69], v[136:137], v[88:89]
	v_pk_fma_f32 v[138:139], v[70:71], v[138:139], v[90:91]
	v_pk_fma_f32 v[140:141], v[72:73], v[140:141], v[92:93]
	v_pk_fma_f32 v[142:143], v[74:75], v[142:143], v[94:95]
	v_cvt_pk_bf16_f32 v128, v128, v129
	v_cvt_pk_bf16_f32 v129, v130, v131
	v_cvt_pk_bf16_f32 v132, v132, v133
	v_cvt_pk_bf16_f32 v133, v134, v135
	v_cvt_pk_bf16_f32 v136, v136, v137
	v_cvt_pk_bf16_f32 v137, v138, v139
	v_cvt_pk_bf16_f32 v140, v140, v141
	v_cvt_pk_bf16_f32 v141, v142, v143
	global_store_dwordx2 v2, v[128:129], s[10:11] sc1
	global_store_dwordx2 v2, v[132:133], s[10:11] offset:512 sc1
	global_store_dwordx2 v2, v[136:137], s[10:11] offset:1024 sc1
	global_store_dwordx2 v2, v[140:141], s[10:11] offset:1536 sc1
	s_add_u32 s10, s10, 0x800
	s_addc_u32 s11, s11, 0
	v_pk_mul_f32 v[144:145], v[144:145], v[62:63] op_sel_hi:[1,0]
	v_pk_mul_f32 v[146:147], v[146:147], v[62:63] op_sel_hi:[1,0]
	v_pk_mul_f32 v[148:149], v[148:149], v[62:63] op_sel_hi:[1,0]
	v_pk_mul_f32 v[150:151], v[150:151], v[62:63] op_sel_hi:[1,0]
	v_pk_mul_f32 v[152:153], v[152:153], v[62:63] op_sel_hi:[1,0]
	v_pk_mul_f32 v[154:155], v[154:155], v[62:63] op_sel_hi:[1,0]
	v_pk_mul_f32 v[156:157], v[156:157], v[62:63] op_sel_hi:[1,0]
	v_pk_mul_f32 v[158:159], v[158:159], v[62:63] op_sel_hi:[1,0]
	v_pk_mul_f32 v[144:145], v[24:25], v[144:145]
	v_pk_mul_f32 v[146:147], v[26:27], v[146:147]
	v_pk_mul_f32 v[148:149], v[28:29], v[148:149]
	v_pk_mul_f32 v[150:151], v[30:31], v[150:151]
	v_pk_mul_f32 v[152:153], v[32:33], v[152:153]
	v_pk_mul_f32 v[154:155], v[34:35], v[154:155]
	v_pk_mul_f32 v[156:157], v[36:37], v[156:157]
	v_pk_mul_f32 v[158:159], v[38:39], v[158:159]
	v_pk_fma_f32 v[144:145], v[40:41], v[144:145], v[80:81]
	v_pk_fma_f32 v[146:147], v[42:43], v[146:147], v[82:83]
	v_pk_fma_f32 v[148:149], v[64:65], v[148:149], v[84:85]
	v_pk_fma_f32 v[150:151], v[66:67], v[150:151], v[86:87]
	v_pk_fma_f32 v[152:153], v[68:69], v[152:153], v[88:89]
	v_pk_fma_f32 v[154:155], v[70:71], v[154:155], v[90:91]
	v_pk_fma_f32 v[156:157], v[72:73], v[156:157], v[92:93]
	v_pk_fma_f32 v[158:159], v[74:75], v[158:159], v[94:95]
	v_cvt_pk_bf16_f32 v144, v144, v145
	v_cvt_pk_bf16_f32 v145, v146, v147
	v_cvt_pk_bf16_f32 v148, v148, v149
	v_cvt_pk_bf16_f32 v149, v150, v151
	v_cvt_pk_bf16_f32 v152, v152, v153
	v_cvt_pk_bf16_f32 v153, v154, v155
	v_cvt_pk_bf16_f32 v156, v156, v157
	v_cvt_pk_bf16_f32 v157, v158, v159
	global_store_dwordx2 v2, v[144:145], s[10:11] sc1
	global_store_dwordx2 v2, v[148:149], s[10:11] offset:512 sc1
	global_store_dwordx2 v2, v[152:153], s[10:11] offset:1024 sc1
	global_store_dwordx2 v2, v[156:157], s[10:11] offset:1536 sc1
	s_add_u32 s10, s10, 0x800
	s_addc_u32 s11, s11, 0
	global_load_dwordx4 v[96:99], v1, s[8:9]
	global_load_dwordx4 v[100:103], v1, s[8:9] offset:1024
	global_load_dwordx4 v[104:107], v1, s[8:9] offset:2048
	global_load_dwordx4 v[108:111], v1, s[8:9] offset:3072
	s_add_u32 s8, s8, 0x1000
	s_addc_u32 s9, s9, 0
	global_load_dwordx4 v[112:115], v1, s[8:9]
	global_load_dwordx4 v[116:119], v1, s[8:9] offset:1024
	global_load_dwordx4 v[120:123], v1, s[8:9] offset:2048
	global_load_dwordx4 v[124:127], v1, s[8:9] offset:3072
	s_add_u32 s8, s8, 0x1000
	s_addc_u32 s9, s9, 0
	global_load_dwordx4 v[128:131], v1, s[8:9]
	global_load_dwordx4 v[132:135], v1, s[8:9] offset:1024
	global_load_dwordx4 v[136:139], v1, s[8:9] offset:2048
	global_load_dwordx4 v[140:143], v1, s[8:9] offset:3072
	s_add_u32 s8, s8, 0x1000
	s_addc_u32 s9, s9, 0
	global_load_dwordx4 v[144:147], v1, s[8:9]
	global_load_dwordx4 v[148:151], v1, s[8:9] offset:1024
	global_load_dwordx4 v[152:155], v1, s[8:9] offset:2048
	global_load_dwordx4 v[156:159], v1, s[8:9] offset:3072
	s_add_u32 s8, s8, 0x1000
	s_addc_u32 s9, s9, 0
	s_waitcnt vmcnt(32)
; DI unsigned pk2(float lo, float hi) { return f2bf(lo) | (f2bf(hi) << 16); }
; DI void norm_phase(const Args& A, int wave_s, int l, int which, int rows) {
;     ...
;             float ss = 0.f;
; #pragma unroll
;             for (int j = 0; j < 4; ++j) ss += (xv[rr][j].x * xv[rr][j].x + xv[rr][j].y * xv[rr][j].y) + (xv[rr][j].z * xv[rr][j].z + xv[rr][j].w * xv[rr][j].w);
;             ss = wave_sum(C.lane, ss);
;             const float rs = rsqrtf(ss * (1.f / 1024.f) + EPS);
; #pragma unroll
;             for (int j = 0; j < 4; ++j) { const int col = 4 * (C.lane + 64 * j);
;                 const f32x4 y = xv[rr][j] * rs * g[j] * (sc[j] + 1.f) + sh[j];
;                 v2u o; o.x = pk2(y.x, y.y); o.y = pk2(y.z, y.w);
;                 *(v2u*)(C.H + (size_t)m * 1024 + col) = o; }
	v_mul_f32_e32 v10, v164, v164
	v_fmac_f32_e32 v10, v165, v165
	v_fmac_f32_e32 v10, v166, v166
	v_fmac_f32_e32 v10, v167, v167
	v_fmac_f32_e32 v10, v168, v168
	v_fmac_f32_e32 v10, v169, v169
	v_fmac_f32_e32 v10, v170, v170
	v_fmac_f32_e32 v10, v171, v171
	v_fmac_f32_e32 v10, v172, v172
	v_fmac_f32_e32 v10, v173, v173
	v_fmac_f32_e32 v10, v174, v174
	v_fmac_f32_e32 v10, v175, v175
	v_fmac_f32_e32 v10, v176, v176
	v_fmac_f32_e32 v10, v177, v177
	v_fmac_f32_e32 v10, v178, v178
	v_fmac_f32_e32 v10, v179, v179
	v_mul_f32_e32 v11, v180, v180
	v_fmac_f32_e32 v11, v181, v181
	v_fmac_f32_e32 v11, v182, v182
	v_fmac_f32_e32 v11, v183, v183
	v_fmac_f32_e32 v11, v184, v184
	v_fmac_f32_e32 v11, v185, v185
	v_fmac_f32_e32 v11, v186, v186
	v_fmac_f32_e32 v11, v187, v187
	v_fmac_f32_e32 v11, v188, v188
	v_fmac_f32_e32 v11, v189, v189
	v_fmac_f32_e32 v11, v190, v190
	v_fmac_f32_e32 v11, v191, v191
	v_fmac_f32_e32 v11, v192, v192
	v_fmac_f32_e32 v11, v193, v193
	v_fmac_f32_e32 v11, v194, v194
	v_fmac_f32_e32 v11, v195, v195
	v_mul_f32_e32 v12, v196, v196
	v_fmac_f32_e32 v12, v197, v197
	v_fmac_f32_e32 v12, v198, v198
	v_fmac_f32_e32 v12, v199, v199
	v_fmac_f32_e32 v12, v200, v200
	v_fmac_f32_e32 v12, v201, v201
	v_fmac_f32_e32 v12, v202, v202
	v_fmac_f32_e32 v12, v203, v203
	v_fmac_f32_e32 v12, v204, v204
	v_fmac_f32_e32 v12, v205, v205
	v_fmac_f32_e32 v12, v206, v206
	v_fmac_f32_e32 v12, v207, v207
	v_fmac_f32_e32 v12, v208, v208
	v_fmac_f32_e32 v12, v209, v209
	v_fmac_f32_e32 v12, v210, v210
	v_fmac_f32_e32 v12, v211, v211
	v_mul_f32_e32 v13, v212, v212
	v_fmac_f32_e32 v13, v213, v213
	v_fmac_f32_e32 v13, v214, v214
	v_fmac_f32_e32 v13, v215, v215
	v_fmac_f32_e32 v13, v216, v216
	v_fmac_f32_e32 v13, v217, v217
	v_fmac_f32_e32 v13, v218, v218
	v_fmac_f32_e32 v13, v219, v219
	v_fmac_f32_e32 v13, v220, v220
	v_fmac_f32_e32 v13, v221, v221
	v_fmac_f32_e32 v13, v222, v222
	v_fmac_f32_e32 v13, v223, v223
	v_fmac_f32_e32 v13, v224, v224
	v_fmac_f32_e32 v13, v225, v225
	v_fmac_f32_e32 v13, v226, v226
	v_fmac_f32_e32 v13, v227, v227
	ds_bpermute_b32 v14, v4, v10
	ds_bpermute_b32 v15, v4, v11
	ds_bpermute_b32 v16, v4, v12
	ds_bpermute_b32 v17, v4, v13
	s_waitcnt lgkmcnt(0)
	v_add_f32_e32 v10, v10, v14
	v_add_f32_e32 v11, v11, v15
	v_add_f32_e32 v12, v12, v16
	v_add_f32_e32 v13, v13, v17
	ds_bpermute_b32 v14, v5, v10
	ds_bpermute_b32 v15, v5, v11
	ds_bpermute_b32 v16, v5, v12
	ds_bpermute_b32 v17, v5, v13
	s_waitcnt lgkmcnt(0)
	v_add_f32_e32 v10, v10, v14
	v_add_f32_e32 v11, v11, v15
	v_add_f32_e32 v12, v12, v16
	v_add_f32_e32 v13, v13, v17
	ds_bpermute_b32 v14, v6, v10
	ds_bpermute_b32 v15, v6, v11
	ds_bpermute_b32 v16, v6, v12
	ds_bpermute_b32 v17, v6, v13
	s_waitcnt lgkmcnt(0)
	v_add_f32_e32 v10, v10, v14
	v_add_f32_e32 v11, v11, v15
	v_add_f32_e32 v12, v12, v16
	v_add_f32_e32 v13, v13, v17
	ds_bpermute_b32 v14, v7, v10
	ds_bpermute_b32 v15, v7, v11
	ds_bpermute_b32 v16, v7, v12
	ds_bpermute_b32 v17, v7, v13
	s_waitcnt lgkmcnt(0)
	v_add_f32_e32 v10, v10, v14
	v_add_f32_e32 v11, v11, v15
	v_add_f32_e32 v12, v12, v16
	v_add_f32_e32 v13, v13, v17
	ds_bpermute_b32 v14, v8, v10
	ds_bpermute_b32 v15, v8, v11
	ds_bpermute_b32 v16, v8, v12
	ds_bpermute_b32 v17, v8, v13
	s_waitcnt lgkmcnt(0)
	v_add_f32_e32 v10, v10, v14
	v_add_f32_e32 v11, v11, v15
	v_add_f32_e32 v12, v12, v16
	v_add_f32_e32 v13, v13, v17
	ds_bpermute_b32 v14, v9, v10
	ds_bpermute_b32 v15, v9, v11
	ds_bpermute_b32 v16, v9, v12
	ds_bpermute_b32 v17, v9, v13
	s_waitcnt lgkmcnt(0)
	v_add_f32_e32 v10, v10, v14
	v_add_f32_e32 v11, v11, v15
	v_add_f32_e32 v12, v12, v16
	v_add_f32_e32 v13, v13, v17
	v_fma_f32 v10, v10, s32, v60
	v_fma_f32 v11, v11, s32, v60
	v_fma_f32 v12, v12, s32, v60
	v_fma_f32 v13, v13, s32, v60
	v_rsq_f32_e32 v18, v10
	v_rsq_f32_e32 v20, v11
	v_rsq_f32_e32 v22, v12
	v_rsq_f32_e32 v62, v13
	s_nop 0
	v_pk_mul_f32 v[164:165], v[164:165], v[18:19] op_sel_hi:[1,0]
	v_pk_mul_f32 v[166:167], v[166:167], v[18:19] op_sel_hi:[1,0]
	v_pk_mul_f32 v[168:169], v[168:169], v[18:19] op_sel_hi:[1,0]
	v_pk_mul_f32 v[170:171], v[170:171], v[18:19] op_sel_hi:[1,0]
	v_pk_mul_f32 v[172:173], v[172:173], v[18:19] op_sel_hi:[1,0]
	v_pk_mul_f32 v[174:175], v[174:175], v[18:19] op_sel_hi:[1,0]
	v_pk_mul_f32 v[176:177], v[176:177], v[18:19] op_sel_hi:[1,0]
	v_pk_mul_f32 v[178:179], v[178:179], v[18:19] op_sel_hi:[1,0]
	v_pk_mul_f32 v[164:165], v[24:25], v[164:165]
	v_pk_mul_f32 v[166:167], v[26:27], v[166:167]
	v_pk_mul_f32 v[168:169], v[28:29], v[168:169]
	v_pk_mul_f32 v[170:171], v[30:31], v[170:171]
	v_pk_mul_f32 v[172:173], v[32:33], v[172:173]
	v_pk_mul_f32 v[174:175], v[34:35], v[174:175]
	v_pk_mul_f32 v[176:177], v[36:37], v[176:177]
	v_pk_mul_f32 v[178:179], v[38:39], v[178:179]
	v_pk_fma_f32 v[164:165], v[40:41], v[164:165], v[80:81]
	v_pk_fma_f32 v[166:167], v[42:43], v[166:167], v[82:83]
	v_pk_fma_f32 v[168:169], v[64:65], v[168:169], v[84:85]
	v_pk_fma_f32 v[170:171], v[66:67], v[170:171], v[86:87]
	v_pk_fma_f32 v[172:173], v[68:69], v[172:173], v[88:89]
	v_pk_fma_f32 v[174:175], v[70:71], v[174:175], v[90:91]
	v_pk_fma_f32 v[176:177], v[72:73], v[176:177], v[92:93]
	v_pk_fma_f32 v[178:179], v[74:75], v[178:179], v[94:95]
	v_cvt_pk_bf16_f32 v164, v164, v165
	v_cvt_pk_bf16_f32 v165, v166, v167
	v_cvt_pk_bf16_f32 v168, v168, v169
	v_cvt_pk_bf16_f32 v169, v170, v171
	v_cvt_pk_bf16_f32 v172, v172, v173
	v_cvt_pk_bf16_f32 v173, v174, v175
	v_cvt_pk_bf16_f32 v176, v176, v177
	v_cvt_pk_bf16_f32 v177, v178, v179
	global_store_dwordx2 v2, v[164:165], s[10:11] sc1
	global_store_dwordx2 v2, v[168:169], s[10:11] offset:512 sc1
	global_store_dwordx2 v2, v[172:173], s[10:11] offset:1024 sc1
; DI unsigned pk2(float lo, float hi) { return f2bf(lo) | (f2bf(hi) << 16); }
; DI void norm_phase(const Args& A, int wave_s, int l, int which, int rows) {
;     ...
;             for (int j = 0; j < 4; ++j) xv[rr][j] = ((const f32x4*)xr)[C.lane + 64 * j];
;     ...
; #pragma unroll
;             for (int j = 0; j < 4; ++j) { const int col = 4 * (C.lane + 64 * j);
;                 const f32x4 y = xv[rr][j] * rs * g[j] * (sc[j] + 1.f) + sh[j];
;                 v2u o; o.x = pk2(y.x, y.y); o.y = pk2(y.z, y.w);
;                 *(v2u*)(C.H + (size_t)m * 1024 + col) = o; }
	global_store_dwordx2 v2, v[176:177], s[10:11] offset:1536 sc1
	s_add_u32 s10, s10, 0x800
	s_addc_u32 s11, s11, 0
	v_pk_mul_f32 v[180:181], v[180:181], v[20:21] op_sel_hi:[1,0]
	v_pk_mul_f32 v[182:183], v[182:183], v[20:21] op_sel_hi:[1,0]
	v_pk_mul_f32 v[184:185], v[184:185], v[20:21] op_sel_hi:[1,0]
	v_pk_mul_f32 v[186:187], v[186:187], v[20:21] op_sel_hi:[1,0]
	v_pk_mul_f32 v[188:189], v[188:189], v[20:21] op_sel_hi:[1,0]
	v_pk_mul_f32 v[190:191], v[190:191], v[20:21] op_sel_hi:[1,0]
	v_pk_mul_f32 v[192:193], v[192:193], v[20:21] op_sel_hi:[1,0]
	v_pk_mul_f32 v[194:195], v[194:195], v[20:21] op_sel_hi:[1,0]
	v_pk_mul_f32 v[180:181], v[24:25], v[180:181]
	v_pk_mul_f32 v[182:183], v[26:27], v[182:183]
	v_pk_mul_f32 v[184:185], v[28:29], v[184:185]
	v_pk_mul_f32 v[186:187], v[30:31], v[186:187]
	v_pk_mul_f32 v[188:189], v[32:33], v[188:189]
	v_pk_mul_f32 v[190:191], v[34:35], v[190:191]
	v_pk_mul_f32 v[192:193], v[36:37], v[192:193]
	v_pk_mul_f32 v[194:195], v[38:39], v[194:195]
	v_pk_fma_f32 v[180:181], v[40:41], v[180:181], v[80:81]
	v_pk_fma_f32 v[182:183], v[42:43], v[182:183], v[82:83]
	v_pk_fma_f32 v[184:185], v[64:65], v[184:185], v[84:85]
	v_pk_fma_f32 v[186:187], v[66:67], v[186:187], v[86:87]
	v_pk_fma_f32 v[188:189], v[68:69], v[188:189], v[88:89]
	v_pk_fma_f32 v[190:191], v[70:71], v[190:191], v[90:91]
	v_pk_fma_f32 v[192:193], v[72:73], v[192:193], v[92:93]
	v_pk_fma_f32 v[194:195], v[74:75], v[194:195], v[94:95]
	v_cvt_pk_bf16_f32 v180, v180, v181
	v_cvt_pk_bf16_f32 v181, v182, v183
	v_cvt_pk_bf16_f32 v184, v184, v185
	v_cvt_pk_bf16_f32 v185, v186, v187
	v_cvt_pk_bf16_f32 v188, v188, v189
	v_cvt_pk_bf16_f32 v189, v190, v191
	v_cvt_pk_bf16_f32 v192, v192, v193
	v_cvt_pk_bf16_f32 v193, v194, v195
	global_store_dwordx2 v2, v[180:181], s[10:11] sc1
	global_store_dwordx2 v2, v[184:185], s[10:11] offset:512 sc1
	global_store_dwordx2 v2, v[188:189], s[10:11] offset:1024 sc1
	global_store_dwordx2 v2, v[192:193], s[10:11] offset:1536 sc1
	s_add_u32 s10, s10, 0x800
	s_addc_u32 s11, s11, 0
	v_pk_mul_f32 v[196:197], v[196:197], v[22:23] op_sel_hi:[1,0]
	v_pk_mul_f32 v[198:199], v[198:199], v[22:23] op_sel_hi:[1,0]
	v_pk_mul_f32 v[200:201], v[200:201], v[22:23] op_sel_hi:[1,0]
	v_pk_mul_f32 v[202:203], v[202:203], v[22:23] op_sel_hi:[1,0]
	v_pk_mul_f32 v[204:205], v[204:205], v[22:23] op_sel_hi:[1,0]
	v_pk_mul_f32 v[206:207], v[206:207], v[22:23] op_sel_hi:[1,0]
	v_pk_mul_f32 v[208:209], v[208:209], v[22:23] op_sel_hi:[1,0]
	v_pk_mul_f32 v[210:211], v[210:211], v[22:23] op_sel_hi:[1,0]
	v_pk_mul_f32 v[196:197], v[24:25], v[196:197]
	v_pk_mul_f32 v[198:199], v[26:27], v[198:199]
	v_pk_mul_f32 v[200:201], v[28:29], v[200:201]
	v_pk_mul_f32 v[202:203], v[30:31], v[202:203]
	v_pk_mul_f32 v[204:205], v[32:33], v[204:205]
	v_pk_mul_f32 v[206:207], v[34:35], v[206:207]
	v_pk_mul_f32 v[208:209], v[36:37], v[208:209]
	v_pk_mul_f32 v[210:211], v[38:39], v[210:211]
	v_pk_fma_f32 v[196:197], v[40:41], v[196:197], v[80:81]
	v_pk_fma_f32 v[198:199], v[42:43], v[198:199], v[82:83]
	v_pk_fma_f32 v[200:201], v[64:65], v[200:201], v[84:85]
	v_pk_fma_f32 v[202:203], v[66:67], v[202:203], v[86:87]
	v_pk_fma_f32 v[204:205], v[68:69], v[204:205], v[88:89]
	v_pk_fma_f32 v[206:207], v[70:71], v[206:207], v[90:91]
	v_pk_fma_f32 v[208:209], v[72:73], v[208:209], v[92:93]
	v_pk_fma_f32 v[210:211], v[74:75], v[210:211], v[94:95]
	v_cvt_pk_bf16_f32 v196, v196, v197
	v_cvt_pk_bf16_f32 v197, v198, v199
	v_cvt_pk_bf16_f32 v200, v200, v201
	v_cvt_pk_bf16_f32 v201, v202, v203
	v_cvt_pk_bf16_f32 v204, v204, v205
	v_cvt_pk_bf16_f32 v205, v206, v207
	v_cvt_pk_bf16_f32 v208, v208, v209
	v_cvt_pk_bf16_f32 v209, v210, v211
	global_store_dwordx2 v2, v[196:197], s[10:11] sc1
	global_store_dwordx2 v2, v[200:201], s[10:11] offset:512 sc1
	global_store_dwordx2 v2, v[204:205], s[10:11] offset:1024 sc1
	global_store_dwordx2 v2, v[208:209], s[10:11] offset:1536 sc1
	s_add_u32 s10, s10, 0x800
	s_addc_u32 s11, s11, 0
	v_pk_mul_f32 v[212:213], v[212:213], v[62:63] op_sel_hi:[1,0]
	v_pk_mul_f32 v[214:215], v[214:215], v[62:63] op_sel_hi:[1,0]
	v_pk_mul_f32 v[216:217], v[216:217], v[62:63] op_sel_hi:[1,0]
	v_pk_mul_f32 v[218:219], v[218:219], v[62:63] op_sel_hi:[1,0]
	v_pk_mul_f32 v[220:221], v[220:221], v[62:63] op_sel_hi:[1,0]
	v_pk_mul_f32 v[222:223], v[222:223], v[62:63] op_sel_hi:[1,0]
	v_pk_mul_f32 v[224:225], v[224:225], v[62:63] op_sel_hi:[1,0]
	v_pk_mul_f32 v[226:227], v[226:227], v[62:63] op_sel_hi:[1,0]
	v_pk_mul_f32 v[212:213], v[24:25], v[212:213]
	v_pk_mul_f32 v[214:215], v[26:27], v[214:215]
	v_pk_mul_f32 v[216:217], v[28:29], v[216:217]
	v_pk_mul_f32 v[218:219], v[30:31], v[218:219]
	v_pk_mul_f32 v[220:221], v[32:33], v[220:221]
	v_pk_mul_f32 v[222:223], v[34:35], v[222:223]
	v_pk_mul_f32 v[224:225], v[36:37], v[224:225]
	v_pk_mul_f32 v[226:227], v[38:39], v[226:227]
	v_pk_fma_f32 v[212:213], v[40:41], v[212:213], v[80:81]
	v_pk_fma_f32 v[214:215], v[42:43], v[214:215], v[82:83]
	v_pk_fma_f32 v[216:217], v[64:65], v[216:217], v[84:85]
	v_pk_fma_f32 v[218:219], v[66:67], v[218:219], v[86:87]
	v_pk_fma_f32 v[220:221], v[68:69], v[220:221], v[88:89]
	v_pk_fma_f32 v[222:223], v[70:71], v[222:223], v[90:91]
	v_pk_fma_f32 v[224:225], v[72:73], v[224:225], v[92:93]
	v_pk_fma_f32 v[226:227], v[74:75], v[226:227], v[94:95]
	v_cvt_pk_bf16_f32 v212, v212, v213
	v_cvt_pk_bf16_f32 v213, v214, v215
	v_cvt_pk_bf16_f32 v216, v216, v217
	v_cvt_pk_bf16_f32 v217, v218, v219
	v_cvt_pk_bf16_f32 v220, v220, v221
	v_cvt_pk_bf16_f32 v221, v222, v223
	v_cvt_pk_bf16_f32 v224, v224, v225
	v_cvt_pk_bf16_f32 v225, v226, v227
	global_store_dwordx2 v2, v[212:213], s[10:11] sc1
	global_store_dwordx2 v2, v[216:217], s[10:11] offset:512 sc1
	global_store_dwordx2 v2, v[220:221], s[10:11] offset:1024 sc1
	global_store_dwordx2 v2, v[224:225], s[10:11] offset:1536 sc1
	s_add_u32 s10, s10, 0x800
	s_addc_u32 s11, s11, 0
	global_load_dwordx4 v[164:167], v1, s[8:9]
	global_load_dwordx4 v[168:171], v1, s[8:9] offset:1024
	global_load_dwordx4 v[172:175], v1, s[8:9] offset:2048
	global_load_dwordx4 v[176:179], v1, s[8:9] offset:3072
	s_add_u32 s8, s8, 0x1000
	s_addc_u32 s9, s9, 0
	global_load_dwordx4 v[180:183], v1, s[8:9]
	global_load_dwordx4 v[184:187], v1, s[8:9] offset:1024
	global_load_dwordx4 v[188:191], v1, s[8:9] offset:2048
	global_load_dwordx4 v[192:195], v1, s[8:9] offset:3072
	s_add_u32 s8, s8, 0x1000
	s_addc_u32 s9, s9, 0
	global_load_dwordx4 v[196:199], v1, s[8:9]
	global_load_dwordx4 v[200:203], v1, s[8:9] offset:1024
	global_load_dwordx4 v[204:207], v1, s[8:9] offset:2048
	global_load_dwordx4 v[208:211], v1, s[8:9] offset:3072
	s_add_u32 s8, s8, 0x1000
	s_addc_u32 s9, s9, 0
	global_load_dwordx4 v[212:215], v1, s[8:9]
	global_load_dwordx4 v[216:219], v1, s[8:9] offset:1024
	global_load_dwordx4 v[220:223], v1, s[8:9] offset:2048
	global_load_dwordx4 v[224:227], v1, s[8:9] offset:3072
	s_add_u32 s8, s8, 0x1000
	s_addc_u32 s9, s9, 0
	s_waitcnt vmcnt(32)
; DI unsigned pk2(float lo, float hi) { return f2bf(lo) | (f2bf(hi) << 16); }
; DI void norm_phase(const Args& A, int wave_s, int l, int which, int rows) {
;     ...
;             float ss = 0.f;
; #pragma unroll
;             for (int j = 0; j < 4; ++j) ss += (xv[rr][j].x * xv[rr][j].x + xv[rr][j].y * xv[rr][j].y) + (xv[rr][j].z * xv[rr][j].z + xv[rr][j].w * xv[rr][j].w);
;             ss = wave_sum(C.lane, ss);
;             const float rs = rsqrtf(ss * (1.f / 1024.f) + EPS);
; #pragma unroll
;             for (int j = 0; j < 4; ++j) { const int col = 4 * (C.lane + 64 * j);
;                 const f32x4 y = xv[rr][j] * rs * g[j] * (sc[j] + 1.f) + sh[j];
;                 v2u o; o.x = pk2(y.x, y.y); o.y = pk2(y.z, y.w);
;                 *(v2u*)(C.H + (size_t)m * 1024 + col) = o; }
	v_mul_f32_e32 v10, v96, v96
	v_fmac_f32_e32 v10, v97, v97
	v_fmac_f32_e32 v10, v98, v98
	v_fmac_f32_e32 v10, v99, v99
	v_fmac_f32_e32 v10, v100, v100
	v_fmac_f32_e32 v10, v101, v101
	v_fmac_f32_e32 v10, v102, v102
	v_fmac_f32_e32 v10, v103, v103
	v_fmac_f32_e32 v10, v104, v104
	v_fmac_f32_e32 v10, v105, v105
	v_fmac_f32_e32 v10, v106, v106
	v_fmac_f32_e32 v10, v107, v107
	v_fmac_f32_e32 v10, v108, v108
	v_fmac_f32_e32 v10, v109, v109
	v_fmac_f32_e32 v10, v110, v110
	v_fmac_f32_e32 v10, v111, v111
	v_mul_f32_e32 v11, v112, v112
	v_fmac_f32_e32 v11, v113, v113
	v_fmac_f32_e32 v11, v114, v114
	v_fmac_f32_e32 v11, v115, v115
	v_fmac_f32_e32 v11, v116, v116
	v_fmac_f32_e32 v11, v117, v117
	v_fmac_f32_e32 v11, v118, v118
	v_fmac_f32_e32 v11, v119, v119
	v_fmac_f32_e32 v11, v120, v120
	v_fmac_f32_e32 v11, v121, v121
	v_fmac_f32_e32 v11, v122, v122
	v_fmac_f32_e32 v11, v123, v123
	v_fmac_f32_e32 v11, v124, v124
	v_fmac_f32_e32 v11, v125, v125
	v_fmac_f32_e32 v11, v126, v126
	v_fmac_f32_e32 v11, v127, v127
	v_mul_f32_e32 v12, v128, v128
	v_fmac_f32_e32 v12, v129, v129
	v_fmac_f32_e32 v12, v130, v130
	v_fmac_f32_e32 v12, v131, v131
	v_fmac_f32_e32 v12, v132, v132
	v_fmac_f32_e32 v12, v133, v133
	v_fmac_f32_e32 v12, v134, v134
	v_fmac_f32_e32 v12, v135, v135
	v_fmac_f32_e32 v12, v136, v136
	v_fmac_f32_e32 v12, v137, v137
	v_fmac_f32_e32 v12, v138, v138
	v_fmac_f32_e32 v12, v139, v139
	v_fmac_f32_e32 v12, v140, v140
	v_fmac_f32_e32 v12, v141, v141
	v_fmac_f32_e32 v12, v142, v142
	v_fmac_f32_e32 v12, v143, v143
	v_mul_f32_e32 v13, v144, v144
	v_fmac_f32_e32 v13, v145, v145
	v_fmac_f32_e32 v13, v146, v146
	v_fmac_f32_e32 v13, v147, v147
	v_fmac_f32_e32 v13, v148, v148
	v_fmac_f32_e32 v13, v149, v149
	v_fmac_f32_e32 v13, v150, v150
	v_fmac_f32_e32 v13, v151, v151
	v_fmac_f32_e32 v13, v152, v152
	v_fmac_f32_e32 v13, v153, v153
	v_fmac_f32_e32 v13, v154, v154
	v_fmac_f32_e32 v13, v155, v155
	v_fmac_f32_e32 v13, v156, v156
	v_fmac_f32_e32 v13, v157, v157
	v_fmac_f32_e32 v13, v158, v158
	v_fmac_f32_e32 v13, v159, v159
	ds_bpermute_b32 v14, v4, v10
	ds_bpermute_b32 v15, v4, v11
	ds_bpermute_b32 v16, v4, v12
	ds_bpermute_b32 v17, v4, v13
	s_waitcnt lgkmcnt(0)
	v_add_f32_e32 v10, v10, v14
	v_add_f32_e32 v11, v11, v15
	v_add_f32_e32 v12, v12, v16
	v_add_f32_e32 v13, v13, v17
	ds_bpermute_b32 v14, v5, v10
	ds_bpermute_b32 v15, v5, v11
	ds_bpermute_b32 v16, v5, v12
	ds_bpermute_b32 v17, v5, v13
	s_waitcnt lgkmcnt(0)
	v_add_f32_e32 v10, v10, v14
	v_add_f32_e32 v11, v11, v15
	v_add_f32_e32 v12, v12, v16
	v_add_f32_e32 v13, v13, v17
	ds_bpermute_b32 v14, v6, v10
	ds_bpermute_b32 v15, v6, v11
	ds_bpermute_b32 v16, v6, v12
	ds_bpermute_b32 v17, v6, v13
	s_waitcnt lgkmcnt(0)
	v_add_f32_e32 v10, v10, v14
	v_add_f32_e32 v11, v11, v15
	v_add_f32_e32 v12, v12, v16
	v_add_f32_e32 v13, v13, v17
	ds_bpermute_b32 v14, v7, v10
	ds_bpermute_b32 v15, v7, v11
	ds_bpermute_b32 v16, v7, v12
	ds_bpermute_b32 v17, v7, v13
	s_waitcnt lgkmcnt(0)
	v_add_f32_e32 v10, v10, v14
	v_add_f32_e32 v11, v11, v15
	v_add_f32_e32 v12, v12, v16
	v_add_f32_e32 v13, v13, v17
	ds_bpermute_b32 v14, v8, v10
	ds_bpermute_b32 v15, v8, v11
	ds_bpermute_b32 v16, v8, v12
	ds_bpermute_b32 v17, v8, v13
	s_waitcnt lgkmcnt(0)
	v_add_f32_e32 v10, v10, v14
	v_add_f32_e32 v11, v11, v15
	v_add_f32_e32 v12, v12, v16
	v_add_f32_e32 v13, v13, v17
	ds_bpermute_b32 v14, v9, v10
	ds_bpermute_b32 v15, v9, v11
	ds_bpermute_b32 v16, v9, v12
	ds_bpermute_b32 v17, v9, v13
	s_waitcnt lgkmcnt(0)
	v_add_f32_e32 v10, v10, v14
	v_add_f32_e32 v11, v11, v15
	v_add_f32_e32 v12, v12, v16
	v_add_f32_e32 v13, v13, v17
	v_fma_f32 v10, v10, s32, v60
	v_fma_f32 v11, v11, s32, v60
	v_fma_f32 v12, v12, s32, v60
	v_fma_f32 v13, v13, s32, v60
	v_rsq_f32_e32 v18, v10
	v_rsq_f32_e32 v20, v11
	v_rsq_f32_e32 v22, v12
	v_rsq_f32_e32 v62, v13
	s_nop 0
	v_pk_mul_f32 v[96:97], v[96:97], v[18:19] op_sel_hi:[1,0]
	v_pk_mul_f32 v[98:99], v[98:99], v[18:19] op_sel_hi:[1,0]
	v_pk_mul_f32 v[100:101], v[100:101], v[18:19] op_sel_hi:[1,0]
	v_pk_mul_f32 v[102:103], v[102:103], v[18:19] op_sel_hi:[1,0]
	v_pk_mul_f32 v[104:105], v[104:105], v[18:19] op_sel_hi:[1,0]
	v_pk_mul_f32 v[106:107], v[106:107], v[18:19] op_sel_hi:[1,0]
	v_pk_mul_f32 v[108:109], v[108:109], v[18:19] op_sel_hi:[1,0]
	v_pk_mul_f32 v[110:111], v[110:111], v[18:19] op_sel_hi:[1,0]
	v_pk_mul_f32 v[96:97], v[24:25], v[96:97]
	v_pk_mul_f32 v[98:99], v[26:27], v[98:99]
	v_pk_mul_f32 v[100:101], v[28:29], v[100:101]
	v_pk_mul_f32 v[102:103], v[30:31], v[102:103]
	v_pk_mul_f32 v[104:105], v[32:33], v[104:105]
	v_pk_mul_f32 v[106:107], v[34:35], v[106:107]
	v_pk_mul_f32 v[108:109], v[36:37], v[108:109]
	v_pk_mul_f32 v[110:111], v[38:39], v[110:111]
	v_pk_fma_f32 v[96:97], v[40:41], v[96:97], v[80:81]
	v_pk_fma_f32 v[98:99], v[42:43], v[98:99], v[82:83]
	v_pk_fma_f32 v[100:101], v[64:65], v[100:101], v[84:85]
	v_pk_fma_f32 v[102:103], v[66:67], v[102:103], v[86:87]
	v_pk_fma_f32 v[104:105], v[68:69], v[104:105], v[88:89]
	v_pk_fma_f32 v[106:107], v[70:71], v[106:107], v[90:91]
	v_pk_fma_f32 v[108:109], v[72:73], v[108:109], v[92:93]
	v_pk_fma_f32 v[110:111], v[74:75], v[110:111], v[94:95]
	v_cvt_pk_bf16_f32 v96, v96, v97
	v_cvt_pk_bf16_f32 v97, v98, v99
	v_cvt_pk_bf16_f32 v100, v100, v101
	v_cvt_pk_bf16_f32 v101, v102, v103
	v_cvt_pk_bf16_f32 v104, v104, v105
	v_cvt_pk_bf16_f32 v105, v106, v107
	v_cvt_pk_bf16_f32 v108, v108, v109
	v_cvt_pk_bf16_f32 v109, v110, v111
	global_store_dwordx2 v2, v[96:97], s[10:11] sc1
	global_store_dwordx2 v2, v[100:101], s[10:11] offset:512 sc1
	global_store_dwordx2 v2, v[104:105], s[10:11] offset:1024 sc1
	global_store_dwordx2 v2, v[108:109], s[10:11] offset:1536 sc1
; DI unsigned pk2(float lo, float hi) { return f2bf(lo) | (f2bf(hi) << 16); }
; DI void norm_phase(const Args& A, int wave_s, int l, int which, int rows) {
;     ...
;             const int m = m0 + rr; const float* xr; int v;
;             if (m < NLAT) { xr = (from_in ? C.x : C.out) + (size_t)m * 1024; v = m >> 13; }
;             else { xr = (from_in ? C.ctx : C.XC) + (size_t)(m - NLAT) * 1024; v = 4; }
;             modp[rr] = C.SM + SM_MOD + (l * 5 + v) * 6144 + (which == 1 ? 0 : 3072);
; #pragma unroll
;             for (int j = 0; j < 4; ++j) xv[rr][j] = ((const f32x4*)xr)[C.lane + 64 * j];
;     ...
; #pragma unroll
;             for (int j = 0; j < 4; ++j) { const int col = 4 * (C.lane + 64 * j);
;                 const f32x4 y = xv[rr][j] * rs * g[j] * (sc[j] + 1.f) + sh[j];
;                 v2u o; o.x = pk2(y.x, y.y); o.y = pk2(y.z, y.w);
;                 *(v2u*)(C.H + (size_t)m * 1024 + col) = o; }
	s_add_u32 s10, s10, 0x800
	s_addc_u32 s11, s11, 0
	v_pk_mul_f32 v[112:113], v[112:113], v[20:21] op_sel_hi:[1,0]
	v_pk_mul_f32 v[114:115], v[114:115], v[20:21] op_sel_hi:[1,0]
	v_pk_mul_f32 v[116:117], v[116:117], v[20:21] op_sel_hi:[1,0]
	v_pk_mul_f32 v[118:119], v[118:119], v[20:21] op_sel_hi:[1,0]
	v_pk_mul_f32 v[120:121], v[120:121], v[20:21] op_sel_hi:[1,0]
	v_pk_mul_f32 v[122:123], v[122:123], v[20:21] op_sel_hi:[1,0]
	v_pk_mul_f32 v[124:125], v[124:125], v[20:21] op_sel_hi:[1,0]
	v_pk_mul_f32 v[126:127], v[126:127], v[20:21] op_sel_hi:[1,0]
	v_pk_mul_f32 v[112:113], v[24:25], v[112:113]
	v_pk_mul_f32 v[114:115], v[26:27], v[114:115]
	v_pk_mul_f32 v[116:117], v[28:29], v[116:117]
	v_pk_mul_f32 v[118:119], v[30:31], v[118:119]
	v_pk_mul_f32 v[120:121], v[32:33], v[120:121]
	v_pk_mul_f32 v[122:123], v[34:35], v[122:123]
	v_pk_mul_f32 v[124:125], v[36:37], v[124:125]
	v_pk_mul_f32 v[126:127], v[38:39], v[126:127]
	v_pk_fma_f32 v[112:113], v[40:41], v[112:113], v[80:81]
	v_pk_fma_f32 v[114:115], v[42:43], v[114:115], v[82:83]
	v_pk_fma_f32 v[116:117], v[64:65], v[116:117], v[84:85]
	v_pk_fma_f32 v[118:119], v[66:67], v[118:119], v[86:87]
	v_pk_fma_f32 v[120:121], v[68:69], v[120:121], v[88:89]
	v_pk_fma_f32 v[122:123], v[70:71], v[122:123], v[90:91]
	v_pk_fma_f32 v[124:125], v[72:73], v[124:125], v[92:93]
	v_pk_fma_f32 v[126:127], v[74:75], v[126:127], v[94:95]
	v_cvt_pk_bf16_f32 v112, v112, v113
	v_cvt_pk_bf16_f32 v113, v114, v115
	v_cvt_pk_bf16_f32 v116, v116, v117
	v_cvt_pk_bf16_f32 v117, v118, v119
	v_cvt_pk_bf16_f32 v120, v120, v121
	v_cvt_pk_bf16_f32 v121, v122, v123
	v_cvt_pk_bf16_f32 v124, v124, v125
	v_cvt_pk_bf16_f32 v125, v126, v127
	global_store_dwordx2 v2, v[112:113], s[10:11] sc1
	global_store_dwordx2 v2, v[116:117], s[10:11] offset:512 sc1
	global_store_dwordx2 v2, v[120:121], s[10:11] offset:1024 sc1
	global_store_dwordx2 v2, v[124:125], s[10:11] offset:1536 sc1
	s_add_u32 s10, s10, 0x800
	s_addc_u32 s11, s11, 0
	v_pk_mul_f32 v[128:129], v[128:129], v[22:23] op_sel_hi:[1,0]
	v_pk_mul_f32 v[130:131], v[130:131], v[22:23] op_sel_hi:[1,0]
	v_pk_mul_f32 v[132:133], v[132:133], v[22:23] op_sel_hi:[1,0]
	v_pk_mul_f32 v[134:135], v[134:135], v[22:23] op_sel_hi:[1,0]
	v_pk_mul_f32 v[136:137], v[136:137], v[22:23] op_sel_hi:[1,0]
	v_pk_mul_f32 v[138:139], v[138:139], v[22:23] op_sel_hi:[1,0]
	v_pk_mul_f32 v[140:141], v[140:141], v[22:23] op_sel_hi:[1,0]
	v_pk_mul_f32 v[142:143], v[142:143], v[22:23] op_sel_hi:[1,0]
	v_pk_mul_f32 v[128:129], v[24:25], v[128:129]
	v_pk_mul_f32 v[130:131], v[26:27], v[130:131]
	v_pk_mul_f32 v[132:133], v[28:29], v[132:133]
	v_pk_mul_f32 v[134:135], v[30:31], v[134:135]
	v_pk_mul_f32 v[136:137], v[32:33], v[136:137]
	v_pk_mul_f32 v[138:139], v[34:35], v[138:139]
	v_pk_mul_f32 v[140:141], v[36:37], v[140:141]
	v_pk_mul_f32 v[142:143], v[38:39], v[142:143]
	v_pk_fma_f32 v[128:129], v[40:41], v[128:129], v[80:81]
	v_pk_fma_f32 v[130:131], v[42:43], v[130:131], v[82:83]
	v_pk_fma_f32 v[132:133], v[64:65], v[132:133], v[84:85]
	v_pk_fma_f32 v[134:135], v[66:67], v[134:135], v[86:87]
	v_pk_fma_f32 v[136:137], v[68:69], v[136:137], v[88:89]
	v_pk_fma_f32 v[138:139], v[70:71], v[138:139], v[90:91]
	v_pk_fma_f32 v[140:141], v[72:73], v[140:141], v[92:93]
	v_pk_fma_f32 v[142:143], v[74:75], v[142:143], v[94:95]
	v_cvt_pk_bf16_f32 v128, v128, v129
	v_cvt_pk_bf16_f32 v129, v130, v131
	v_cvt_pk_bf16_f32 v132, v132, v133
	v_cvt_pk_bf16_f32 v133, v134, v135
	v_cvt_pk_bf16_f32 v136, v136, v137
	v_cvt_pk_bf16_f32 v137, v138, v139
	v_cvt_pk_bf16_f32 v140, v140, v141
	v_cvt_pk_bf16_f32 v141, v142, v143
	global_store_dwordx2 v2, v[128:129], s[10:11] sc1
	global_store_dwordx2 v2, v[132:133], s[10:11] offset:512 sc1
	global_store_dwordx2 v2, v[136:137], s[10:11] offset:1024 sc1
	global_store_dwordx2 v2, v[140:141], s[10:11] offset:1536 sc1
	s_add_u32 s10, s10, 0x800
	s_addc_u32 s11, s11, 0
	v_pk_mul_f32 v[144:145], v[144:145], v[62:63] op_sel_hi:[1,0]
	v_pk_mul_f32 v[146:147], v[146:147], v[62:63] op_sel_hi:[1,0]
	v_pk_mul_f32 v[148:149], v[148:149], v[62:63] op_sel_hi:[1,0]
	v_pk_mul_f32 v[150:151], v[150:151], v[62:63] op_sel_hi:[1,0]
	v_pk_mul_f32 v[152:153], v[152:153], v[62:63] op_sel_hi:[1,0]
	v_pk_mul_f32 v[154:155], v[154:155], v[62:63] op_sel_hi:[1,0]
	v_pk_mul_f32 v[156:157], v[156:157], v[62:63] op_sel_hi:[1,0]
	v_pk_mul_f32 v[158:159], v[158:159], v[62:63] op_sel_hi:[1,0]
	v_pk_mul_f32 v[144:145], v[24:25], v[144:145]
	v_pk_mul_f32 v[146:147], v[26:27], v[146:147]
	v_pk_mul_f32 v[148:149], v[28:29], v[148:149]
	v_pk_mul_f32 v[150:151], v[30:31], v[150:151]
	v_pk_mul_f32 v[152:153], v[32:33], v[152:153]
	v_pk_mul_f32 v[154:155], v[34:35], v[154:155]
	v_pk_mul_f32 v[156:157], v[36:37], v[156:157]
	v_pk_mul_f32 v[158:159], v[38:39], v[158:159]
	v_pk_fma_f32 v[144:145], v[40:41], v[144:145], v[80:81]
	v_pk_fma_f32 v[146:147], v[42:43], v[146:147], v[82:83]
	v_pk_fma_f32 v[148:149], v[64:65], v[148:149], v[84:85]
	v_pk_fma_f32 v[150:151], v[66:67], v[150:151], v[86:87]
	v_pk_fma_f32 v[152:153], v[68:69], v[152:153], v[88:89]
	v_pk_fma_f32 v[154:155], v[70:71], v[154:155], v[90:91]
	v_pk_fma_f32 v[156:157], v[72:73], v[156:157], v[92:93]
	v_pk_fma_f32 v[158:159], v[74:75], v[158:159], v[94:95]
	v_cvt_pk_bf16_f32 v144, v144, v145
	v_cvt_pk_bf16_f32 v145, v146, v147
	v_cvt_pk_bf16_f32 v148, v148, v149
	v_cvt_pk_bf16_f32 v149, v150, v151
	v_cvt_pk_bf16_f32 v152, v152, v153
	v_cvt_pk_bf16_f32 v153, v154, v155
	v_cvt_pk_bf16_f32 v156, v156, v157
	v_cvt_pk_bf16_f32 v157, v158, v159
	global_store_dwordx2 v2, v[144:145], s[10:11] sc1
	global_store_dwordx2 v2, v[148:149], s[10:11] offset:512 sc1
	global_store_dwordx2 v2, v[152:153], s[10:11] offset:1024 sc1
	global_store_dwordx2 v2, v[156:157], s[10:11] offset:1536 sc1
	s_add_u32 s10, s10, 0x800
	s_addc_u32 s11, s11, 0
	s_mul_i32 s5, s6, 5
	s_add_u32 s5, s5, 4
	s_mul_i32 s5, s5, 0x6000
	s_add_u32 s24, s88, 0x103000
	s_addc_u32 s25, s89, 0
	s_add_u32 s24, s24, s5
	s_addc_u32 s25, s25, 0
	s_add_u32 s26, s24, 0x1000
	s_addc_u32 s27, s25, 0
	global_load_dwordx4 v[96:99], v1, s[30:31]
	global_load_dwordx4 v[100:103], v1, s[30:31] offset:1024
	global_load_dwordx4 v[104:107], v1, s[30:31] offset:2048
	global_load_dwordx4 v[108:111], v1, s[30:31] offset:3072
	global_load_dwordx4 v[112:115], v1, s[26:27]
	global_load_dwordx4 v[116:119], v1, s[26:27] offset:1024
	global_load_dwordx4 v[120:123], v1, s[26:27] offset:2048
	global_load_dwordx4 v[124:127], v1, s[26:27] offset:3072
	global_load_dwordx4 v[128:131], v1, s[24:25]
	global_load_dwordx4 v[132:135], v1, s[24:25] offset:1024
	global_load_dwordx4 v[136:139], v1, s[24:25] offset:2048
	global_load_dwordx4 v[140:143], v1, s[24:25] offset:3072
	s_waitcnt vmcnt(28)
; DI unsigned pk2(float lo, float hi) { return f2bf(lo) | (f2bf(hi) << 16); }
; DI void norm_phase(const Args& A, int wave_s, int l, int which, int rows) {
;     ...
;             float ss = 0.f;
; #pragma unroll
;             for (int j = 0; j < 4; ++j) ss += (xv[rr][j].x * xv[rr][j].x + xv[rr][j].y * xv[rr][j].y) + (xv[rr][j].z * xv[rr][j].z + xv[rr][j].w * xv[rr][j].w);
;             ss = wave_sum(C.lane, ss);
;             const float rs = rsqrtf(ss * (1.f / 1024.f) + EPS);
; #pragma unroll
;             for (int j = 0; j < 4; ++j) { const int col = 4 * (C.lane + 64 * j);
;                 const f32x4 y = xv[rr][j] * rs * g[j] * (sc[j] + 1.f) + sh[j];
;                 v2u o; o.x = pk2(y.x, y.y); o.y = pk2(y.z, y.w);
;                 *(v2u*)(C.H + (size_t)m * 1024 + col) = o; }
	v_mul_f32_e32 v10, v164, v164
	v_fmac_f32_e32 v10, v165, v165
	v_fmac_f32_e32 v10, v166, v166
	v_fmac_f32_e32 v10, v167, v167
	v_fmac_f32_e32 v10, v168, v168
	v_fmac_f32_e32 v10, v169, v169
	v_fmac_f32_e32 v10, v170, v170
	v_fmac_f32_e32 v10, v171, v171
	v_fmac_f32_e32 v10, v172, v172
	v_fmac_f32_e32 v10, v173, v173
	v_fmac_f32_e32 v10, v174, v174
	v_fmac_f32_e32 v10, v175, v175
	v_fmac_f32_e32 v10, v176, v176
	v_fmac_f32_e32 v10, v177, v177
	v_fmac_f32_e32 v10, v178, v178
	v_fmac_f32_e32 v10, v179, v179
	v_mul_f32_e32 v11, v180, v180
	v_fmac_f32_e32 v11, v181, v181
	v_fmac_f32_e32 v11, v182, v182
	v_fmac_f32_e32 v11, v183, v183
	v_fmac_f32_e32 v11, v184, v184
	v_fmac_f32_e32 v11, v185, v185
	v_fmac_f32_e32 v11, v186, v186
	v_fmac_f32_e32 v11, v187, v187
	v_fmac_f32_e32 v11, v188, v188
	v_fmac_f32_e32 v11, v189, v189
	v_fmac_f32_e32 v11, v190, v190
	v_fmac_f32_e32 v11, v191, v191
	v_fmac_f32_e32 v11, v192, v192
	v_fmac_f32_e32 v11, v193, v193
	v_fmac_f32_e32 v11, v194, v194
	v_fmac_f32_e32 v11, v195, v195
	v_mul_f32_e32 v12, v196, v196
	v_fmac_f32_e32 v12, v197, v197
	v_fmac_f32_e32 v12, v198, v198
	v_fmac_f32_e32 v12, v199, v199
	v_fmac_f32_e32 v12, v200, v200
	v_fmac_f32_e32 v12, v201, v201
	v_fmac_f32_e32 v12, v202, v202
	v_fmac_f32_e32 v12, v203, v203
	v_fmac_f32_e32 v12, v204, v204
	v_fmac_f32_e32 v12, v205, v205
	v_fmac_f32_e32 v12, v206, v206
	v_fmac_f32_e32 v12, v207, v207
	v_fmac_f32_e32 v12, v208, v208
	v_fmac_f32_e32 v12, v209, v209
	v_fmac_f32_e32 v12, v210, v210
	v_fmac_f32_e32 v12, v211, v211
	v_mul_f32_e32 v13, v212, v212
	v_fmac_f32_e32 v13, v213, v213
	v_fmac_f32_e32 v13, v214, v214
	v_fmac_f32_e32 v13, v215, v215
	v_fmac_f32_e32 v13, v216, v216
	v_fmac_f32_e32 v13, v217, v217
	v_fmac_f32_e32 v13, v218, v218
	v_fmac_f32_e32 v13, v219, v219
	v_fmac_f32_e32 v13, v220, v220
	v_fmac_f32_e32 v13, v221, v221
	v_fmac_f32_e32 v13, v222, v222
	v_fmac_f32_e32 v13, v223, v223
	v_fmac_f32_e32 v13, v224, v224
	v_fmac_f32_e32 v13, v225, v225
	v_fmac_f32_e32 v13, v226, v226
	v_fmac_f32_e32 v13, v227, v227
	ds_bpermute_b32 v14, v4, v10
	ds_bpermute_b32 v15, v4, v11
	ds_bpermute_b32 v16, v4, v12
	ds_bpermute_b32 v17, v4, v13
	s_waitcnt lgkmcnt(0)
	v_add_f32_e32 v10, v10, v14
	v_add_f32_e32 v11, v11, v15
	v_add_f32_e32 v12, v12, v16
	v_add_f32_e32 v13, v13, v17
	ds_bpermute_b32 v14, v5, v10
	ds_bpermute_b32 v15, v5, v11
	ds_bpermute_b32 v16, v5, v12
	ds_bpermute_b32 v17, v5, v13
	s_waitcnt lgkmcnt(0)
	v_add_f32_e32 v10, v10, v14
	v_add_f32_e32 v11, v11, v15
	v_add_f32_e32 v12, v12, v16
	v_add_f32_e32 v13, v13, v17
	ds_bpermute_b32 v14, v6, v10
	ds_bpermute_b32 v15, v6, v11
	ds_bpermute_b32 v16, v6, v12
	ds_bpermute_b32 v17, v6, v13
	s_waitcnt lgkmcnt(0)
	v_add_f32_e32 v10, v10, v14
	v_add_f32_e32 v11, v11, v15
	v_add_f32_e32 v12, v12, v16
	v_add_f32_e32 v13, v13, v17
	ds_bpermute_b32 v14, v7, v10
	ds_bpermute_b32 v15, v7, v11
	ds_bpermute_b32 v16, v7, v12
	ds_bpermute_b32 v17, v7, v13
	s_waitcnt lgkmcnt(0)
	v_add_f32_e32 v10, v10, v14
	v_add_f32_e32 v11, v11, v15
	v_add_f32_e32 v12, v12, v16
	v_add_f32_e32 v13, v13, v17
	ds_bpermute_b32 v14, v8, v10
	ds_bpermute_b32 v15, v8, v11
	ds_bpermute_b32 v16, v8, v12
	ds_bpermute_b32 v17, v8, v13
	s_waitcnt lgkmcnt(0)
	v_add_f32_e32 v10, v10, v14
	v_add_f32_e32 v11, v11, v15
	v_add_f32_e32 v12, v12, v16
	v_add_f32_e32 v13, v13, v17
	ds_bpermute_b32 v14, v9, v10
	ds_bpermute_b32 v15, v9, v11
	ds_bpermute_b32 v16, v9, v12
	ds_bpermute_b32 v17, v9, v13
	s_waitcnt lgkmcnt(0)
	v_add_f32_e32 v10, v10, v14
	v_add_f32_e32 v11, v11, v15
	v_add_f32_e32 v12, v12, v16
	v_add_f32_e32 v13, v13, v17
	v_fma_f32 v10, v10, s32, v60
	v_fma_f32 v11, v11, s32, v60
	v_fma_f32 v12, v12, s32, v60
	v_fma_f32 v13, v13, s32, v60
	v_rsq_f32_e32 v18, v10
	v_rsq_f32_e32 v20, v11
	v_rsq_f32_e32 v22, v12
	v_rsq_f32_e32 v62, v13
	s_nop 0
	v_pk_mul_f32 v[164:165], v[164:165], v[18:19] op_sel_hi:[1,0]
	v_pk_mul_f32 v[166:167], v[166:167], v[18:19] op_sel_hi:[1,0]
	v_pk_mul_f32 v[168:169], v[168:169], v[18:19] op_sel_hi:[1,0]
	v_pk_mul_f32 v[170:171], v[170:171], v[18:19] op_sel_hi:[1,0]
	v_pk_mul_f32 v[172:173], v[172:173], v[18:19] op_sel_hi:[1,0]
	v_pk_mul_f32 v[174:175], v[174:175], v[18:19] op_sel_hi:[1,0]
	v_pk_mul_f32 v[176:177], v[176:177], v[18:19] op_sel_hi:[1,0]
	v_pk_mul_f32 v[178:179], v[178:179], v[18:19] op_sel_hi:[1,0]
	v_pk_mul_f32 v[164:165], v[24:25], v[164:165]
	v_pk_mul_f32 v[166:167], v[26:27], v[166:167]
	v_pk_mul_f32 v[168:169], v[28:29], v[168:169]
	v_pk_mul_f32 v[170:171], v[30:31], v[170:171]
	v_pk_mul_f32 v[172:173], v[32:33], v[172:173]
	v_pk_mul_f32 v[174:175], v[34:35], v[174:175]
	v_pk_mul_f32 v[176:177], v[36:37], v[176:177]
	v_pk_mul_f32 v[178:179], v[38:39], v[178:179]
	v_pk_fma_f32 v[164:165], v[40:41], v[164:165], v[80:81]
	v_pk_fma_f32 v[166:167], v[42:43], v[166:167], v[82:83]
	v_pk_fma_f32 v[168:169], v[64:65], v[168:169], v[84:85]
	v_pk_fma_f32 v[170:171], v[66:67], v[170:171], v[86:87]
	v_pk_fma_f32 v[172:173], v[68:69], v[172:173], v[88:89]
	v_pk_fma_f32 v[174:175], v[70:71], v[174:175], v[90:91]
	v_pk_fma_f32 v[176:177], v[72:73], v[176:177], v[92:93]
	v_pk_fma_f32 v[178:179], v[74:75], v[178:179], v[94:95]
	v_cvt_pk_bf16_f32 v164, v164, v165
	v_cvt_pk_bf16_f32 v165, v166, v167
	v_cvt_pk_bf16_f32 v168, v168, v169
	v_cvt_pk_bf16_f32 v169, v170, v171
	v_cvt_pk_bf16_f32 v172, v172, v173
	v_cvt_pk_bf16_f32 v173, v174, v175
	v_cvt_pk_bf16_f32 v176, v176, v177
	v_cvt_pk_bf16_f32 v177, v178, v179
	global_store_dwordx2 v2, v[164:165], s[10:11] sc1
	global_store_dwordx2 v2, v[168:169], s[10:11] offset:512 sc1
	global_store_dwordx2 v2, v[172:173], s[10:11] offset:1024 sc1
; DI unsigned pk2(float lo, float hi) { return f2bf(lo) | (f2bf(hi) << 16); }
; DI void norm_phase(const Args& A, int wave_s, int l, int which, int rows) {
;     ...
; #pragma unroll
;             for (int j = 0; j < 4; ++j) { const int col = 4 * (C.lane + 64 * j);
;                 const f32x4 y = xv[rr][j] * rs * g[j] * (sc[j] + 1.f) + sh[j];
;                 v2u o; o.x = pk2(y.x, y.y); o.y = pk2(y.z, y.w);
;                 *(v2u*)(C.H + (size_t)m * 1024 + col) = o; }
	global_store_dwordx2 v2, v[176:177], s[10:11] offset:1536 sc1
	s_add_u32 s10, s10, 0x800
	s_addc_u32 s11, s11, 0
	v_pk_mul_f32 v[180:181], v[180:181], v[20:21] op_sel_hi:[1,0]
	v_pk_mul_f32 v[182:183], v[182:183], v[20:21] op_sel_hi:[1,0]
	v_pk_mul_f32 v[184:185], v[184:185], v[20:21] op_sel_hi:[1,0]
	v_pk_mul_f32 v[186:187], v[186:187], v[20:21] op_sel_hi:[1,0]
	v_pk_mul_f32 v[188:189], v[188:189], v[20:21] op_sel_hi:[1,0]
	v_pk_mul_f32 v[190:191], v[190:191], v[20:21] op_sel_hi:[1,0]
	v_pk_mul_f32 v[192:193], v[192:193], v[20:21] op_sel_hi:[1,0]
	v_pk_mul_f32 v[194:195], v[194:195], v[20:21] op_sel_hi:[1,0]
	v_pk_mul_f32 v[180:181], v[24:25], v[180:181]
	v_pk_mul_f32 v[182:183], v[26:27], v[182:183]
	v_pk_mul_f32 v[184:185], v[28:29], v[184:185]
	v_pk_mul_f32 v[186:187], v[30:31], v[186:187]
	v_pk_mul_f32 v[188:189], v[32:33], v[188:189]
	v_pk_mul_f32 v[190:191], v[34:35], v[190:191]
	v_pk_mul_f32 v[192:193], v[36:37], v[192:193]
	v_pk_mul_f32 v[194:195], v[38:39], v[194:195]
	v_pk_fma_f32 v[180:181], v[40:41], v[180:181], v[80:81]
	v_pk_fma_f32 v[182:183], v[42:43], v[182:183], v[82:83]
	v_pk_fma_f32 v[184:185], v[64:65], v[184:185], v[84:85]
	v_pk_fma_f32 v[186:187], v[66:67], v[186:187], v[86:87]
	v_pk_fma_f32 v[188:189], v[68:69], v[188:189], v[88:89]
	v_pk_fma_f32 v[190:191], v[70:71], v[190:191], v[90:91]
	v_pk_fma_f32 v[192:193], v[72:73], v[192:193], v[92:93]
	v_pk_fma_f32 v[194:195], v[74:75], v[194:195], v[94:95]
	v_cvt_pk_bf16_f32 v180, v180, v181
	v_cvt_pk_bf16_f32 v181, v182, v183
	v_cvt_pk_bf16_f32 v184, v184, v185
	v_cvt_pk_bf16_f32 v185, v186, v187
	v_cvt_pk_bf16_f32 v188, v188, v189
	v_cvt_pk_bf16_f32 v189, v190, v191
	v_cvt_pk_bf16_f32 v192, v192, v193
	v_cvt_pk_bf16_f32 v193, v194, v195
	global_store_dwordx2 v2, v[180:181], s[10:11] sc1
	global_store_dwordx2 v2, v[184:185], s[10:11] offset:512 sc1
	global_store_dwordx2 v2, v[188:189], s[10:11] offset:1024 sc1
	global_store_dwordx2 v2, v[192:193], s[10:11] offset:1536 sc1
	s_add_u32 s10, s10, 0x800
	s_addc_u32 s11, s11, 0
	v_pk_mul_f32 v[196:197], v[196:197], v[22:23] op_sel_hi:[1,0]
	v_pk_mul_f32 v[198:199], v[198:199], v[22:23] op_sel_hi:[1,0]
	v_pk_mul_f32 v[200:201], v[200:201], v[22:23] op_sel_hi:[1,0]
	v_pk_mul_f32 v[202:203], v[202:203], v[22:23] op_sel_hi:[1,0]
	v_pk_mul_f32 v[204:205], v[204:205], v[22:23] op_sel_hi:[1,0]
	v_pk_mul_f32 v[206:207], v[206:207], v[22:23] op_sel_hi:[1,0]
	v_pk_mul_f32 v[208:209], v[208:209], v[22:23] op_sel_hi:[1,0]
	v_pk_mul_f32 v[210:211], v[210:211], v[22:23] op_sel_hi:[1,0]
	v_pk_mul_f32 v[196:197], v[24:25], v[196:197]
	v_pk_mul_f32 v[198:199], v[26:27], v[198:199]
	v_pk_mul_f32 v[200:201], v[28:29], v[200:201]
	v_pk_mul_f32 v[202:203], v[30:31], v[202:203]
	v_pk_mul_f32 v[204:205], v[32:33], v[204:205]
	v_pk_mul_f32 v[206:207], v[34:35], v[206:207]
	v_pk_mul_f32 v[208:209], v[36:37], v[208:209]
	v_pk_mul_f32 v[210:211], v[38:39], v[210:211]
	v_pk_fma_f32 v[196:197], v[40:41], v[196:197], v[80:81]
	v_pk_fma_f32 v[198:199], v[42:43], v[198:199], v[82:83]
	v_pk_fma_f32 v[200:201], v[64:65], v[200:201], v[84:85]
	v_pk_fma_f32 v[202:203], v[66:67], v[202:203], v[86:87]
	v_pk_fma_f32 v[204:205], v[68:69], v[204:205], v[88:89]
	v_pk_fma_f32 v[206:207], v[70:71], v[206:207], v[90:91]
	v_pk_fma_f32 v[208:209], v[72:73], v[208:209], v[92:93]
	v_pk_fma_f32 v[210:211], v[74:75], v[210:211], v[94:95]
	v_cvt_pk_bf16_f32 v196, v196, v197
	v_cvt_pk_bf16_f32 v197, v198, v199
	v_cvt_pk_bf16_f32 v200, v200, v201
	v_cvt_pk_bf16_f32 v201, v202, v203
	v_cvt_pk_bf16_f32 v204, v204, v205
	v_cvt_pk_bf16_f32 v205, v206, v207
	v_cvt_pk_bf16_f32 v208, v208, v209
	v_cvt_pk_bf16_f32 v209, v210, v211
	global_store_dwordx2 v2, v[196:197], s[10:11] sc1
	global_store_dwordx2 v2, v[200:201], s[10:11] offset:512 sc1
	global_store_dwordx2 v2, v[204:205], s[10:11] offset:1024 sc1
	global_store_dwordx2 v2, v[208:209], s[10:11] offset:1536 sc1
	s_add_u32 s10, s10, 0x800
	s_addc_u32 s11, s11, 0
	v_pk_mul_f32 v[212:213], v[212:213], v[62:63] op_sel_hi:[1,0]
	v_pk_mul_f32 v[214:215], v[214:215], v[62:63] op_sel_hi:[1,0]
	v_pk_mul_f32 v[216:217], v[216:217], v[62:63] op_sel_hi:[1,0]
	v_pk_mul_f32 v[218:219], v[218:219], v[62:63] op_sel_hi:[1,0]
	v_pk_mul_f32 v[220:221], v[220:221], v[62:63] op_sel_hi:[1,0]
	v_pk_mul_f32 v[222:223], v[222:223], v[62:63] op_sel_hi:[1,0]
	v_pk_mul_f32 v[224:225], v[224:225], v[62:63] op_sel_hi:[1,0]
	v_pk_mul_f32 v[226:227], v[226:227], v[62:63] op_sel_hi:[1,0]
	v_pk_mul_f32 v[212:213], v[24:25], v[212:213]
	v_pk_mul_f32 v[214:215], v[26:27], v[214:215]
	v_pk_mul_f32 v[216:217], v[28:29], v[216:217]
	v_pk_mul_f32 v[218:219], v[30:31], v[218:219]
	v_pk_mul_f32 v[220:221], v[32:33], v[220:221]
	v_pk_mul_f32 v[222:223], v[34:35], v[222:223]
	v_pk_mul_f32 v[224:225], v[36:37], v[224:225]
	v_pk_mul_f32 v[226:227], v[38:39], v[226:227]
	v_pk_fma_f32 v[212:213], v[40:41], v[212:213], v[80:81]
	v_pk_fma_f32 v[214:215], v[42:43], v[214:215], v[82:83]
	v_pk_fma_f32 v[216:217], v[64:65], v[216:217], v[84:85]
	v_pk_fma_f32 v[218:219], v[66:67], v[218:219], v[86:87]
	v_pk_fma_f32 v[220:221], v[68:69], v[220:221], v[88:89]
	v_pk_fma_f32 v[222:223], v[70:71], v[222:223], v[90:91]
	v_pk_fma_f32 v[224:225], v[72:73], v[224:225], v[92:93]
	v_pk_fma_f32 v[226:227], v[74:75], v[226:227], v[94:95]
	v_cvt_pk_bf16_f32 v212, v212, v213
	v_cvt_pk_bf16_f32 v213, v214, v215
	v_cvt_pk_bf16_f32 v216, v216, v217
	v_cvt_pk_bf16_f32 v217, v218, v219
	v_cvt_pk_bf16_f32 v220, v220, v221
	v_cvt_pk_bf16_f32 v221, v222, v223
	v_cvt_pk_bf16_f32 v224, v224, v225
	v_cvt_pk_bf16_f32 v225, v226, v227
	global_store_dwordx2 v2, v[212:213], s[10:11] sc1
	global_store_dwordx2 v2, v[216:217], s[10:11] offset:512 sc1
	global_store_dwordx2 v2, v[220:221], s[10:11] offset:1024 sc1
	global_store_dwordx2 v2, v[224:225], s[10:11] offset:1536 sc1
	s_add_u32 s10, s10, 0x800
	s_addc_u32 s11, s11, 0
	s_add_u32 s10, s88, 0x3800000
	s_addc_u32 s11, s89, 0
	s_add_u32 s10, s10, 0x4000000
	s_addc_u32 s11, s11, 0
	s_lshl_b32 s5, s7, 11
	s_add_u32 s10, s10, s5
	s_addc_u32 s11, s11, 0
	s_waitcnt vmcnt(16)
	v_pk_add_f32 v[112:113], v[112:113], 1.0 op_sel_hi:[1,0]
	v_pk_add_f32 v[114:115], v[114:115], 1.0 op_sel_hi:[1,0]
	v_pk_add_f32 v[116:117], v[116:117], 1.0 op_sel_hi:[1,0]
	v_pk_add_f32 v[118:119], v[118:119], 1.0 op_sel_hi:[1,0]
	v_pk_add_f32 v[120:121], v[120:121], 1.0 op_sel_hi:[1,0]
	v_pk_add_f32 v[122:123], v[122:123], 1.0 op_sel_hi:[1,0]
	v_pk_add_f32 v[124:125], v[124:125], 1.0 op_sel_hi:[1,0]
	v_pk_add_f32 v[126:127], v[126:127], 1.0 op_sel_hi:[1,0]
	s_cmp_eq_u32 s2, 0
	s_cbranch_scc1 .Lnorm_n2_done
; DI unsigned pk2(float lo, float hi) { return f2bf(lo) | (f2bf(hi) << 16); }
; DI void norm_phase(const Args& A, int wave_s, int l, int which, int rows) {
;     ...
;             float ss = 0.f;
; #pragma unroll
;             for (int j = 0; j < 4; ++j) ss += (xv[rr][j].x * xv[rr][j].x + xv[rr][j].y * xv[rr][j].y) + (xv[rr][j].z * xv[rr][j].z + xv[rr][j].w * xv[rr][j].w);
;             ss = wave_sum(C.lane, ss);
;             const float rs = rsqrtf(ss * (1.f / 1024.f) + EPS);
; #pragma unroll
;             for (int j = 0; j < 4; ++j) { const int col = 4 * (C.lane + 64 * j);
;                 const f32x4 y = xv[rr][j] * rs * g[j] * (sc[j] + 1.f) + sh[j];
;                 v2u o; o.x = pk2(y.x, y.y); o.y = pk2(y.z, y.w);
;                 *(v2u*)(C.H + (size_t)m * 1024 + col) = o; }
	v_mul_f32_e32 v10, v96, v96
	v_fmac_f32_e32 v10, v97, v97
	v_fmac_f32_e32 v10, v98, v98
	v_fmac_f32_e32 v10, v99, v99
	v_fmac_f32_e32 v10, v100, v100
	v_fmac_f32_e32 v10, v101, v101
	v_fmac_f32_e32 v10, v102, v102
	v_fmac_f32_e32 v10, v103, v103
	v_fmac_f32_e32 v10, v104, v104
	v_fmac_f32_e32 v10, v105, v105
	v_fmac_f32_e32 v10, v106, v106
	v_fmac_f32_e32 v10, v107, v107
	v_fmac_f32_e32 v10, v108, v108
	v_fmac_f32_e32 v10, v109, v109
	v_fmac_f32_e32 v10, v110, v110
	v_fmac_f32_e32 v10, v111, v111
	ds_bpermute_b32 v14, v4, v10
	s_waitcnt lgkmcnt(0)
	v_add_f32_e32 v10, v10, v14
	ds_bpermute_b32 v14, v5, v10
	s_waitcnt lgkmcnt(0)
	v_add_f32_e32 v10, v10, v14
	ds_bpermute_b32 v14, v6, v10
	s_waitcnt lgkmcnt(0)
	v_add_f32_e32 v10, v10, v14
	ds_bpermute_b32 v14, v7, v10
	s_waitcnt lgkmcnt(0)
	v_add_f32_e32 v10, v10, v14
	ds_bpermute_b32 v14, v8, v10
	s_waitcnt lgkmcnt(0)
	v_add_f32_e32 v10, v10, v14
	ds_bpermute_b32 v14, v9, v10
	s_waitcnt lgkmcnt(0)
	v_add_f32_e32 v10, v10, v14
	v_fma_f32 v10, v10, s32, v60
	v_rsq_f32_e32 v18, v10
	s_nop 0
	v_pk_mul_f32 v[96:97], v[96:97], v[18:19] op_sel_hi:[1,0]
	v_pk_mul_f32 v[98:99], v[98:99], v[18:19] op_sel_hi:[1,0]
	v_pk_mul_f32 v[100:101], v[100:101], v[18:19] op_sel_hi:[1,0]
	v_pk_mul_f32 v[102:103], v[102:103], v[18:19] op_sel_hi:[1,0]
	v_pk_mul_f32 v[104:105], v[104:105], v[18:19] op_sel_hi:[1,0]
	v_pk_mul_f32 v[106:107], v[106:107], v[18:19] op_sel_hi:[1,0]
	v_pk_mul_f32 v[108:109], v[108:109], v[18:19] op_sel_hi:[1,0]
	v_pk_mul_f32 v[110:111], v[110:111], v[18:19] op_sel_hi:[1,0]
	v_pk_mul_f32 v[96:97], v[24:25], v[96:97]
	v_pk_mul_f32 v[98:99], v[26:27], v[98:99]
	v_pk_mul_f32 v[100:101], v[28:29], v[100:101]
	v_pk_mul_f32 v[102:103], v[30:31], v[102:103]
	v_pk_mul_f32 v[104:105], v[32:33], v[104:105]
	v_pk_mul_f32 v[106:107], v[34:35], v[106:107]
	v_pk_mul_f32 v[108:109], v[36:37], v[108:109]
	v_pk_mul_f32 v[110:111], v[38:39], v[110:111]
	v_pk_fma_f32 v[96:97], v[112:113], v[96:97], v[128:129]
	v_pk_fma_f32 v[98:99], v[114:115], v[98:99], v[130:131]
	v_pk_fma_f32 v[100:101], v[116:117], v[100:101], v[132:133]
	v_pk_fma_f32 v[102:103], v[118:119], v[102:103], v[134:135]
	v_pk_fma_f32 v[104:105], v[120:121], v[104:105], v[136:137]
	v_pk_fma_f32 v[106:107], v[122:123], v[106:107], v[138:139]
	v_pk_fma_f32 v[108:109], v[124:125], v[108:109], v[140:141]
	v_pk_fma_f32 v[110:111], v[126:127], v[110:111], v[142:143]
	v_cvt_pk_bf16_f32 v96, v96, v97
	v_cvt_pk_bf16_f32 v97, v98, v99
	v_cvt_pk_bf16_f32 v100, v100, v101
	v_cvt_pk_bf16_f32 v101, v102, v103
	v_cvt_pk_bf16_f32 v104, v104, v105
	v_cvt_pk_bf16_f32 v105, v106, v107
	v_cvt_pk_bf16_f32 v108, v108, v109
	v_cvt_pk_bf16_f32 v109, v110, v111
	global_store_dwordx2 v2, v[96:97], s[10:11] sc1
	global_store_dwordx2 v2, v[100:101], s[10:11] offset:512 sc1
	global_store_dwordx2 v2, v[104:105], s[10:11] offset:1024 sc1
	global_store_dwordx2 v2, v[108:109], s[10:11] offset:1536 sc1

; DI void ffn_fixup_phase(const Args& A, int wave_s, int l, int rows) {
;     const Ctx C = make_ctx(A, wave_s);
;     const float* cw = C.conv_w + (size_t)l * 3 * 5632; const float* cb = C.conv_b + (size_t)l * 5632;
;     const bf16* UB = C.ACT;
;     bf16* ACTF = C.U;
;     const int nkb = rows / 64, total = nkb * 2 * 352;
;     for (int e = blockIdx.x * 512 + C.tid; e < total; e += gridDim.x * 512) {
;         const int c8 = (e % 352) * 8, rs = e / 352, side = rs & 1, kb = rs >> 1;
;         const int R = kb * 64 + (side ? 63 : 0);
;         bool first, last;
;         if (R < NLAT) { first = (R & 8191) == 0; last = (R & 8191) == 8191; } else { first = ((R - NLAT) & 255) == 0; last = ((R - NLAT) & 255) == 255; }
;         const v4u z = {0u, 0u, 0u, 0u};
;         const bf16* pp = side ? UB + (size_t)((kb * 4 + 2) * 2) * 2816 : UB + (size_t)(((kb - 1) * 4 + 3) * 2) * 2816;
;         const bf16* pc = UB + (size_t)((kb * 4 + (side ? 3 : 0)) * 2) * 2816;
;         const bf16* pn = side ? UB + (size_t)(((kb + 1) * 4 + 0) * 2) * 2816 : UB + (size_t)((kb * 4 + 1) * 2) * 2816;
;         const bool zp = (!side) && first, zn = side && last;
;         const v4u a0 = zp ? z : *(const v4u*)(pp + c8), a1 = *(const v4u*)(pc + c8), a2 = zn ? z : *(const v4u*)(pn + c8);
;         const v4u b0 = zp ? z : *(const v4u*)(pp + 2816 + c8), b1 = *(const v4u*)(pc + 2816 + c8), b2 = zn ? z : *(const v4u*)(pn + 2816 + c8);
.LBB0_696:
	s_or_b64 exec, exec, s[4:5]
	s_lshr_b32 s2, s42, 5
	v_readlane_b32 s4, v253, 37
	s_waitcnt lgkmcnt(0)
	s_barrier
	v_mbcnt_lo_u32_b32 v0, -1, 0
	v_mbcnt_hi_u32_b32 v0, -1, v0
	v_mbcnt_lo_u32_b32 v0, -1, 0
	v_mbcnt_hi_u32_b32 v0, -1, v0
	v_readlane_b32 s6, v255, 32
	s_lshr_b32 s5, s94, 6
	s_lshl_b32 s7, s65, 3
	s_add_u32 s5, s5, s7
	s_cmp_ge_u32 s5, 2046
	s_cbranch_scc1 .Lfix_f_done
	s_lshr_b32 s6, s6, 10
	s_lshl_b32 s7, s5, 6
	v_add_u32_e32 v224, s7, v0
	v_mov_b32_e32 v225, 0xba2e8c
	v_mul_hi_u32 v225, v224, v225
	v_mov_b32_e32 v226, 0x160
	v_mul_lo_u32 v226, v225, v226
	v_sub_u32_e32 v226, v224, v226
	v_lshlrev_b32_e32 v227, 4, v226
	v_readlane_b32 s8, v252, 25
	v_readlane_b32 s9, v252, 26
	v_readlane_b32 s24, v252, 27
	v_readlane_b32 s25, v252, 28
	s_mul_i32 s7, s6, 0x10800
	s_nop 0
	s_add_u32 s8, s8, s7
	s_addc_u32 s9, s9, 0
	s_mul_i32 s7, s6, 0x5800
	s_add_u32 s24, s24, s7
	s_addc_u32 s25, s25, 0
	v_lshlrev_b32_e32 v228, 5, v226
	s_add_u32 s26, s8, 0x0
	s_addc_u32 s27, s9, 0
	global_load_dwordx4 v[4:7], v228, s[26:27]
	global_load_dwordx4 v[8:11], v228, s[26:27] offset:16
	s_add_u32 s26, s8, 0x5800
	s_addc_u32 s27, s9, 0
	global_load_dwordx4 v[12:15], v228, s[26:27]
	global_load_dwordx4 v[24:27], v228, s[26:27] offset:16
	s_add_u32 s26, s8, 0xb000
	s_addc_u32 s27, s9, 0
	global_load_dwordx4 v[28:31], v228, s[26:27]
	global_load_dwordx4 v[32:35], v228, s[26:27] offset:16
	s_add_u32 s26, s8, 0x2c00
	s_addc_u32 s27, s9, 0
	global_load_dwordx4 v[64:67], v228, s[26:27]
	global_load_dwordx4 v[68:71], v228, s[26:27] offset:16
	s_add_u32 s26, s8, 0x8400
	s_addc_u32 s27, s9, 0
	global_load_dwordx4 v[72:75], v228, s[26:27]
	global_load_dwordx4 v[80:83], v228, s[26:27] offset:16
	s_add_u32 s26, s8, 0xdc00
	s_addc_u32 s27, s9, 0
	global_load_dwordx4 v[84:87], v228, s[26:27]
	global_load_dwordx4 v[88:91], v228, s[26:27] offset:16
	s_add_u32 s26, s24, 0x0
	s_addc_u32 s27, s25, 0
	global_load_dwordx4 v[36:39], v228, s[26:27]
	global_load_dwordx4 v[40:43], v228, s[26:27] offset:16
	s_add_u32 s26, s24, 0x2c00
	s_addc_u32 s27, s25, 0
	global_load_dwordx4 v[92:95], v228, s[26:27]
	global_load_dwordx4 v[96:99], v228, s[26:27] offset:16
	s_add_u32 s28, s88, 0x171fd400
	s_addc_u32 s29, s89, 0
	s_add_u32 s30, s88, 0xbc00000
	s_addc_u32 s31, s89, 0
	v_mov_b32_e32 v229, v225
	v_and_b32_e32 v184, 1, v229
	v_lshrrev_b32_e32 v185, 1, v229
	v_lshlrev_b32_e32 v185, 2, v185
	v_mad_u32_u24 v185, v184, 3, v185
	v_mov_b32_e32 v184, 0x2c00
	v_mul_lo_u32 v185, v185, v184
	v_add_u32_e32 v185, v185, v227
	v_mov_b32_e32 v177, 0
	v_mov_b32_e32 v176, v185
	v_lshl_add_u64 v[176:177], v[176:177], 0, s[28:29]
	global_load_dwordx4 v[100:103], v[176:177], off
	s_mov_b64 s[26:27], 5632
	v_lshl_add_u64 v[178:179], v[176:177], 0, s[26:27]
	global_load_dwordx4 v[104:107], v[178:179], off
	s_mov_b64 s[26:27], 11264
	v_lshl_add_u64 v[178:179], v[176:177], 0, s[26:27]
	global_load_dwordx4 v[108:111], v[178:179], off
	s_mov_b64 s[26:27], 16896
	v_lshl_add_u64 v[178:179], v[176:177], 0, s[26:27]
	global_load_dwordx4 v[112:115], v[178:179], off
	s_mov_b64 s[26:27], 22528
	v_lshl_add_u64 v[178:179], v[176:177], 0, s[26:27]
	global_load_dwordx4 v[116:119], v[178:179], off
	s_mov_b64 s[26:27], 28160
	v_lshl_add_u64 v[178:179], v[176:177], 0, s[26:27]
	global_load_dwordx4 v[120:123], v[178:179], off
	v_add_u32_e32 v230, 372, v225
	v_and_b32_e32 v184, 1, v230
	v_lshrrev_b32_e32 v185, 1, v230
	v_lshlrev_b32_e32 v185, 2, v185
	v_mad_u32_u24 v185, v184, 3, v185
	v_mov_b32_e32 v184, 0x2c00
	v_mul_lo_u32 v185, v185, v184
	v_add_u32_e32 v185, v185, v227
	v_mov_b32_e32 v177, 0
	v_mov_b32_e32 v176, v185
	v_lshl_add_u64 v[176:177], v[176:177], 0, s[28:29]
	global_load_dwordx4 v[124:127], v[176:177], off
	s_mov_b64 s[26:27], 5632
	v_lshl_add_u64 v[178:179], v[176:177], 0, s[26:27]
	global_load_dwordx4 v[128:131], v[178:179], off
	s_mov_b64 s[26:27], 11264
	v_lshl_add_u64 v[178:179], v[176:177], 0, s[26:27]
	global_load_dwordx4 v[132:135], v[178:179], off
	s_mov_b64 s[26:27], 16896
	v_lshl_add_u64 v[178:179], v[176:177], 0, s[26:27]
	global_load_dwordx4 v[136:139], v[178:179], off
	s_mov_b64 s[26:27], 22528
	v_lshl_add_u64 v[178:179], v[176:177], 0, s[26:27]
	global_load_dwordx4 v[140:143], v[178:179], off
	s_mov_b64 s[26:27], 28160
	v_lshl_add_u64 v[178:179], v[176:177], 0, s[26:27]
	global_load_dwordx4 v[144:147], v[178:179], off
	v_add_u32_e32 v231, 744, v225
	v_and_b32_e32 v184, 1, v231
	v_lshrrev_b32_e32 v185, 1, v231
	v_lshlrev_b32_e32 v185, 2, v185
	v_mad_u32_u24 v185, v184, 3, v185
	v_mov_b32_e32 v184, 0x2c00
	v_mul_lo_u32 v185, v185, v184
	v_add_u32_e32 v185, v185, v227
	v_mov_b32_e32 v177, 0
	v_mov_b32_e32 v176, v185
	v_lshl_add_u64 v[176:177], v[176:177], 0, s[28:29]
	global_load_dwordx4 v[148:151], v[176:177], off
	s_mov_b64 s[26:27], 5632
	v_lshl_add_u64 v[178:179], v[176:177], 0, s[26:27]
	global_load_dwordx4 v[152:155], v[178:179], off
	s_mov_b64 s[26:27], 11264
	v_lshl_add_u64 v[178:179], v[176:177], 0, s[26:27]
	global_load_dwordx4 v[156:159], v[178:179], off
	s_mov_b64 s[26:27], 16896
	v_lshl_add_u64 v[178:179], v[176:177], 0, s[26:27]
	global_load_dwordx4 v[164:167], v[178:179], off
	s_mov_b64 s[26:27], 22528
	v_lshl_add_u64 v[178:179], v[176:177], 0, s[26:27]
	global_load_dwordx4 v[168:171], v[178:179], off
	s_mov_b64 s[26:27], 28160
	v_lshl_add_u64 v[178:179], v[176:177], 0, s[26:27]
	global_load_dwordx4 v[172:175], v[178:179], off
	s_mul_i32 s7, s42, 11
	s_mov_b32 s10, 0x7fff
	s_mov_b32 s11, 0xffff0000
	s_waitcnt vmcnt(12)
; DI float silu_f(float x) { return x / (1.f + __expf(-x)); }
; DI void ffn_fixup_phase(const Args& A, int wave_s, int l, int rows) {
;     ...
;         const int R = kb * 64 + (side ? 63 : 0);
;         bool first, last;
;         if (R < NLAT) { first = (R & 8191) == 0; last = (R & 8191) == 8191; } else { first = ((R - NLAT) & 255) == 0; last = ((R - NLAT) & 255) == 255; }
;         const v4u z = {0u, 0u, 0u, 0u};
;         const bf16* pp = side ? UB + (size_t)((kb * 4 + 2) * 2) * 2816 : UB + (size_t)(((kb - 1) * 4 + 3) * 2) * 2816;
;         const bf16* pc = UB + (size_t)((kb * 4 + (side ? 3 : 0)) * 2) * 2816;
;         const bf16* pn = side ? UB + (size_t)(((kb + 1) * 4 + 0) * 2) * 2816 : UB + (size_t)((kb * 4 + 1) * 2) * 2816;
;         const bool zp = (!side) && first, zn = side && last;
;         const v4u a0 = zp ? z : *(const v4u*)(pp + c8), a1 = *(const v4u*)(pc + c8), a2 = zn ? z : *(const v4u*)(pn + c8);
;         const v4u b0 = zp ? z : *(const v4u*)(pp + 2816 + c8), b1 = *(const v4u*)(pc + 2816 + c8), b2 = zn ? z : *(const v4u*)(pn + 2816 + c8);
;         unsigned res[4];
; #pragma unroll
;         for (int q = 0; q < 4; ++q) {
;             float r2[2];
; #pragma unroll
;             for (int hlf = 0; hlf < 2; ++hlf) {
;                 const int i = c8 + 2 * q + hlf;
;                 const float ua0 = hlf ? __builtin_bit_cast(float, a0[q] & 0xffff0000u) : __builtin_bit_cast(float, a0[q] << 16);
;                 const float ua1 = hlf ? __builtin_bit_cast(float, a1[q] & 0xffff0000u) : __builtin_bit_cast(float, a1[q] << 16);
;                 const float ua2 = hlf ? __builtin_bit_cast(float, a2[q] & 0xffff0000u) : __builtin_bit_cast(float, a2[q] << 16);
;                 const float ub0 = hlf ? __builtin_bit_cast(float, b0[q] & 0xffff0000u) : __builtin_bit_cast(float, b0[q] << 16);
;                 const float ub1 = hlf ? __builtin_bit_cast(float, b1[q] & 0xffff0000u) : __builtin_bit_cast(float, b1[q] << 16);
;                 const float ub2 = hlf ? __builtin_bit_cast(float, b2[q] & 0xffff0000u) : __builtin_bit_cast(float, b2[q] << 16);
;                 const float ya = cb[i] + ua0 * cw[i] + ua1 * cw[5632 + i] + ua2 * cw[2 * 5632 + i];
;                 const float yv = cb[2816 + i] + ub0 * cw[2816 + i] + ub1 * cw[5632 + 2816 + i] + ub2 * cw[2 * 5632 + 2816 + i];
;                 r2[hlf] = silu_f(ya) * yv;
	v_and_b32_e32 v188, 1, v229
	v_lshrrev_b32_e32 v190, 1, v229
	v_lshlrev_b32_e32 v190, 6, v190
	v_mad_u32_u24 v190, v188, 63, v190
	v_mov_b32_e32 v191, 0xff
	v_mov_b32_e32 v189, 0x1fff
	v_cmp_gt_u32_e32 vcc, 0x8000, v190
	s_nop 1
	v_cndmask_b32_e32 v191, v191, v189, vcc
	v_and_b32_e32 v189, v190, v191
	v_or_b32_e32 v192, v189, v188
	v_cmp_eq_u32_e32 vcc, 0, v192
	s_nop 1
	v_cndmask_b32_e64 v100, v100, 0, vcc
	v_cndmask_b32_e64 v101, v101, 0, vcc
	v_cndmask_b32_e64 v102, v102, 0, vcc
	v_cndmask_b32_e64 v103, v103, 0, vcc
	v_cndmask_b32_e64 v104, v104, 0, vcc
	v_cndmask_b32_e64 v105, v105, 0, vcc
	v_cndmask_b32_e64 v106, v106, 0, vcc
	v_cndmask_b32_e64 v107, v107, 0, vcc
	v_cmp_eq_u32_e64 s[26:27], v189, v191
	v_cmp_eq_u32_e32 vcc, 1, v188
	s_nop 1
	s_and_b64 vcc, vcc, s[26:27]
	s_nop 1
	v_cndmask_b32_e64 v116, v116, 0, vcc
	v_cndmask_b32_e64 v117, v117, 0, vcc
	v_cndmask_b32_e64 v118, v118, 0, vcc
	v_cndmask_b32_e64 v119, v119, 0, vcc
	v_cndmask_b32_e64 v120, v120, 0, vcc
	v_cndmask_b32_e64 v121, v121, 0, vcc
	v_cndmask_b32_e64 v122, v122, 0, vcc
	v_cndmask_b32_e64 v123, v123, 0, vcc
	v_lshlrev_b32_e32 v204, 16, v100
	v_lshlrev_b32_e32 v205, 16, v108
	v_lshlrev_b32_e32 v206, 16, v116
	v_fma_f32 v200, v4, v204, v36
	v_fma_f32 v200, v12, v205, v200
	v_fma_f32 v200, v28, v206, v200
	v_lshlrev_b32_e32 v204, 16, v104
	v_lshlrev_b32_e32 v205, 16, v112
	v_lshlrev_b32_e32 v206, 16, v120
	v_fma_f32 v201, v64, v204, v92
	v_fma_f32 v201, v72, v205, v201
	v_fma_f32 v201, v84, v206, v201
	v_mul_f32_e32 v208, 0xbfb8aa3b, v200
	v_exp_f32_e32 v208, v208
	s_nop 0
	v_add_f32_e32 v209, 1.0, v208
	v_div_scale_f32 v210, s[26:27], v209, v209, v200
	v_rcp_f32_e32 v211, v210
	s_nop 0
	v_fma_f32 v212, -v210, v211, 1.0
	v_fmac_f32_e32 v211, v212, v211
	v_div_scale_f32 v213, vcc, v200, v209, v200
	v_mul_f32_e32 v214, v213, v211
	v_fma_f32 v215, -v210, v214, v213
	v_fmac_f32_e32 v214, v215, v211
	v_fma_f32 v210, -v210, v214, v213
	v_div_fmas_f32 v210, v210, v211, v214
	v_div_fixup_f32 v210, v210, v209, v200
	v_mul_f32_e32 v216, v210, v201
	v_and_b32_e32 v204, 0xffff0000, v100
	v_and_b32_e32 v205, 0xffff0000, v108
	v_and_b32_e32 v206, 0xffff0000, v116
	v_fma_f32 v200, v5, v204, v37
	v_fma_f32 v200, v13, v205, v200
	v_fma_f32 v200, v29, v206, v200
	v_and_b32_e32 v204, 0xffff0000, v104
	v_and_b32_e32 v205, 0xffff0000, v112
	v_and_b32_e32 v206, 0xffff0000, v120
	v_fma_f32 v201, v65, v204, v93
	v_fma_f32 v201, v73, v205, v201
	v_fma_f32 v201, v85, v206, v201
	v_mul_f32_e32 v208, 0xbfb8aa3b, v200
	v_exp_f32_e32 v208, v208
	s_nop 0
	v_add_f32_e32 v209, 1.0, v208
	v_div_scale_f32 v210, s[26:27], v209, v209, v200
	v_rcp_f32_e32 v211, v210
	s_nop 0
	v_fma_f32 v212, -v210, v211, 1.0
	v_fmac_f32_e32 v211, v212, v211
	v_div_scale_f32 v213, vcc, v200, v209, v200
	v_mul_f32_e32 v214, v213, v211
	v_fma_f32 v215, -v210, v214, v213
	v_fmac_f32_e32 v214, v215, v211
	v_fma_f32 v210, -v210, v214, v213
	v_div_fmas_f32 v210, v210, v211, v214
	v_div_fixup_f32 v210, v210, v209, v200
	v_mul_f32_e32 v217, v210, v201
	v_bfe_u32 v220, v216, 16, 1
	v_bfe_u32 v221, v217, 16, 1
	v_add3_u32 v220, v216, v220, s10
	v_add3_u32 v221, v217, v221, s10
	v_lshrrev_b32_e32 v220, 16, v220
	v_and_or_b32 v196, v221, s11, v220
	v_lshlrev_b32_e32 v204, 16, v101
	v_lshlrev_b32_e32 v205, 16, v109
	v_lshlrev_b32_e32 v206, 16, v117
	v_fma_f32 v200, v6, v204, v38
	v_fma_f32 v200, v14, v205, v200
	v_fma_f32 v200, v30, v206, v200
	v_lshlrev_b32_e32 v204, 16, v105
	v_lshlrev_b32_e32 v205, 16, v113
	v_lshlrev_b32_e32 v206, 16, v121
	v_fma_f32 v201, v66, v204, v94
	v_fma_f32 v201, v74, v205, v201
	v_fma_f32 v201, v86, v206, v201
	v_mul_f32_e32 v208, 0xbfb8aa3b, v200
	v_exp_f32_e32 v208, v208
	s_nop 0
	v_add_f32_e32 v209, 1.0, v208
	v_div_scale_f32 v210, s[26:27], v209, v209, v200
	v_rcp_f32_e32 v211, v210
	s_nop 0
	v_fma_f32 v212, -v210, v211, 1.0
	v_fmac_f32_e32 v211, v212, v211
	v_div_scale_f32 v213, vcc, v200, v209, v200
	v_mul_f32_e32 v214, v213, v211
	v_fma_f32 v215, -v210, v214, v213
	v_fmac_f32_e32 v214, v215, v211
	v_fma_f32 v210, -v210, v214, v213
	v_div_fmas_f32 v210, v210, v211, v214
	v_div_fixup_f32 v210, v210, v209, v200
	v_mul_f32_e32 v216, v210, v201
	v_and_b32_e32 v204, 0xffff0000, v101
	v_and_b32_e32 v205, 0xffff0000, v109
	v_and_b32_e32 v206, 0xffff0000, v117
	v_fma_f32 v200, v7, v204, v39
	v_fma_f32 v200, v15, v205, v200
	v_fma_f32 v200, v31, v206, v200
	v_and_b32_e32 v204, 0xffff0000, v105
	v_and_b32_e32 v205, 0xffff0000, v113
	v_and_b32_e32 v206, 0xffff0000, v121
	v_fma_f32 v201, v67, v204, v95
	v_fma_f32 v201, v75, v205, v201
	v_fma_f32 v201, v87, v206, v201
	v_mul_f32_e32 v208, 0xbfb8aa3b, v200
	v_exp_f32_e32 v208, v208
	s_nop 0
	v_add_f32_e32 v209, 1.0, v208
	v_div_scale_f32 v210, s[26:27], v209, v209, v200
	v_rcp_f32_e32 v211, v210
	s_nop 0
	v_fma_f32 v212, -v210, v211, 1.0
	v_fmac_f32_e32 v211, v212, v211
	v_div_scale_f32 v213, vcc, v200, v209, v200
	v_mul_f32_e32 v214, v213, v211
	v_fma_f32 v215, -v210, v214, v213
	v_fmac_f32_e32 v214, v215, v211
	v_fma_f32 v210, -v210, v214, v213
	v_div_fmas_f32 v210, v210, v211, v214
	v_div_fixup_f32 v210, v210, v209, v200
	v_mul_f32_e32 v217, v210, v201
	v_bfe_u32 v220, v216, 16, 1
	v_bfe_u32 v221, v217, 16, 1
	v_add3_u32 v220, v216, v220, s10
	v_add3_u32 v221, v217, v221, s10
	v_lshrrev_b32_e32 v220, 16, v220
	v_and_or_b32 v197, v221, s11, v220
	v_lshlrev_b32_e32 v204, 16, v102
	v_lshlrev_b32_e32 v205, 16, v110
	v_lshlrev_b32_e32 v206, 16, v118
	v_fma_f32 v200, v8, v204, v40
	v_fma_f32 v200, v24, v205, v200
	v_fma_f32 v200, v32, v206, v200
	v_lshlrev_b32_e32 v204, 16, v106
	v_lshlrev_b32_e32 v205, 16, v114
	v_lshlrev_b32_e32 v206, 16, v122
; DI unsigned pk2(float lo, float hi) { return f2bf(lo) | (f2bf(hi) << 16); }
; DI float silu_f(float x) { return x / (1.f + __expf(-x)); }
; DI void ffn_fixup_phase(const Args& A, int wave_s, int l, int rows) {
;     ...
;             for (int hlf = 0; hlf < 2; ++hlf) {
;                 const int i = c8 + 2 * q + hlf;
;                 const float ua0 = hlf ? __builtin_bit_cast(float, a0[q] & 0xffff0000u) : __builtin_bit_cast(float, a0[q] << 16);
;                 const float ua1 = hlf ? __builtin_bit_cast(float, a1[q] & 0xffff0000u) : __builtin_bit_cast(float, a1[q] << 16);
;                 const float ua2 = hlf ? __builtin_bit_cast(float, a2[q] & 0xffff0000u) : __builtin_bit_cast(float, a2[q] << 16);
;                 const float ub0 = hlf ? __builtin_bit_cast(float, b0[q] & 0xffff0000u) : __builtin_bit_cast(float, b0[q] << 16);
;                 const float ub1 = hlf ? __builtin_bit_cast(float, b1[q] & 0xffff0000u) : __builtin_bit_cast(float, b1[q] << 16);
;                 const float ub2 = hlf ? __builtin_bit_cast(float, b2[q] & 0xffff0000u) : __builtin_bit_cast(float, b2[q] << 16);
;                 const float ya = cb[i] + ua0 * cw[i] + ua1 * cw[5632 + i] + ua2 * cw[2 * 5632 + i];
;                 const float yv = cb[2816 + i] + ub0 * cw[2816 + i] + ub1 * cw[5632 + 2816 + i] + ub2 * cw[2 * 5632 + 2816 + i];
;                 r2[hlf] = silu_f(ya) * yv;
;             }
;             res[q] = pk2(r2[0], r2[1]);
;         }
;         v4u o; o.x = res[0]; o.y = res[1]; o.z = res[2]; o.w = res[3];
;         *(v4u*)(ACTF + (size_t)R * 2816 + c8) = o;
	v_fma_f32 v201, v68, v204, v96
	v_fma_f32 v201, v80, v205, v201
	v_fma_f32 v201, v88, v206, v201
	v_mul_f32_e32 v208, 0xbfb8aa3b, v200
	v_exp_f32_e32 v208, v208
	s_nop 0
	v_add_f32_e32 v209, 1.0, v208
	v_div_scale_f32 v210, s[26:27], v209, v209, v200
	v_rcp_f32_e32 v211, v210
	s_nop 0
	v_fma_f32 v212, -v210, v211, 1.0
	v_fmac_f32_e32 v211, v212, v211
	v_div_scale_f32 v213, vcc, v200, v209, v200
	v_mul_f32_e32 v214, v213, v211
	v_fma_f32 v215, -v210, v214, v213
	v_fmac_f32_e32 v214, v215, v211
	v_fma_f32 v210, -v210, v214, v213
	v_div_fmas_f32 v210, v210, v211, v214
	v_div_fixup_f32 v210, v210, v209, v200
	v_mul_f32_e32 v216, v210, v201
	v_and_b32_e32 v204, 0xffff0000, v102
	v_and_b32_e32 v205, 0xffff0000, v110
	v_and_b32_e32 v206, 0xffff0000, v118
	v_fma_f32 v200, v9, v204, v41
	v_fma_f32 v200, v25, v205, v200
	v_fma_f32 v200, v33, v206, v200
	v_and_b32_e32 v204, 0xffff0000, v106
	v_and_b32_e32 v205, 0xffff0000, v114
	v_and_b32_e32 v206, 0xffff0000, v122
	v_fma_f32 v201, v69, v204, v97
	v_fma_f32 v201, v81, v205, v201
	v_fma_f32 v201, v89, v206, v201
	v_mul_f32_e32 v208, 0xbfb8aa3b, v200
	v_exp_f32_e32 v208, v208
	s_nop 0
	v_add_f32_e32 v209, 1.0, v208
	v_div_scale_f32 v210, s[26:27], v209, v209, v200
	v_rcp_f32_e32 v211, v210
	s_nop 0
	v_fma_f32 v212, -v210, v211, 1.0
	v_fmac_f32_e32 v211, v212, v211
	v_div_scale_f32 v213, vcc, v200, v209, v200
	v_mul_f32_e32 v214, v213, v211
	v_fma_f32 v215, -v210, v214, v213
	v_fmac_f32_e32 v214, v215, v211
	v_fma_f32 v210, -v210, v214, v213
	v_div_fmas_f32 v210, v210, v211, v214
	v_div_fixup_f32 v210, v210, v209, v200
	v_mul_f32_e32 v217, v210, v201
	v_bfe_u32 v220, v216, 16, 1
	v_bfe_u32 v221, v217, 16, 1
	v_add3_u32 v220, v216, v220, s10
	v_add3_u32 v221, v217, v221, s10
	v_lshrrev_b32_e32 v220, 16, v220
	v_and_or_b32 v198, v221, s11, v220
	v_lshlrev_b32_e32 v204, 16, v103
	v_lshlrev_b32_e32 v205, 16, v111
	v_lshlrev_b32_e32 v206, 16, v119
	v_fma_f32 v200, v10, v204, v42
	v_fma_f32 v200, v26, v205, v200
	v_fma_f32 v200, v34, v206, v200
	v_lshlrev_b32_e32 v204, 16, v107
	v_lshlrev_b32_e32 v205, 16, v115
	v_lshlrev_b32_e32 v206, 16, v123
	v_fma_f32 v201, v70, v204, v98
	v_fma_f32 v201, v82, v205, v201
	v_fma_f32 v201, v90, v206, v201
	v_mul_f32_e32 v208, 0xbfb8aa3b, v200
	v_exp_f32_e32 v208, v208
	s_nop 0
	v_add_f32_e32 v209, 1.0, v208
	v_div_scale_f32 v210, s[26:27], v209, v209, v200
	v_rcp_f32_e32 v211, v210
	s_nop 0
	v_fma_f32 v212, -v210, v211, 1.0
	v_fmac_f32_e32 v211, v212, v211
	v_div_scale_f32 v213, vcc, v200, v209, v200
	v_mul_f32_e32 v214, v213, v211
	v_fma_f32 v215, -v210, v214, v213
	v_fmac_f32_e32 v214, v215, v211
	v_fma_f32 v210, -v210, v214, v213
	v_div_fmas_f32 v210, v210, v211, v214
	v_div_fixup_f32 v210, v210, v209, v200
	v_mul_f32_e32 v216, v210, v201
	v_and_b32_e32 v204, 0xffff0000, v103
	v_and_b32_e32 v205, 0xffff0000, v111
	v_and_b32_e32 v206, 0xffff0000, v119
	v_fma_f32 v200, v11, v204, v43
	v_fma_f32 v200, v27, v205, v200
	v_fma_f32 v200, v35, v206, v200
	v_and_b32_e32 v204, 0xffff0000, v107
	v_and_b32_e32 v205, 0xffff0000, v115
	v_and_b32_e32 v206, 0xffff0000, v123
	v_fma_f32 v201, v71, v204, v99
	v_fma_f32 v201, v83, v205, v201
	v_fma_f32 v201, v91, v206, v201
	v_mul_f32_e32 v208, 0xbfb8aa3b, v200
	v_exp_f32_e32 v208, v208
	s_nop 0
	v_add_f32_e32 v209, 1.0, v208
	v_div_scale_f32 v210, s[26:27], v209, v209, v200
	v_rcp_f32_e32 v211, v210
	s_nop 0
	v_fma_f32 v212, -v210, v211, 1.0
	v_fmac_f32_e32 v211, v212, v211
	v_div_scale_f32 v213, vcc, v200, v209, v200
	v_mul_f32_e32 v214, v213, v211
	v_fma_f32 v215, -v210, v214, v213
	v_fmac_f32_e32 v214, v215, v211
	v_fma_f32 v210, -v210, v214, v213
	v_div_fmas_f32 v210, v210, v211, v214
	v_div_fixup_f32 v210, v210, v209, v200
	v_mul_f32_e32 v217, v210, v201
	v_bfe_u32 v220, v216, 16, 1
	v_bfe_u32 v221, v217, 16, 1
	v_add3_u32 v220, v216, v220, s10
	v_add3_u32 v221, v217, v221, s10
	v_lshrrev_b32_e32 v220, 16, v220
	v_and_or_b32 v199, v221, s11, v220
	v_mov_b32_e32 v192, v224
	v_cmp_gt_u32_e32 vcc, s7, v192
	v_mov_b32_e32 v193, 0x1600
	v_mul_lo_u32 v193, v190, v193
	v_add_u32_e32 v180, v193, v227
	v_mov_b32_e32 v181, 0
	v_lshl_add_u64 v[180:181], v[180:181], 0, s[30:31]
	s_and_saveexec_b64 s[26:27], vcc
	global_store_dwordx4 v[180:181], v[196:199], off sc1
	s_mov_b64 exec, s[26:27]
	s_nop 1
	s_waitcnt vmcnt(7)
; DI float silu_f(float x) { return x / (1.f + __expf(-x)); }
; DI void ffn_fixup_phase(const Args& A, int wave_s, int l, int rows) {
;     ...
;         const int R = kb * 64 + (side ? 63 : 0);
;         bool first, last;
;         if (R < NLAT) { first = (R & 8191) == 0; last = (R & 8191) == 8191; } else { first = ((R - NLAT) & 255) == 0; last = ((R - NLAT) & 255) == 255; }
;         const v4u z = {0u, 0u, 0u, 0u};
;         const bf16* pp = side ? UB + (size_t)((kb * 4 + 2) * 2) * 2816 : UB + (size_t)(((kb - 1) * 4 + 3) * 2) * 2816;
;         const bf16* pc = UB + (size_t)((kb * 4 + (side ? 3 : 0)) * 2) * 2816;
;         const bf16* pn = side ? UB + (size_t)(((kb + 1) * 4 + 0) * 2) * 2816 : UB + (size_t)((kb * 4 + 1) * 2) * 2816;
;         const bool zp = (!side) && first, zn = side && last;
;         const v4u a0 = zp ? z : *(const v4u*)(pp + c8), a1 = *(const v4u*)(pc + c8), a2 = zn ? z : *(const v4u*)(pn + c8);
;         const v4u b0 = zp ? z : *(const v4u*)(pp + 2816 + c8), b1 = *(const v4u*)(pc + 2816 + c8), b2 = zn ? z : *(const v4u*)(pn + 2816 + c8);
;         unsigned res[4];
; #pragma unroll
;         for (int q = 0; q < 4; ++q) {
;             float r2[2];
; #pragma unroll
;             for (int hlf = 0; hlf < 2; ++hlf) {
;                 const int i = c8 + 2 * q + hlf;
;                 const float ua0 = hlf ? __builtin_bit_cast(float, a0[q] & 0xffff0000u) : __builtin_bit_cast(float, a0[q] << 16);
;                 const float ua1 = hlf ? __builtin_bit_cast(float, a1[q] & 0xffff0000u) : __builtin_bit_cast(float, a1[q] << 16);
;                 const float ua2 = hlf ? __builtin_bit_cast(float, a2[q] & 0xffff0000u) : __builtin_bit_cast(float, a2[q] << 16);
;                 const float ub0 = hlf ? __builtin_bit_cast(float, b0[q] & 0xffff0000u) : __builtin_bit_cast(float, b0[q] << 16);
;                 const float ub1 = hlf ? __builtin_bit_cast(float, b1[q] & 0xffff0000u) : __builtin_bit_cast(float, b1[q] << 16);
;                 const float ub2 = hlf ? __builtin_bit_cast(float, b2[q] & 0xffff0000u) : __builtin_bit_cast(float, b2[q] << 16);
;                 const float ya = cb[i] + ua0 * cw[i] + ua1 * cw[5632 + i] + ua2 * cw[2 * 5632 + i];
;                 const float yv = cb[2816 + i] + ub0 * cw[2816 + i] + ub1 * cw[5632 + 2816 + i] + ub2 * cw[2 * 5632 + 2816 + i];
;                 r2[hlf] = silu_f(ya) * yv;
	v_and_b32_e32 v188, 1, v230
	v_lshrrev_b32_e32 v190, 1, v230
	v_lshlrev_b32_e32 v190, 6, v190
	v_mad_u32_u24 v190, v188, 63, v190
	v_mov_b32_e32 v191, 0xff
	v_mov_b32_e32 v189, 0x1fff
	v_cmp_gt_u32_e32 vcc, 0x8000, v190
	s_nop 1
	v_cndmask_b32_e32 v191, v191, v189, vcc
	v_and_b32_e32 v189, v190, v191
	v_or_b32_e32 v192, v189, v188
	v_cmp_eq_u32_e32 vcc, 0, v192
	s_nop 1
	v_cndmask_b32_e64 v124, v124, 0, vcc
	v_cndmask_b32_e64 v125, v125, 0, vcc
	v_cndmask_b32_e64 v126, v126, 0, vcc
	v_cndmask_b32_e64 v127, v127, 0, vcc
	v_cndmask_b32_e64 v128, v128, 0, vcc
	v_cndmask_b32_e64 v129, v129, 0, vcc
	v_cndmask_b32_e64 v130, v130, 0, vcc
	v_cndmask_b32_e64 v131, v131, 0, vcc
	v_cmp_eq_u32_e64 s[26:27], v189, v191
	v_cmp_eq_u32_e32 vcc, 1, v188
	s_nop 1
	s_and_b64 vcc, vcc, s[26:27]
	s_nop 1
	v_cndmask_b32_e64 v140, v140, 0, vcc
	v_cndmask_b32_e64 v141, v141, 0, vcc
	v_cndmask_b32_e64 v142, v142, 0, vcc
	v_cndmask_b32_e64 v143, v143, 0, vcc
	v_cndmask_b32_e64 v144, v144, 0, vcc
	v_cndmask_b32_e64 v145, v145, 0, vcc
	v_cndmask_b32_e64 v146, v146, 0, vcc
	v_cndmask_b32_e64 v147, v147, 0, vcc
	v_lshlrev_b32_e32 v204, 16, v124
	v_lshlrev_b32_e32 v205, 16, v132
	v_lshlrev_b32_e32 v206, 16, v140
	v_fma_f32 v200, v4, v204, v36
	v_fma_f32 v200, v12, v205, v200
	v_fma_f32 v200, v28, v206, v200
	v_lshlrev_b32_e32 v204, 16, v128
	v_lshlrev_b32_e32 v205, 16, v136
	v_lshlrev_b32_e32 v206, 16, v144
	v_fma_f32 v201, v64, v204, v92
	v_fma_f32 v201, v72, v205, v201
	v_fma_f32 v201, v84, v206, v201
	v_mul_f32_e32 v208, 0xbfb8aa3b, v200
	v_exp_f32_e32 v208, v208
	s_nop 0
	v_add_f32_e32 v209, 1.0, v208
	v_div_scale_f32 v210, s[26:27], v209, v209, v200
	v_rcp_f32_e32 v211, v210
	s_nop 0
	v_fma_f32 v212, -v210, v211, 1.0
	v_fmac_f32_e32 v211, v212, v211
	v_div_scale_f32 v213, vcc, v200, v209, v200
	v_mul_f32_e32 v214, v213, v211
	v_fma_f32 v215, -v210, v214, v213
	v_fmac_f32_e32 v214, v215, v211
	v_fma_f32 v210, -v210, v214, v213
	v_div_fmas_f32 v210, v210, v211, v214
	v_div_fixup_f32 v210, v210, v209, v200
	v_mul_f32_e32 v216, v210, v201
	v_and_b32_e32 v204, 0xffff0000, v124
	v_and_b32_e32 v205, 0xffff0000, v132
	v_and_b32_e32 v206, 0xffff0000, v140
	v_fma_f32 v200, v5, v204, v37
	v_fma_f32 v200, v13, v205, v200
	v_fma_f32 v200, v29, v206, v200
	v_and_b32_e32 v204, 0xffff0000, v128
	v_and_b32_e32 v205, 0xffff0000, v136
	v_and_b32_e32 v206, 0xffff0000, v144
	v_fma_f32 v201, v65, v204, v93
	v_fma_f32 v201, v73, v205, v201
	v_fma_f32 v201, v85, v206, v201
	v_mul_f32_e32 v208, 0xbfb8aa3b, v200
	v_exp_f32_e32 v208, v208
	s_nop 0
	v_add_f32_e32 v209, 1.0, v208
	v_div_scale_f32 v210, s[26:27], v209, v209, v200
	v_rcp_f32_e32 v211, v210
	s_nop 0
	v_fma_f32 v212, -v210, v211, 1.0
	v_fmac_f32_e32 v211, v212, v211
	v_div_scale_f32 v213, vcc, v200, v209, v200
	v_mul_f32_e32 v214, v213, v211
	v_fma_f32 v215, -v210, v214, v213
	v_fmac_f32_e32 v214, v215, v211
	v_fma_f32 v210, -v210, v214, v213
	v_div_fmas_f32 v210, v210, v211, v214
	v_div_fixup_f32 v210, v210, v209, v200
	v_mul_f32_e32 v217, v210, v201
	v_bfe_u32 v220, v216, 16, 1
	v_bfe_u32 v221, v217, 16, 1
	v_add3_u32 v220, v216, v220, s10
	v_add3_u32 v221, v217, v221, s10
	v_lshrrev_b32_e32 v220, 16, v220
	v_and_or_b32 v196, v221, s11, v220
	v_lshlrev_b32_e32 v204, 16, v125
	v_lshlrev_b32_e32 v205, 16, v133
	v_lshlrev_b32_e32 v206, 16, v141
	v_fma_f32 v200, v6, v204, v38
	v_fma_f32 v200, v14, v205, v200
	v_fma_f32 v200, v30, v206, v200
	v_lshlrev_b32_e32 v204, 16, v129
	v_lshlrev_b32_e32 v205, 16, v137
	v_lshlrev_b32_e32 v206, 16, v145
	v_fma_f32 v201, v66, v204, v94
	v_fma_f32 v201, v74, v205, v201
	v_fma_f32 v201, v86, v206, v201
	v_mul_f32_e32 v208, 0xbfb8aa3b, v200
	v_exp_f32_e32 v208, v208
	s_nop 0
	v_add_f32_e32 v209, 1.0, v208
	v_div_scale_f32 v210, s[26:27], v209, v209, v200
	v_rcp_f32_e32 v211, v210
	s_nop 0
	v_fma_f32 v212, -v210, v211, 1.0
	v_fmac_f32_e32 v211, v212, v211
	v_div_scale_f32 v213, vcc, v200, v209, v200
	v_mul_f32_e32 v214, v213, v211
	v_fma_f32 v215, -v210, v214, v213
	v_fmac_f32_e32 v214, v215, v211
	v_fma_f32 v210, -v210, v214, v213
	v_div_fmas_f32 v210, v210, v211, v214
	v_div_fixup_f32 v210, v210, v209, v200
	v_mul_f32_e32 v216, v210, v201
	v_and_b32_e32 v204, 0xffff0000, v125
	v_and_b32_e32 v205, 0xffff0000, v133
	v_and_b32_e32 v206, 0xffff0000, v141
	v_fma_f32 v200, v7, v204, v39
	v_fma_f32 v200, v15, v205, v200
	v_fma_f32 v200, v31, v206, v200
	v_and_b32_e32 v204, 0xffff0000, v129
	v_and_b32_e32 v205, 0xffff0000, v137
	v_and_b32_e32 v206, 0xffff0000, v145
	v_fma_f32 v201, v67, v204, v95
	v_fma_f32 v201, v75, v205, v201
	v_fma_f32 v201, v87, v206, v201
	v_mul_f32_e32 v208, 0xbfb8aa3b, v200
	v_exp_f32_e32 v208, v208
	s_nop 0
	v_add_f32_e32 v209, 1.0, v208
	v_div_scale_f32 v210, s[26:27], v209, v209, v200
	v_rcp_f32_e32 v211, v210
	s_nop 0
	v_fma_f32 v212, -v210, v211, 1.0
	v_fmac_f32_e32 v211, v212, v211
	v_div_scale_f32 v213, vcc, v200, v209, v200
	v_mul_f32_e32 v214, v213, v211
	v_fma_f32 v215, -v210, v214, v213
	v_fmac_f32_e32 v214, v215, v211
	v_fma_f32 v210, -v210, v214, v213
	v_div_fmas_f32 v210, v210, v211, v214
	v_div_fixup_f32 v210, v210, v209, v200
	v_mul_f32_e32 v217, v210, v201
	v_bfe_u32 v220, v216, 16, 1
	v_bfe_u32 v221, v217, 16, 1
	v_add3_u32 v220, v216, v220, s10
	v_add3_u32 v221, v217, v221, s10
	v_lshrrev_b32_e32 v220, 16, v220
	v_and_or_b32 v197, v221, s11, v220
	v_lshlrev_b32_e32 v204, 16, v126
	v_lshlrev_b32_e32 v205, 16, v134
	v_lshlrev_b32_e32 v206, 16, v142
	v_fma_f32 v200, v8, v204, v40
	v_fma_f32 v200, v24, v205, v200
	v_fma_f32 v200, v32, v206, v200
	v_lshlrev_b32_e32 v204, 16, v130
	v_lshlrev_b32_e32 v205, 16, v138
	v_lshlrev_b32_e32 v206, 16, v146
; DI unsigned pk2(float lo, float hi) { return f2bf(lo) | (f2bf(hi) << 16); }
; DI float silu_f(float x) { return x / (1.f + __expf(-x)); }
; DI void ffn_fixup_phase(const Args& A, int wave_s, int l, int rows) {
;     ...
;             for (int hlf = 0; hlf < 2; ++hlf) {
;                 const int i = c8 + 2 * q + hlf;
;                 const float ua0 = hlf ? __builtin_bit_cast(float, a0[q] & 0xffff0000u) : __builtin_bit_cast(float, a0[q] << 16);
;                 const float ua1 = hlf ? __builtin_bit_cast(float, a1[q] & 0xffff0000u) : __builtin_bit_cast(float, a1[q] << 16);
;                 const float ua2 = hlf ? __builtin_bit_cast(float, a2[q] & 0xffff0000u) : __builtin_bit_cast(float, a2[q] << 16);
;                 const float ub0 = hlf ? __builtin_bit_cast(float, b0[q] & 0xffff0000u) : __builtin_bit_cast(float, b0[q] << 16);
;                 const float ub1 = hlf ? __builtin_bit_cast(float, b1[q] & 0xffff0000u) : __builtin_bit_cast(float, b1[q] << 16);
;                 const float ub2 = hlf ? __builtin_bit_cast(float, b2[q] & 0xffff0000u) : __builtin_bit_cast(float, b2[q] << 16);
;                 const float ya = cb[i] + ua0 * cw[i] + ua1 * cw[5632 + i] + ua2 * cw[2 * 5632 + i];
;                 const float yv = cb[2816 + i] + ub0 * cw[2816 + i] + ub1 * cw[5632 + 2816 + i] + ub2 * cw[2 * 5632 + 2816 + i];
;                 r2[hlf] = silu_f(ya) * yv;
;             }
;             res[q] = pk2(r2[0], r2[1]);
;         }
;         v4u o; o.x = res[0]; o.y = res[1]; o.z = res[2]; o.w = res[3];
;         *(v4u*)(ACTF + (size_t)R * 2816 + c8) = o;
	v_fma_f32 v201, v68, v204, v96
	v_fma_f32 v201, v80, v205, v201
	v_fma_f32 v201, v88, v206, v201
	v_mul_f32_e32 v208, 0xbfb8aa3b, v200
	v_exp_f32_e32 v208, v208
	s_nop 0
	v_add_f32_e32 v209, 1.0, v208
	v_div_scale_f32 v210, s[26:27], v209, v209, v200
	v_rcp_f32_e32 v211, v210
	s_nop 0
	v_fma_f32 v212, -v210, v211, 1.0
	v_fmac_f32_e32 v211, v212, v211
	v_div_scale_f32 v213, vcc, v200, v209, v200
	v_mul_f32_e32 v214, v213, v211
	v_fma_f32 v215, -v210, v214, v213
	v_fmac_f32_e32 v214, v215, v211
	v_fma_f32 v210, -v210, v214, v213
	v_div_fmas_f32 v210, v210, v211, v214
	v_div_fixup_f32 v210, v210, v209, v200
	v_mul_f32_e32 v216, v210, v201
	v_and_b32_e32 v204, 0xffff0000, v126
	v_and_b32_e32 v205, 0xffff0000, v134
	v_and_b32_e32 v206, 0xffff0000, v142
	v_fma_f32 v200, v9, v204, v41
	v_fma_f32 v200, v25, v205, v200
	v_fma_f32 v200, v33, v206, v200
	v_and_b32_e32 v204, 0xffff0000, v130
	v_and_b32_e32 v205, 0xffff0000, v138
	v_and_b32_e32 v206, 0xffff0000, v146
	v_fma_f32 v201, v69, v204, v97
	v_fma_f32 v201, v81, v205, v201
	v_fma_f32 v201, v89, v206, v201
	v_mul_f32_e32 v208, 0xbfb8aa3b, v200
	v_exp_f32_e32 v208, v208
	s_nop 0
	v_add_f32_e32 v209, 1.0, v208
	v_div_scale_f32 v210, s[26:27], v209, v209, v200
	v_rcp_f32_e32 v211, v210
	s_nop 0
	v_fma_f32 v212, -v210, v211, 1.0
	v_fmac_f32_e32 v211, v212, v211
	v_div_scale_f32 v213, vcc, v200, v209, v200
	v_mul_f32_e32 v214, v213, v211
	v_fma_f32 v215, -v210, v214, v213
	v_fmac_f32_e32 v214, v215, v211
	v_fma_f32 v210, -v210, v214, v213
	v_div_fmas_f32 v210, v210, v211, v214
	v_div_fixup_f32 v210, v210, v209, v200
	v_mul_f32_e32 v217, v210, v201
	v_bfe_u32 v220, v216, 16, 1
	v_bfe_u32 v221, v217, 16, 1
	v_add3_u32 v220, v216, v220, s10
	v_add3_u32 v221, v217, v221, s10
	v_lshrrev_b32_e32 v220, 16, v220
	v_and_or_b32 v198, v221, s11, v220
	v_lshlrev_b32_e32 v204, 16, v127
	v_lshlrev_b32_e32 v205, 16, v135
	v_lshlrev_b32_e32 v206, 16, v143
	v_fma_f32 v200, v10, v204, v42
	v_fma_f32 v200, v26, v205, v200
	v_fma_f32 v200, v34, v206, v200
	v_lshlrev_b32_e32 v204, 16, v131
	v_lshlrev_b32_e32 v205, 16, v139
	v_lshlrev_b32_e32 v206, 16, v147
	v_fma_f32 v201, v70, v204, v98
	v_fma_f32 v201, v82, v205, v201
	v_fma_f32 v201, v90, v206, v201
	v_mul_f32_e32 v208, 0xbfb8aa3b, v200
	v_exp_f32_e32 v208, v208
	s_nop 0
	v_add_f32_e32 v209, 1.0, v208
	v_div_scale_f32 v210, s[26:27], v209, v209, v200
	v_rcp_f32_e32 v211, v210
	s_nop 0
	v_fma_f32 v212, -v210, v211, 1.0
	v_fmac_f32_e32 v211, v212, v211
	v_div_scale_f32 v213, vcc, v200, v209, v200
	v_mul_f32_e32 v214, v213, v211
	v_fma_f32 v215, -v210, v214, v213
	v_fmac_f32_e32 v214, v215, v211
	v_fma_f32 v210, -v210, v214, v213
	v_div_fmas_f32 v210, v210, v211, v214
	v_div_fixup_f32 v210, v210, v209, v200
	v_mul_f32_e32 v216, v210, v201
	v_and_b32_e32 v204, 0xffff0000, v127
	v_and_b32_e32 v205, 0xffff0000, v135
	v_and_b32_e32 v206, 0xffff0000, v143
	v_fma_f32 v200, v11, v204, v43
	v_fma_f32 v200, v27, v205, v200
	v_fma_f32 v200, v35, v206, v200
	v_and_b32_e32 v204, 0xffff0000, v131
	v_and_b32_e32 v205, 0xffff0000, v139
	v_and_b32_e32 v206, 0xffff0000, v147
	v_fma_f32 v201, v71, v204, v99
	v_fma_f32 v201, v83, v205, v201
	v_fma_f32 v201, v91, v206, v201
	v_mul_f32_e32 v208, 0xbfb8aa3b, v200
	v_exp_f32_e32 v208, v208
	s_nop 0
	v_add_f32_e32 v209, 1.0, v208
	v_div_scale_f32 v210, s[26:27], v209, v209, v200
	v_rcp_f32_e32 v211, v210
	s_nop 0
	v_fma_f32 v212, -v210, v211, 1.0
	v_fmac_f32_e32 v211, v212, v211
	v_div_scale_f32 v213, vcc, v200, v209, v200
	v_mul_f32_e32 v214, v213, v211
	v_fma_f32 v215, -v210, v214, v213
	v_fmac_f32_e32 v214, v215, v211
	v_fma_f32 v210, -v210, v214, v213
	v_div_fmas_f32 v210, v210, v211, v214
	v_div_fixup_f32 v210, v210, v209, v200
	v_mul_f32_e32 v217, v210, v201
	v_bfe_u32 v220, v216, 16, 1
	v_bfe_u32 v221, v217, 16, 1
	v_add3_u32 v220, v216, v220, s10
	v_add3_u32 v221, v217, v221, s10
	v_lshrrev_b32_e32 v220, 16, v220
	v_and_or_b32 v199, v221, s11, v220
	v_add_u32_e32 v192, 130944, v224
	v_cmp_gt_u32_e32 vcc, s7, v192
	v_mov_b32_e32 v193, 0x1600
	v_mul_lo_u32 v193, v190, v193
	v_add_u32_e32 v180, v193, v227
	v_mov_b32_e32 v181, 0
	v_lshl_add_u64 v[180:181], v[180:181], 0, s[30:31]
	s_and_saveexec_b64 s[26:27], vcc
	global_store_dwordx4 v[180:181], v[196:199], off sc1
	s_mov_b64 exec, s[26:27]
	s_nop 1
	s_waitcnt vmcnt(2)
; DI float silu_f(float x) { return x / (1.f + __expf(-x)); }
; DI void ffn_fixup_phase(const Args& A, int wave_s, int l, int rows) {
;     ...
;         const int R = kb * 64 + (side ? 63 : 0);
;         bool first, last;
;         if (R < NLAT) { first = (R & 8191) == 0; last = (R & 8191) == 8191; } else { first = ((R - NLAT) & 255) == 0; last = ((R - NLAT) & 255) == 255; }
;         const v4u z = {0u, 0u, 0u, 0u};
;         const bf16* pp = side ? UB + (size_t)((kb * 4 + 2) * 2) * 2816 : UB + (size_t)(((kb - 1) * 4 + 3) * 2) * 2816;
;         const bf16* pc = UB + (size_t)((kb * 4 + (side ? 3 : 0)) * 2) * 2816;
;         const bf16* pn = side ? UB + (size_t)(((kb + 1) * 4 + 0) * 2) * 2816 : UB + (size_t)((kb * 4 + 1) * 2) * 2816;
;         const bool zp = (!side) && first, zn = side && last;
;         const v4u a0 = zp ? z : *(const v4u*)(pp + c8), a1 = *(const v4u*)(pc + c8), a2 = zn ? z : *(const v4u*)(pn + c8);
;         const v4u b0 = zp ? z : *(const v4u*)(pp + 2816 + c8), b1 = *(const v4u*)(pc + 2816 + c8), b2 = zn ? z : *(const v4u*)(pn + 2816 + c8);
;         unsigned res[4];
; #pragma unroll
;         for (int q = 0; q < 4; ++q) {
;             float r2[2];
; #pragma unroll
;             for (int hlf = 0; hlf < 2; ++hlf) {
;                 const int i = c8 + 2 * q + hlf;
;                 const float ua0 = hlf ? __builtin_bit_cast(float, a0[q] & 0xffff0000u) : __builtin_bit_cast(float, a0[q] << 16);
;                 const float ua1 = hlf ? __builtin_bit_cast(float, a1[q] & 0xffff0000u) : __builtin_bit_cast(float, a1[q] << 16);
;                 const float ua2 = hlf ? __builtin_bit_cast(float, a2[q] & 0xffff0000u) : __builtin_bit_cast(float, a2[q] << 16);
;                 const float ub0 = hlf ? __builtin_bit_cast(float, b0[q] & 0xffff0000u) : __builtin_bit_cast(float, b0[q] << 16);
;                 const float ub1 = hlf ? __builtin_bit_cast(float, b1[q] & 0xffff0000u) : __builtin_bit_cast(float, b1[q] << 16);
;                 const float ub2 = hlf ? __builtin_bit_cast(float, b2[q] & 0xffff0000u) : __builtin_bit_cast(float, b2[q] << 16);
;                 const float ya = cb[i] + ua0 * cw[i] + ua1 * cw[5632 + i] + ua2 * cw[2 * 5632 + i];
;                 const float yv = cb[2816 + i] + ub0 * cw[2816 + i] + ub1 * cw[5632 + 2816 + i] + ub2 * cw[2 * 5632 + 2816 + i];
;                 r2[hlf] = silu_f(ya) * yv;
	v_and_b32_e32 v188, 1, v231
	v_lshrrev_b32_e32 v190, 1, v231
	v_lshlrev_b32_e32 v190, 6, v190
	v_mad_u32_u24 v190, v188, 63, v190
	v_mov_b32_e32 v191, 0xff
	v_mov_b32_e32 v189, 0x1fff
	v_cmp_gt_u32_e32 vcc, 0x8000, v190
	s_nop 1
	v_cndmask_b32_e32 v191, v191, v189, vcc
	v_and_b32_e32 v189, v190, v191
	v_or_b32_e32 v192, v189, v188
	v_cmp_eq_u32_e32 vcc, 0, v192
	s_nop 1
	v_cndmask_b32_e64 v148, v148, 0, vcc
	v_cndmask_b32_e64 v149, v149, 0, vcc
	v_cndmask_b32_e64 v150, v150, 0, vcc
	v_cndmask_b32_e64 v151, v151, 0, vcc
	v_cndmask_b32_e64 v152, v152, 0, vcc
	v_cndmask_b32_e64 v153, v153, 0, vcc
	v_cndmask_b32_e64 v154, v154, 0, vcc
	v_cndmask_b32_e64 v155, v155, 0, vcc
	v_cmp_eq_u32_e64 s[26:27], v189, v191
	v_cmp_eq_u32_e32 vcc, 1, v188
	s_nop 1
	s_and_b64 vcc, vcc, s[26:27]
	s_nop 1
	v_cndmask_b32_e64 v168, v168, 0, vcc
	v_cndmask_b32_e64 v169, v169, 0, vcc
	v_cndmask_b32_e64 v170, v170, 0, vcc
	v_cndmask_b32_e64 v171, v171, 0, vcc
	v_cndmask_b32_e64 v172, v172, 0, vcc
	v_cndmask_b32_e64 v173, v173, 0, vcc
	v_cndmask_b32_e64 v174, v174, 0, vcc
	v_cndmask_b32_e64 v175, v175, 0, vcc
	v_lshlrev_b32_e32 v204, 16, v148
	v_lshlrev_b32_e32 v205, 16, v156
	v_lshlrev_b32_e32 v206, 16, v168
	v_fma_f32 v200, v4, v204, v36
	v_fma_f32 v200, v12, v205, v200
	v_fma_f32 v200, v28, v206, v200
	v_lshlrev_b32_e32 v204, 16, v152
	v_lshlrev_b32_e32 v205, 16, v164
	v_lshlrev_b32_e32 v206, 16, v172
	v_fma_f32 v201, v64, v204, v92
	v_fma_f32 v201, v72, v205, v201
	v_fma_f32 v201, v84, v206, v201
	v_mul_f32_e32 v208, 0xbfb8aa3b, v200
	v_exp_f32_e32 v208, v208
	s_nop 0
	v_add_f32_e32 v209, 1.0, v208
	v_div_scale_f32 v210, s[26:27], v209, v209, v200
	v_rcp_f32_e32 v211, v210
	s_nop 0
	v_fma_f32 v212, -v210, v211, 1.0
	v_fmac_f32_e32 v211, v212, v211
	v_div_scale_f32 v213, vcc, v200, v209, v200
	v_mul_f32_e32 v214, v213, v211
	v_fma_f32 v215, -v210, v214, v213
	v_fmac_f32_e32 v214, v215, v211
	v_fma_f32 v210, -v210, v214, v213
	v_div_fmas_f32 v210, v210, v211, v214
	v_div_fixup_f32 v210, v210, v209, v200
	v_mul_f32_e32 v216, v210, v201
	v_and_b32_e32 v204, 0xffff0000, v148
	v_and_b32_e32 v205, 0xffff0000, v156
	v_and_b32_e32 v206, 0xffff0000, v168
	v_fma_f32 v200, v5, v204, v37
	v_fma_f32 v200, v13, v205, v200
	v_fma_f32 v200, v29, v206, v200
	v_and_b32_e32 v204, 0xffff0000, v152
	v_and_b32_e32 v205, 0xffff0000, v164
	v_and_b32_e32 v206, 0xffff0000, v172
	v_fma_f32 v201, v65, v204, v93
	v_fma_f32 v201, v73, v205, v201
	v_fma_f32 v201, v85, v206, v201
	v_mul_f32_e32 v208, 0xbfb8aa3b, v200
	v_exp_f32_e32 v208, v208
	s_nop 0
	v_add_f32_e32 v209, 1.0, v208
	v_div_scale_f32 v210, s[26:27], v209, v209, v200
	v_rcp_f32_e32 v211, v210
	s_nop 0
	v_fma_f32 v212, -v210, v211, 1.0
	v_fmac_f32_e32 v211, v212, v211
	v_div_scale_f32 v213, vcc, v200, v209, v200
	v_mul_f32_e32 v214, v213, v211
	v_fma_f32 v215, -v210, v214, v213
	v_fmac_f32_e32 v214, v215, v211
	v_fma_f32 v210, -v210, v214, v213
	v_div_fmas_f32 v210, v210, v211, v214
	v_div_fixup_f32 v210, v210, v209, v200
	v_mul_f32_e32 v217, v210, v201
	v_bfe_u32 v220, v216, 16, 1
	v_bfe_u32 v221, v217, 16, 1
	v_add3_u32 v220, v216, v220, s10
	v_add3_u32 v221, v217, v221, s10
	v_lshrrev_b32_e32 v220, 16, v220
	v_and_or_b32 v196, v221, s11, v220
	v_lshlrev_b32_e32 v204, 16, v149
	v_lshlrev_b32_e32 v205, 16, v157
	v_lshlrev_b32_e32 v206, 16, v169
	v_fma_f32 v200, v6, v204, v38
	v_fma_f32 v200, v14, v205, v200
	v_fma_f32 v200, v30, v206, v200
	v_lshlrev_b32_e32 v204, 16, v153
	v_lshlrev_b32_e32 v205, 16, v165
	v_lshlrev_b32_e32 v206, 16, v173
	v_fma_f32 v201, v66, v204, v94
	v_fma_f32 v201, v74, v205, v201
	v_fma_f32 v201, v86, v206, v201
	v_mul_f32_e32 v208, 0xbfb8aa3b, v200
	v_exp_f32_e32 v208, v208
	s_nop 0
	v_add_f32_e32 v209, 1.0, v208
	v_div_scale_f32 v210, s[26:27], v209, v209, v200
	v_rcp_f32_e32 v211, v210
	s_nop 0
	v_fma_f32 v212, -v210, v211, 1.0
	v_fmac_f32_e32 v211, v212, v211
	v_div_scale_f32 v213, vcc, v200, v209, v200
	v_mul_f32_e32 v214, v213, v211
	v_fma_f32 v215, -v210, v214, v213
	v_fmac_f32_e32 v214, v215, v211
	v_fma_f32 v210, -v210, v214, v213
	v_div_fmas_f32 v210, v210, v211, v214
	v_div_fixup_f32 v210, v210, v209, v200
	v_mul_f32_e32 v216, v210, v201
	v_and_b32_e32 v204, 0xffff0000, v149
	v_and_b32_e32 v205, 0xffff0000, v157
	v_and_b32_e32 v206, 0xffff0000, v169
	v_fma_f32 v200, v7, v204, v39
	v_fma_f32 v200, v15, v205, v200
	v_fma_f32 v200, v31, v206, v200
	v_and_b32_e32 v204, 0xffff0000, v153
	v_and_b32_e32 v205, 0xffff0000, v165
	v_and_b32_e32 v206, 0xffff0000, v173
	v_fma_f32 v201, v67, v204, v95
	v_fma_f32 v201, v75, v205, v201
	v_fma_f32 v201, v87, v206, v201
	v_mul_f32_e32 v208, 0xbfb8aa3b, v200
	v_exp_f32_e32 v208, v208
	s_nop 0
	v_add_f32_e32 v209, 1.0, v208
	v_div_scale_f32 v210, s[26:27], v209, v209, v200
	v_rcp_f32_e32 v211, v210
	s_nop 0
	v_fma_f32 v212, -v210, v211, 1.0
	v_fmac_f32_e32 v211, v212, v211
	v_div_scale_f32 v213, vcc, v200, v209, v200
	v_mul_f32_e32 v214, v213, v211
	v_fma_f32 v215, -v210, v214, v213
; DI unsigned pk2(float lo, float hi) { return f2bf(lo) | (f2bf(hi) << 16); }
; DI float silu_f(float x) { return x / (1.f + __expf(-x)); }
; DI void ffn_fixup_phase(const Args& A, int wave_s, int l, int rows) {
;     ...
;             for (int hlf = 0; hlf < 2; ++hlf) {
;                 const int i = c8 + 2 * q + hlf;
;                 const float ua0 = hlf ? __builtin_bit_cast(float, a0[q] & 0xffff0000u) : __builtin_bit_cast(float, a0[q] << 16);
;                 const float ua1 = hlf ? __builtin_bit_cast(float, a1[q] & 0xffff0000u) : __builtin_bit_cast(float, a1[q] << 16);
;                 const float ua2 = hlf ? __builtin_bit_cast(float, a2[q] & 0xffff0000u) : __builtin_bit_cast(float, a2[q] << 16);
;                 const float ub0 = hlf ? __builtin_bit_cast(float, b0[q] & 0xffff0000u) : __builtin_bit_cast(float, b0[q] << 16);
;                 const float ub1 = hlf ? __builtin_bit_cast(float, b1[q] & 0xffff0000u) : __builtin_bit_cast(float, b1[q] << 16);
;                 const float ub2 = hlf ? __builtin_bit_cast(float, b2[q] & 0xffff0000u) : __builtin_bit_cast(float, b2[q] << 16);
;                 const float ya = cb[i] + ua0 * cw[i] + ua1 * cw[5632 + i] + ua2 * cw[2 * 5632 + i];
;                 const float yv = cb[2816 + i] + ub0 * cw[2816 + i] + ub1 * cw[5632 + 2816 + i] + ub2 * cw[2 * 5632 + 2816 + i];
;                 r2[hlf] = silu_f(ya) * yv;
;             }
;             res[q] = pk2(r2[0], r2[1]);
;         }
;         v4u o; o.x = res[0]; o.y = res[1]; o.z = res[2]; o.w = res[3];
;         *(v4u*)(ACTF + (size_t)R * 2816 + c8) = o;
	v_fmac_f32_e32 v214, v215, v211
	v_fma_f32 v210, -v210, v214, v213
	v_div_fmas_f32 v210, v210, v211, v214
	v_div_fixup_f32 v210, v210, v209, v200
	v_mul_f32_e32 v217, v210, v201
	v_bfe_u32 v220, v216, 16, 1
	v_bfe_u32 v221, v217, 16, 1
	v_add3_u32 v220, v216, v220, s10
	v_add3_u32 v221, v217, v221, s10
	v_lshrrev_b32_e32 v220, 16, v220
	v_and_or_b32 v197, v221, s11, v220
	v_lshlrev_b32_e32 v204, 16, v150
	v_lshlrev_b32_e32 v205, 16, v158
	v_lshlrev_b32_e32 v206, 16, v170
	v_fma_f32 v200, v8, v204, v40
	v_fma_f32 v200, v24, v205, v200
	v_fma_f32 v200, v32, v206, v200
	v_lshlrev_b32_e32 v204, 16, v154
	v_lshlrev_b32_e32 v205, 16, v166
	v_lshlrev_b32_e32 v206, 16, v174
	v_fma_f32 v201, v68, v204, v96
	v_fma_f32 v201, v80, v205, v201
	v_fma_f32 v201, v88, v206, v201
	v_mul_f32_e32 v208, 0xbfb8aa3b, v200
	v_exp_f32_e32 v208, v208
	s_nop 0
	v_add_f32_e32 v209, 1.0, v208
	v_div_scale_f32 v210, s[26:27], v209, v209, v200
	v_rcp_f32_e32 v211, v210
	s_nop 0
	v_fma_f32 v212, -v210, v211, 1.0
	v_fmac_f32_e32 v211, v212, v211
	v_div_scale_f32 v213, vcc, v200, v209, v200
	v_mul_f32_e32 v214, v213, v211
	v_fma_f32 v215, -v210, v214, v213
	v_fmac_f32_e32 v214, v215, v211
	v_fma_f32 v210, -v210, v214, v213
	v_div_fmas_f32 v210, v210, v211, v214
	v_div_fixup_f32 v210, v210, v209, v200
	v_mul_f32_e32 v216, v210, v201
	v_and_b32_e32 v204, 0xffff0000, v150
	v_and_b32_e32 v205, 0xffff0000, v158
	v_and_b32_e32 v206, 0xffff0000, v170
	v_fma_f32 v200, v9, v204, v41
	v_fma_f32 v200, v25, v205, v200
	v_fma_f32 v200, v33, v206, v200
	v_and_b32_e32 v204, 0xffff0000, v154
	v_and_b32_e32 v205, 0xffff0000, v166
	v_and_b32_e32 v206, 0xffff0000, v174
	v_fma_f32 v201, v69, v204, v97
	v_fma_f32 v201, v81, v205, v201
	v_fma_f32 v201, v89, v206, v201
	v_mul_f32_e32 v208, 0xbfb8aa3b, v200
	v_exp_f32_e32 v208, v208
	s_nop 0
	v_add_f32_e32 v209, 1.0, v208
	v_div_scale_f32 v210, s[26:27], v209, v209, v200
	v_rcp_f32_e32 v211, v210
	s_nop 0
	v_fma_f32 v212, -v210, v211, 1.0
	v_fmac_f32_e32 v211, v212, v211
	v_div_scale_f32 v213, vcc, v200, v209, v200
	v_mul_f32_e32 v214, v213, v211
	v_fma_f32 v215, -v210, v214, v213
	v_fmac_f32_e32 v214, v215, v211
	v_fma_f32 v210, -v210, v214, v213
	v_div_fmas_f32 v210, v210, v211, v214
	v_div_fixup_f32 v210, v210, v209, v200
	v_mul_f32_e32 v217, v210, v201
	v_bfe_u32 v220, v216, 16, 1
	v_bfe_u32 v221, v217, 16, 1
	v_add3_u32 v220, v216, v220, s10
	v_add3_u32 v221, v217, v221, s10
	v_lshrrev_b32_e32 v220, 16, v220
	v_and_or_b32 v198, v221, s11, v220
	v_lshlrev_b32_e32 v204, 16, v151
	v_lshlrev_b32_e32 v205, 16, v159
	v_lshlrev_b32_e32 v206, 16, v171
	v_fma_f32 v200, v10, v204, v42
	v_fma_f32 v200, v26, v205, v200
	v_fma_f32 v200, v34, v206, v200
	v_lshlrev_b32_e32 v204, 16, v155
	v_lshlrev_b32_e32 v205, 16, v167
	v_lshlrev_b32_e32 v206, 16, v175
	v_fma_f32 v201, v70, v204, v98
	v_fma_f32 v201, v82, v205, v201
	v_fma_f32 v201, v90, v206, v201
	v_mul_f32_e32 v208, 0xbfb8aa3b, v200
	v_exp_f32_e32 v208, v208
	s_nop 0
	v_add_f32_e32 v209, 1.0, v208
	v_div_scale_f32 v210, s[26:27], v209, v209, v200
	v_rcp_f32_e32 v211, v210
	s_nop 0
	v_fma_f32 v212, -v210, v211, 1.0
	v_fmac_f32_e32 v211, v212, v211
	v_div_scale_f32 v213, vcc, v200, v209, v200
	v_mul_f32_e32 v214, v213, v211
	v_fma_f32 v215, -v210, v214, v213
	v_fmac_f32_e32 v214, v215, v211
	v_fma_f32 v210, -v210, v214, v213
	v_div_fmas_f32 v210, v210, v211, v214
	v_div_fixup_f32 v210, v210, v209, v200
	v_mul_f32_e32 v216, v210, v201
	v_and_b32_e32 v204, 0xffff0000, v151
	v_and_b32_e32 v205, 0xffff0000, v159
	v_and_b32_e32 v206, 0xffff0000, v171
	v_fma_f32 v200, v11, v204, v43
	v_fma_f32 v200, v27, v205, v200
	v_fma_f32 v200, v35, v206, v200
	v_and_b32_e32 v204, 0xffff0000, v155
	v_and_b32_e32 v205, 0xffff0000, v167
	v_and_b32_e32 v206, 0xffff0000, v175
	v_fma_f32 v201, v71, v204, v99
	v_fma_f32 v201, v83, v205, v201
	v_fma_f32 v201, v91, v206, v201
	v_mul_f32_e32 v208, 0xbfb8aa3b, v200
	v_exp_f32_e32 v208, v208
	s_nop 0
	v_add_f32_e32 v209, 1.0, v208
	v_div_scale_f32 v210, s[26:27], v209, v209, v200
	v_rcp_f32_e32 v211, v210
	s_nop 0
	v_fma_f32 v212, -v210, v211, 1.0
	v_fmac_f32_e32 v211, v212, v211
	v_div_scale_f32 v213, vcc, v200, v209, v200
	v_mul_f32_e32 v214, v213, v211
	v_fma_f32 v215, -v210, v214, v213
	v_fmac_f32_e32 v214, v215, v211
	v_fma_f32 v210, -v210, v214, v213
	v_div_fmas_f32 v210, v210, v211, v214
	v_div_fixup_f32 v210, v210, v209, v200
	v_mul_f32_e32 v217, v210, v201
	v_bfe_u32 v220, v216, 16, 1
	v_bfe_u32 v221, v217, 16, 1
	v_add3_u32 v220, v216, v220, s10
	v_add3_u32 v221, v217, v221, s10
	v_lshrrev_b32_e32 v220, 16, v220
	v_and_or_b32 v199, v221, s11, v220
	v_add_u32_e32 v192, 261888, v224
	v_cmp_gt_u32_e32 vcc, s7, v192
	v_mov_b32_e32 v193, 0x1600
	v_mul_lo_u32 v193, v190, v193
	v_add_u32_e32 v180, v193, v227
	v_mov_b32_e32 v181, 0
	v_lshl_add_u64 v[180:181], v[180:181], 0, s[30:31]
	s_and_saveexec_b64 s[26:27], vcc
	global_store_dwordx4 v[180:181], v[196:199], off sc1
	s_mov_b64 exec, s[26:27]
	s_nop 1
